# ladder + A-fragment ds_reads reordered by first MFMA use in all six K-loops
# speedup vs baseline: 1.0186x; 1.0004x over previous
.LBB0_134:
	s_add_u32 s28, s66, 0xfffc0080
	s_addc_u32 s29, s67, -1
	s_add_i32 s88, 0, 0x10000
	v_add_u32_e32 v152, s88, v191
	ds_read_b128 v[128:131], v152
	ds_read_b128 v[132:135], v152 offset:1024
	ds_read_b128 v[148:151], v152 offset:2048
	ds_read_b128 v[152:155], v152 offset:3072
	s_cmp_eq_u32 vcc_lo, 12
	s_cselect_b32 s71, s5, s29
	s_cselect_b32 s70, s7, s28
	s_cselect_b32 s69, s17, s91
	s_cselect_b32 s68, s19, s85
	v_lshl_add_u64 v[172:173], s[66:67], 0, v[144:145]
	s_add_i32 m0, s73, 0xc000
	ds_read_b128 v[156:159], v192
	ds_read_b128 v[164:167], v192 offset:2048
	ds_read_b128 v[194:197], v192 offset:4096
	ds_read_b128 v[202:205], v192 offset:6144
	ds_read_b128 v[160:163], v192 offset:1024
	ds_read_b128 v[168:171], v192 offset:3072
	ds_read_b128 v[198:201], v192 offset:5120
	ds_read_b128 v[206:209], v192 offset:7168
	global_load_lds_dwordx4 v[172:173], off
	v_lshl_add_u64 v[172:173], s[66:67], 0, v[146:147]
	s_add_i32 m0, s73, 0xe000
	s_nop 0
	global_load_lds_dwordx4 v[172:173], off
	s_waitcnt lgkmcnt(8)
	s_barrier
	s_setprio 1
	s_waitcnt lgkmcnt(7)
	v_mfma_f32_16x16x32_bf16 v[124:127], v[128:131], v[156:159], v[124:127]
	v_mfma_f32_16x16x32_bf16 v[120:123], v[148:151], v[156:159], v[120:123]
	s_waitcnt lgkmcnt(6)
	v_mfma_f32_16x16x32_bf16 v[108:111], v[128:131], v[164:167], v[108:111]
	v_mfma_f32_16x16x32_bf16 v[104:107], v[148:151], v[164:167], v[104:107]
	s_waitcnt lgkmcnt(5)
	v_mfma_f32_16x16x32_bf16 v[92:95], v[128:131], v[194:197], v[92:95]
	v_mfma_f32_16x16x32_bf16 v[88:91], v[148:151], v[194:197], v[88:91]
	s_waitcnt lgkmcnt(4)
	v_mfma_f32_16x16x32_bf16 v[76:79], v[128:131], v[202:205], v[76:79]
	v_mfma_f32_16x16x32_bf16 v[72:75], v[148:151], v[202:205], v[72:75]
	s_waitcnt lgkmcnt(3)
	v_mfma_f32_16x16x32_bf16 v[124:127], v[132:135], v[160:163], v[124:127]
	v_mfma_f32_16x16x32_bf16 v[120:123], v[152:155], v[160:163], v[120:123]
	s_waitcnt lgkmcnt(2)
	v_mfma_f32_16x16x32_bf16 v[108:111], v[132:135], v[168:171], v[108:111]
	v_mfma_f32_16x16x32_bf16 v[104:107], v[152:155], v[168:171], v[104:107]
	s_waitcnt lgkmcnt(1)
	v_mfma_f32_16x16x32_bf16 v[92:95], v[132:135], v[198:201], v[92:95]
	v_mfma_f32_16x16x32_bf16 v[88:91], v[152:155], v[198:201], v[88:91]
	s_waitcnt lgkmcnt(0)
	v_mfma_f32_16x16x32_bf16 v[76:79], v[132:135], v[206:209], v[76:79]
	v_mfma_f32_16x16x32_bf16 v[72:75], v[152:155], v[206:209], v[72:75]
	s_setprio 0
	s_barrier
	s_add_i32 s89, 0, 0x14000
	v_add_u32_e32 v172, s89, v191
	s_add_i32 s28, s88, s72
	ds_read_b128 v[210:213], v172
	ds_read_b128 v[214:217], v172 offset:1024
	ds_read_b128 v[232:235], v172 offset:2048
	ds_read_b128 v[236:239], v172 offset:3072
	v_lshl_add_u64 v[172:173], s[68:69], 0, v[138:139]
	s_mov_b32 m0, s28
	v_lshl_add_u64 v[188:189], s[68:69], 0, v[142:143]
	global_load_lds_dwordx4 v[172:173], off
	s_add_i32 m0, s28, 0x2000
	s_nop 0
	global_load_lds_dwordx4 v[188:189], off
	s_barrier
	s_setprio 1
	s_waitcnt lgkmcnt(3)
	v_mfma_f32_16x16x32_bf16 v[116:119], v[210:213], v[156:159], v[116:119]
	s_waitcnt lgkmcnt(1)
	v_mfma_f32_16x16x32_bf16 v[112:115], v[232:235], v[156:159], v[112:115]
	v_mfma_f32_16x16x32_bf16 v[100:103], v[210:213], v[164:167], v[100:103]
	v_mfma_f32_16x16x32_bf16 v[96:99], v[232:235], v[164:167], v[96:99]
	v_mfma_f32_16x16x32_bf16 v[84:87], v[210:213], v[194:197], v[84:87]
	v_mfma_f32_16x16x32_bf16 v[80:83], v[232:235], v[194:197], v[80:83]
	v_mfma_f32_16x16x32_bf16 v[68:71], v[210:213], v[202:205], v[68:71]
	v_mfma_f32_16x16x32_bf16 v[64:67], v[232:235], v[202:205], v[64:67]
	v_mfma_f32_16x16x32_bf16 v[116:119], v[214:217], v[160:163], v[116:119]
	s_waitcnt lgkmcnt(0)
	v_mfma_f32_16x16x32_bf16 v[112:115], v[236:239], v[160:163], v[112:115]
	v_mfma_f32_16x16x32_bf16 v[100:103], v[214:217], v[168:171], v[100:103]
	v_mfma_f32_16x16x32_bf16 v[96:99], v[236:239], v[168:171], v[96:99]
	v_mfma_f32_16x16x32_bf16 v[84:87], v[214:217], v[198:201], v[84:87]
	v_mfma_f32_16x16x32_bf16 v[80:83], v[236:239], v[198:201], v[80:83]
	v_mfma_f32_16x16x32_bf16 v[68:71], v[214:217], v[206:209], v[68:71]
	v_mfma_f32_16x16x32_bf16 v[64:67], v[236:239], v[206:209], v[64:67]
	s_setprio 0
	s_mov_b32 m0, s73
	v_lshl_add_u64 v[240:241], s[70:71], 0, v[136:137]
	s_barrier
	ds_read_b128 v[156:159], v192 offset:16384
	ds_read_b128 v[164:167], v192 offset:18432
	ds_read_b128 v[194:197], v192 offset:20480
	ds_read_b128 v[202:205], v192 offset:22528
	ds_read_b128 v[160:163], v192 offset:17408
	ds_read_b128 v[168:171], v192 offset:19456
	ds_read_b128 v[198:201], v192 offset:21504
	ds_read_b128 v[206:209], v192 offset:23552
	global_load_lds_dwordx4 v[240:241], off
	v_lshl_add_u64 v[242:243], s[70:71], 0, v[140:141]
	s_mov_b32 m0, s74
	s_nop 0
	global_load_lds_dwordx4 v[242:243], off
	s_barrier
	s_setprio 1
	s_waitcnt lgkmcnt(7)
	v_mfma_f32_16x16x32_bf16 v[60:63], v[128:131], v[156:159], v[60:63]
	v_mfma_f32_16x16x32_bf16 v[56:59], v[148:151], v[156:159], v[56:59]
	s_waitcnt lgkmcnt(6)
	v_mfma_f32_16x16x32_bf16 v[44:47], v[128:131], v[164:167], v[44:47]
	v_mfma_f32_16x16x32_bf16 v[40:43], v[148:151], v[164:167], v[40:43]
	s_waitcnt lgkmcnt(5)
	v_mfma_f32_16x16x32_bf16 v[28:31], v[128:131], v[194:197], v[28:31]
	v_mfma_f32_16x16x32_bf16 v[24:27], v[148:151], v[194:197], v[24:27]
	s_waitcnt lgkmcnt(4)
	v_mfma_f32_16x16x32_bf16 v[12:15], v[128:131], v[202:205], v[12:15]
	v_mfma_f32_16x16x32_bf16 v[8:11], v[148:151], v[202:205], v[8:11]
	s_waitcnt lgkmcnt(3)
	v_mfma_f32_16x16x32_bf16 v[60:63], v[132:135], v[160:163], v[60:63]
	v_mfma_f32_16x16x32_bf16 v[56:59], v[152:155], v[160:163], v[56:59]
	s_waitcnt lgkmcnt(2)
	v_mfma_f32_16x16x32_bf16 v[44:47], v[132:135], v[168:171], v[44:47]
	v_mfma_f32_16x16x32_bf16 v[40:43], v[152:155], v[168:171], v[40:43]
	s_waitcnt lgkmcnt(1)
	v_mfma_f32_16x16x32_bf16 v[28:31], v[132:135], v[198:201], v[28:31]
	v_mfma_f32_16x16x32_bf16 v[24:27], v[152:155], v[198:201], v[24:27]
	s_waitcnt lgkmcnt(0)
	v_mfma_f32_16x16x32_bf16 v[12:15], v[132:135], v[206:209], v[12:15]
	v_mfma_f32_16x16x32_bf16 v[8:11], v[152:155], v[206:209], v[8:11]
	s_setprio 0
	s_barrier
	s_add_u32 s28, s68, 0x40000
	s_addc_u32 s29, s69, 0
	s_add_i32 s88, s89, s72
	v_lshl_add_u64 v[128:129], s[28:29], 0, v[138:139]
	s_mov_b32 m0, s88
	s_nop 0
	global_load_lds_dwordx4 v[128:129], off
	v_lshl_add_u64 v[128:129], s[28:29], 0, v[142:143]
	s_add_i32 m0, s88, 0x2000
	s_nop 0
	global_load_lds_dwordx4 v[128:129], off
	s_waitcnt vmcnt(6)
	s_barrier
	s_setprio 1
	v_mfma_f32_16x16x32_bf16 v[52:55], v[210:213], v[156:159], v[52:55]
	v_mfma_f32_16x16x32_bf16 v[48:51], v[232:235], v[156:159], v[48:51]
	v_mfma_f32_16x16x32_bf16 v[36:39], v[210:213], v[164:167], v[36:39]
	v_mfma_f32_16x16x32_bf16 v[32:35], v[232:235], v[164:167], v[32:35]
	v_mfma_f32_16x16x32_bf16 v[20:23], v[210:213], v[194:197], v[20:23]
	v_mfma_f32_16x16x32_bf16 v[16:19], v[232:235], v[194:197], v[16:19]
	v_mfma_f32_16x16x32_bf16 v[4:7], v[210:213], v[202:205], v[4:7]
	v_mfma_f32_16x16x32_bf16 v[0:3], v[232:235], v[202:205], v[0:3]
	v_mfma_f32_16x16x32_bf16 v[52:55], v[214:217], v[160:163], v[52:55]
	v_mfma_f32_16x16x32_bf16 v[48:51], v[236:239], v[160:163], v[48:51]
	v_mfma_f32_16x16x32_bf16 v[36:39], v[214:217], v[168:171], v[36:39]
	v_mfma_f32_16x16x32_bf16 v[32:35], v[236:239], v[168:171], v[32:35]
	v_mfma_f32_16x16x32_bf16 v[20:23], v[214:217], v[198:201], v[20:23]
	v_mfma_f32_16x16x32_bf16 v[16:19], v[236:239], v[198:201], v[16:19]
	v_mfma_f32_16x16x32_bf16 v[4:7], v[214:217], v[206:209], v[4:7]
	v_mfma_f32_16x16x32_bf16 v[0:3], v[236:239], v[206:209], v[0:3]
	s_setprio 0
	s_add_i32 s88, 0, 0x18000
	v_add_u32_e32 v152, s88, v191
	s_barrier
	ds_read_b128 v[128:131], v152
	ds_read_b128 v[132:135], v152 offset:1024
	ds_read_b128 v[148:151], v152 offset:2048
	ds_read_b128 v[152:155], v152 offset:3072
	s_add_u32 s28, s70, 0x40000
	s_addc_u32 s29, s71, 0
	s_mov_b32 m0, s75
	v_lshl_add_u64 v[210:211], s[28:29], 0, v[136:137]
	ds_read_b128 v[156:159], v192 offset:32768
	ds_read_b128 v[164:167], v192 offset:34816
	ds_read_b128 v[194:197], v192 offset:36864
	ds_read_b128 v[202:205], v192 offset:38912
	ds_read_b128 v[160:163], v192 offset:33792
	ds_read_b128 v[168:171], v192 offset:35840
	ds_read_b128 v[198:201], v192 offset:37888
	ds_read_b128 v[206:209], v192 offset:39936
	global_load_lds_dwordx4 v[210:211], off
	v_lshl_add_u64 v[210:211], s[28:29], 0, v[140:141]
	s_mov_b32 m0, s76
	s_nop 0
	global_load_lds_dwordx4 v[210:211], off
	s_waitcnt lgkmcnt(8)
	s_barrier
	s_setprio 1
	s_waitcnt lgkmcnt(7)
	v_mfma_f32_16x16x32_bf16 v[124:127], v[128:131], v[156:159], v[124:127]
	v_mfma_f32_16x16x32_bf16 v[120:123], v[148:151], v[156:159], v[120:123]
	s_waitcnt lgkmcnt(6)
	v_mfma_f32_16x16x32_bf16 v[108:111], v[128:131], v[164:167], v[108:111]
	v_mfma_f32_16x16x32_bf16 v[104:107], v[148:151], v[164:167], v[104:107]
	s_waitcnt lgkmcnt(5)
	v_mfma_f32_16x16x32_bf16 v[92:95], v[128:131], v[194:197], v[92:95]
	v_mfma_f32_16x16x32_bf16 v[88:91], v[148:151], v[194:197], v[88:91]
	s_waitcnt lgkmcnt(4)
	v_mfma_f32_16x16x32_bf16 v[76:79], v[128:131], v[202:205], v[76:79]
	v_mfma_f32_16x16x32_bf16 v[72:75], v[148:151], v[202:205], v[72:75]
	s_waitcnt lgkmcnt(3)
	v_mfma_f32_16x16x32_bf16 v[124:127], v[132:135], v[160:163], v[124:127]
	v_mfma_f32_16x16x32_bf16 v[120:123], v[152:155], v[160:163], v[120:123]
	s_waitcnt lgkmcnt(2)
	v_mfma_f32_16x16x32_bf16 v[108:111], v[132:135], v[168:171], v[108:111]
	v_mfma_f32_16x16x32_bf16 v[104:107], v[152:155], v[168:171], v[104:107]
	s_waitcnt lgkmcnt(1)
	v_mfma_f32_16x16x32_bf16 v[92:95], v[132:135], v[198:201], v[92:95]
	v_mfma_f32_16x16x32_bf16 v[88:91], v[152:155], v[198:201], v[88:91]
	s_waitcnt lgkmcnt(0)
	v_mfma_f32_16x16x32_bf16 v[76:79], v[132:135], v[206:209], v[76:79]
	v_mfma_f32_16x16x32_bf16 v[72:75], v[152:155], v[206:209], v[72:75]
	s_setprio 0
	s_barrier
	s_add_i32 s70, 0, 0x1c000
	s_add_i32 s28, s88, s72
	v_add_u32_e32 v174, s70, v191
	v_lshl_add_u64 v[172:173], v[172:173], 0, s[40:41]
	s_mov_b32 m0, s28
	ds_read_b128 v[210:213], v174
	ds_read_b128 v[214:217], v174 offset:1024
	ds_read_b128 v[232:235], v174 offset:2048
	ds_read_b128 v[236:239], v174 offset:3072
	global_load_lds_dwordx4 v[172:173], off
	v_lshl_add_u64 v[172:173], v[188:189], 0, s[40:41]
	s_add_i32 m0, s28, 0x2000
	s_nop 0
	global_load_lds_dwordx4 v[172:173], off
	s_barrier
	s_setprio 1
	s_waitcnt lgkmcnt(3)
	v_mfma_f32_16x16x32_bf16 v[116:119], v[210:213], v[156:159], v[116:119]
	s_waitcnt lgkmcnt(1)
	v_mfma_f32_16x16x32_bf16 v[112:115], v[232:235], v[156:159], v[112:115]
	v_mfma_f32_16x16x32_bf16 v[100:103], v[210:213], v[164:167], v[100:103]
	v_mfma_f32_16x16x32_bf16 v[96:99], v[232:235], v[164:167], v[96:99]
	v_mfma_f32_16x16x32_bf16 v[84:87], v[210:213], v[194:197], v[84:87]
	v_mfma_f32_16x16x32_bf16 v[80:83], v[232:235], v[194:197], v[80:83]
	v_mfma_f32_16x16x32_bf16 v[68:71], v[210:213], v[202:205], v[68:71]
	v_mfma_f32_16x16x32_bf16 v[64:67], v[232:235], v[202:205], v[64:67]
	v_mfma_f32_16x16x32_bf16 v[116:119], v[214:217], v[160:163], v[116:119]
	s_waitcnt lgkmcnt(0)
	v_mfma_f32_16x16x32_bf16 v[112:115], v[236:239], v[160:163], v[112:115]
	v_mfma_f32_16x16x32_bf16 v[100:103], v[214:217], v[168:171], v[100:103]
	v_mfma_f32_16x16x32_bf16 v[96:99], v[236:239], v[168:171], v[96:99]
	v_mfma_f32_16x16x32_bf16 v[84:87], v[214:217], v[198:201], v[84:87]
	v_mfma_f32_16x16x32_bf16 v[80:83], v[236:239], v[198:201], v[80:83]
	v_mfma_f32_16x16x32_bf16 v[68:71], v[214:217], v[206:209], v[68:71]
	v_mfma_f32_16x16x32_bf16 v[64:67], v[236:239], v[206:209], v[64:67]
	s_setprio 0
	s_mov_b32 m0, s79
	v_lshl_add_u64 v[172:173], v[240:241], 0, s[40:41]
	s_barrier
	ds_read_b128 v[156:159], v192 offset:49152
	ds_read_b128 v[164:167], v192 offset:51200
	ds_read_b128 v[194:197], v192 offset:53248
	ds_read_b128 v[202:205], v192 offset:55296
	ds_read_b128 v[160:163], v192 offset:50176
	ds_read_b128 v[168:171], v192 offset:52224
	ds_read_b128 v[198:201], v192 offset:54272
	ds_read_b128 v[206:209], v192 offset:56320
	global_load_lds_dwordx4 v[172:173], off
	v_lshl_add_u64 v[172:173], v[242:243], 0, s[40:41]
	s_mov_b32 m0, s80
	s_nop 0
	global_load_lds_dwordx4 v[172:173], off
	s_barrier
	s_setprio 1
	s_waitcnt lgkmcnt(7)
	v_mfma_f32_16x16x32_bf16 v[60:63], v[128:131], v[156:159], v[60:63]
	v_mfma_f32_16x16x32_bf16 v[56:59], v[148:151], v[156:159], v[56:59]
	s_waitcnt lgkmcnt(6)
	v_mfma_f32_16x16x32_bf16 v[44:47], v[128:131], v[164:167], v[44:47]
	v_mfma_f32_16x16x32_bf16 v[40:43], v[148:151], v[164:167], v[40:43]
	s_waitcnt lgkmcnt(5)
	v_mfma_f32_16x16x32_bf16 v[28:31], v[128:131], v[194:197], v[28:31]
	v_mfma_f32_16x16x32_bf16 v[24:27], v[148:151], v[194:197], v[24:27]
	s_waitcnt lgkmcnt(4)
	v_mfma_f32_16x16x32_bf16 v[12:15], v[128:131], v[202:205], v[12:15]
	v_mfma_f32_16x16x32_bf16 v[8:11], v[148:151], v[202:205], v[8:11]
	s_waitcnt lgkmcnt(3)
	v_mfma_f32_16x16x32_bf16 v[60:63], v[132:135], v[160:163], v[60:63]
	v_mfma_f32_16x16x32_bf16 v[56:59], v[152:155], v[160:163], v[56:59]
	s_waitcnt lgkmcnt(2)
	v_mfma_f32_16x16x32_bf16 v[44:47], v[132:135], v[168:171], v[44:47]
	v_mfma_f32_16x16x32_bf16 v[40:43], v[152:155], v[168:171], v[40:43]
	s_waitcnt lgkmcnt(1)
	v_mfma_f32_16x16x32_bf16 v[28:31], v[132:135], v[198:201], v[28:31]
	v_mfma_f32_16x16x32_bf16 v[24:27], v[152:155], v[198:201], v[24:27]
	s_waitcnt lgkmcnt(0)
	v_mfma_f32_16x16x32_bf16 v[12:15], v[132:135], v[206:209], v[12:15]
	v_mfma_f32_16x16x32_bf16 v[8:11], v[152:155], v[206:209], v[8:11]
	s_setprio 0
	s_barrier
	s_add_u32 s28, s68, 0x40080
	s_addc_u32 s29, s69, 0
	s_add_i32 s68, s70, s72
	v_lshl_add_u64 v[128:129], s[28:29], 0, v[138:139]
	s_mov_b32 m0, s68
	s_nop 0
	global_load_lds_dwordx4 v[128:129], off
	v_lshl_add_u64 v[128:129], s[28:29], 0, v[142:143]
	s_add_i32 m0, s68, 0x2000
	s_nop 0
	global_load_lds_dwordx4 v[128:129], off
	s_waitcnt vmcnt(6)
	s_barrier
	s_setprio 1
	v_mfma_f32_16x16x32_bf16 v[52:55], v[210:213], v[156:159], v[52:55]
	v_mfma_f32_16x16x32_bf16 v[48:51], v[232:235], v[156:159], v[48:51]
	v_mfma_f32_16x16x32_bf16 v[36:39], v[210:213], v[164:167], v[36:39]
	v_mfma_f32_16x16x32_bf16 v[32:35], v[232:235], v[164:167], v[32:35]
	v_mfma_f32_16x16x32_bf16 v[20:23], v[210:213], v[194:197], v[20:23]
	v_mfma_f32_16x16x32_bf16 v[16:19], v[232:235], v[194:197], v[16:19]
	v_mfma_f32_16x16x32_bf16 v[4:7], v[210:213], v[202:205], v[4:7]
	v_mfma_f32_16x16x32_bf16 v[0:3], v[232:235], v[202:205], v[0:3]
	v_mfma_f32_16x16x32_bf16 v[52:55], v[214:217], v[160:163], v[52:55]
	v_mfma_f32_16x16x32_bf16 v[48:51], v[236:239], v[160:163], v[48:51]
	v_mfma_f32_16x16x32_bf16 v[36:39], v[214:217], v[168:171], v[36:39]
	v_mfma_f32_16x16x32_bf16 v[32:35], v[236:239], v[168:171], v[32:35]
	v_mfma_f32_16x16x32_bf16 v[20:23], v[214:217], v[198:201], v[20:23]
	v_mfma_f32_16x16x32_bf16 v[16:19], v[236:239], v[198:201], v[16:19]
	v_mfma_f32_16x16x32_bf16 v[4:7], v[214:217], v[206:209], v[4:7]
	v_mfma_f32_16x16x32_bf16 v[0:3], v[236:239], v[206:209], v[0:3]
	s_setprio 0
	s_add_i32 vcc_lo, vcc_lo, 2
	s_add_u32 s66, s66, 0x100
	s_addc_u32 s67, s67, 0
	s_add_u32 s85, s85, 0x100
	s_addc_u32 s91, s91, 0
	s_cmp_lt_u32 vcc_lo, 14
	s_barrier
	s_cbranch_scc1 .LBB0_134
	s_lshl_b32 s4, s4, 8
	v_mov_b32_e32 v176, v175
	v_mov_b32_e32 v188, v190
	s_add_i32 s4, s4, s77
	s_cmp_gt_i32 s6, 7
	v_add_u32_e32 v148, s4, v176
	v_lshlrev_b32_e32 v128, 2, v188
	v_ashrrev_i32_e32 v129, 31, v128
	v_ashrrev_i32_e32 v149, 31, v148
	v_lshl_add_u64 v[128:129], v[128:129], 2, s[8:9]
	v_lshlrev_b64 v[130:131], 6, v[148:149]
	v_add_u32_e32 v166, 16, v148
	v_lshl_add_u64 v[130:131], v[128:129], 0, v[130:131]
	v_ashrrev_i32_e32 v167, 31, v166
	global_load_dwordx4 v[160:163], v[130:131], off
	v_lshlrev_b64 v[130:131], 6, v[166:167]
	v_lshl_add_u64 v[130:131], v[128:129], 0, v[130:131]
	global_load_dwordx4 v[168:171], v[130:131], off
	v_add_u32_e32 v164, 32, v148
	v_ashrrev_i32_e32 v165, 31, v164
	v_lshlrev_b64 v[130:131], 6, v[164:165]
	v_add_u32_e32 v158, 48, v148
	v_lshl_add_u64 v[130:131], v[128:129], 0, v[130:131]
	v_ashrrev_i32_e32 v159, 31, v158
	global_load_dwordx4 v[194:197], v[130:131], off
	v_lshlrev_b64 v[130:131], 6, v[158:159]
	v_lshl_add_u64 v[130:131], v[128:129], 0, v[130:131]
	global_load_dwordx4 v[198:201], v[130:131], off
	v_add_u32_e32 v156, 0x80, v148
	v_ashrrev_i32_e32 v157, 31, v156
	v_lshlrev_b64 v[130:131], 6, v[156:157]
	v_add_u32_e32 v154, 0x90, v148
	v_lshl_add_u64 v[130:131], v[128:129], 0, v[130:131]
	v_ashrrev_i32_e32 v155, 31, v154
	global_load_dwordx4 v[202:205], v[130:131], off
	v_lshlrev_b64 v[130:131], 6, v[154:155]
	v_add_u32_e32 v152, 0xa0, v148
	v_lshl_add_u64 v[130:131], v[128:129], 0, v[130:131]
	v_ashrrev_i32_e32 v153, 31, v152
	global_load_dwordx4 v[206:209], v[130:131], off
	v_lshlrev_b64 v[130:131], 6, v[152:153]
	v_add_u32_e32 v150, 0xb0, v148
	v_lshl_add_u64 v[130:131], v[128:129], 0, v[130:131]
	v_ashrrev_i32_e32 v151, 31, v150
	global_load_dwordx4 v[132:135], v[130:131], off
	v_lshlrev_b64 v[130:131], 6, v[150:151]
	v_lshl_add_u64 v[128:129], v[128:129], 0, v[130:131]
	global_load_dwordx4 v[128:131], v[128:129], off
	s_cselect_b64 s[66:67], -1, 0
	s_lshl_b32 s7, s6, 8
	s_add_i32 s7, s81, s7
	s_cmp_lt_i32 s6, 8
	s_mov_b64 s[68:69], -1
	s_waitcnt vmcnt(0)
	v_mov_b32_e32 v172, v161
	v_mov_b32_e32 v173, v162
	v_mov_b32_e32 v161, v163
	v_mov_b32_e32 v162, v169
	v_mov_b32_e32 v163, v170
	v_mov_b32_e32 v169, v171
	v_pk_add_f32 v[160:161], v[172:173], v[160:161]
	v_pk_add_f32 v[162:163], v[162:163], v[168:169]
	v_mov_b32_e32 v169, v160
	v_mov_b32_e32 v168, v162
	v_mov_b32_e32 v160, v163
	v_pk_add_f32 v[160:161], v[168:169], v[160:161]
	ds_bpermute_b32 v163, v219, v161
	ds_bpermute_b32 v162, v219, v160
	s_waitcnt lgkmcnt(0)
	v_pk_add_f32 v[160:161], v[160:161], v[162:163]
	ds_bpermute_b32 v163, v218, v161
	ds_bpermute_b32 v162, v218, v160
	s_waitcnt lgkmcnt(0)
	v_pk_add_f32 v[160:161], v[160:161], v[162:163]
	s_nop 0
	v_pk_fma_f32 v[172:173], v[160:161], s[30:31], v[178:179] op_sel_hi:[1,0,0]
	v_mov_b32_e32 v162, v199
	v_mul_f32_e32 v160, 0x4b800000, v173
	v_cmp_gt_f32_e32 vcc, s86, v173
	v_mov_b32_e32 v163, v200
	v_mov_b32_e32 v199, v201
	v_cndmask_b32_e32 v160, v173, v160, vcc
	v_rsq_f32_e32 v160, v160
	v_pk_add_f32 v[162:163], v[162:163], v[198:199]
	v_cmp_gt_f32_e64 s[4:5], s86, v172
	v_mov_b32_e32 v168, v162
	v_mul_f32_e32 v161, 0x45800000, v160
	v_cndmask_b32_e32 v174, v160, v161, vcc
	v_mov_b32_e32 v160, v195
	v_mov_b32_e32 v161, v196
	v_mov_b32_e32 v195, v197
	v_pk_add_f32 v[160:161], v[160:161], v[194:195]
	s_nop 0
	v_mov_b32_e32 v169, v160
	v_mov_b32_e32 v160, v163
	v_pk_add_f32 v[160:161], v[168:169], v[160:161]
	ds_bpermute_b32 v163, v219, v161
	ds_bpermute_b32 v162, v219, v160
	s_waitcnt lgkmcnt(0)
	v_pk_add_f32 v[168:169], v[160:161], v[162:163]
	v_mov_b32_e32 v160, v203
	v_mov_b32_e32 v161, v204
	v_mov_b32_e32 v203, v205
	v_mov_b32_e32 v162, v207
	v_mov_b32_e32 v163, v208
	v_mov_b32_e32 v207, v209
	v_pk_add_f32 v[160:161], v[160:161], v[202:203]
	v_pk_add_f32 v[162:163], v[162:163], v[206:207]
	v_mov_b32_e32 v195, v160
	v_mov_b32_e32 v194, v162
	v_mov_b32_e32 v160, v163
	v_pk_add_f32 v[160:161], v[194:195], v[160:161]
	v_mov_b32_e32 v194, v133
	v_mov_b32_e32 v195, v134
	v_mov_b32_e32 v133, v135
	v_mov_b32_e32 v134, v129
	v_mov_b32_e32 v135, v130
	v_mov_b32_e32 v129, v131
	v_pk_add_f32 v[132:133], v[194:195], v[132:133]
	v_pk_add_f32 v[128:129], v[134:135], v[128:129]
	v_mov_b32_e32 v131, v132
	v_mov_b32_e32 v130, v128
	v_mov_b32_e32 v132, v129
	v_pk_add_f32 v[128:129], v[130:131], v[132:133]
	ds_bpermute_b32 v163, v219, v161
	ds_bpermute_b32 v162, v219, v160
	ds_bpermute_b32 v131, v219, v129
	ds_bpermute_b32 v130, v219, v128
	ds_bpermute_b32 v171, v218, v169
	ds_bpermute_b32 v170, v218, v168
	s_waitcnt lgkmcnt(4)
	v_pk_add_f32 v[160:161], v[160:161], v[162:163]
	ds_bpermute_b32 v163, v218, v161
	s_waitcnt lgkmcnt(3)
	v_pk_add_f32 v[132:133], v[128:129], v[130:131]
	ds_bpermute_b32 v162, v218, v160
	ds_bpermute_b32 v135, v218, v133
	ds_bpermute_b32 v134, v218, v132
	v_lshlrev_b32_e32 v128, 3, v188
	v_add_u32_e32 v130, s7, v128
	v_lshlrev_b64 v[188:189], 11, v[148:149]
	v_ashrrev_i32_e32 v131, 31, v130
	s_cbranch_scc1 .LBB0_137
	v_mul_f32_e32 v196, v120, v174
	v_mul_f32_e32 v197, v121, v174
	v_mul_f32_e32 v198, v122, v174
	v_mul_f32_e32 v199, v123, v174
	v_mul_f32_e32 v129, v124, v174
	v_mul_f32_e32 v149, v125, v174
	v_mul_f32_e32 v173, v126, v174
	v_mul_f32_e32 v193, v127, v174
	v_cvt_pk_bf16_f32 v194, v129, v149
	v_cvt_pk_bf16_f32 v195, v173, v193
	v_cvt_pk_bf16_f32 v196, v196, v197
	v_cvt_pk_bf16_f32 v197, v198, v199
	v_lshl_add_u64 v[198:199], s[12:13], 0, v[188:189]
	v_lshl_add_u64 v[198:199], v[130:131], 1, v[198:199]
	global_store_dwordx4 v[198:199], v[194:197], off
	s_mov_b64 s[68:69], 0
	v_mul_f32_e32 v129, v116, v174
	v_mul_f32_e32 v196, v112, v174
	v_mul_f32_e32 v197, v113, v174
	v_mul_f32_e32 v149, v117, v174
	v_mul_f32_e32 v173, v118, v174
	v_mul_f32_e32 v193, v119, v174
	v_mul_f32_e32 v200, v114, v174
	v_mul_f32_e32 v201, v115, v174
	v_cvt_pk_bf16_f32 v194, v129, v149
	v_cvt_pk_bf16_f32 v195, v173, v193
	v_cvt_pk_bf16_f32 v196, v196, v197
	v_cvt_pk_bf16_f32 v197, v200, v201
	global_store_dwordx4 v[198:199], v[194:197], off offset:256

.LBB0_413:
	s_add_i32 vcc_lo, s62, 2
	s_add_u32 s4, s18, 0x100
	s_addc_u32 s5, s19, 0
	s_add_i32 s28, 0, 0x10000
	v_add_u32_e32 v140, s28, v164
	ds_read_b128 v[128:131], v140
	ds_read_b128 v[132:135], v140 offset:1024
	ds_read_b128 v[136:139], v140 offset:2048
	ds_read_b128 v[140:143], v140 offset:3072
	s_cmp_eq_u32 s13, s62
	s_cselect_b32 s62, s6, s85
	s_cselect_b32 s65, s17, s5
	s_cselect_b32 s64, s16, s4
	s_cselect_b32 s63, s7, s91
	v_lshl_add_u64 v[174:175], s[18:19], 0, v[150:151]
	s_add_i32 m0, s69, 0xc000
	ds_read_b128 v[154:157], v165
	ds_read_b128 v[166:169], v165 offset:2048
	ds_read_b128 v[188:191], v165 offset:4096
	ds_read_b128 v[196:199], v165 offset:6144
	ds_read_b128 v[158:161], v165 offset:1024
	ds_read_b128 v[170:173], v165 offset:3072
	ds_read_b128 v[192:195], v165 offset:5120
	ds_read_b128 v[200:203], v165 offset:7168
	global_load_lds_dwordx4 v[174:175], off
	v_lshl_add_u64 v[174:175], s[18:19], 0, v[152:153]
	s_add_i32 m0, s69, 0xe000
	s_nop 0
	global_load_lds_dwordx4 v[174:175], off
	s_waitcnt lgkmcnt(8)
	s_barrier
	s_setprio 1
	s_waitcnt lgkmcnt(7)
	v_mfma_f32_16x16x32_bf16 v[124:127], v[128:131], v[154:157], v[124:127]
	v_mfma_f32_16x16x32_bf16 v[120:123], v[136:139], v[154:157], v[120:123]
	s_waitcnt lgkmcnt(6)
	v_mfma_f32_16x16x32_bf16 v[108:111], v[128:131], v[166:169], v[108:111]
	v_mfma_f32_16x16x32_bf16 v[104:107], v[136:139], v[166:169], v[104:107]
	s_waitcnt lgkmcnt(5)
	v_mfma_f32_16x16x32_bf16 v[92:95], v[128:131], v[188:191], v[92:95]
	v_mfma_f32_16x16x32_bf16 v[88:91], v[136:139], v[188:191], v[88:91]
	s_waitcnt lgkmcnt(4)
	v_mfma_f32_16x16x32_bf16 v[76:79], v[128:131], v[196:199], v[76:79]
	v_mfma_f32_16x16x32_bf16 v[72:75], v[136:139], v[196:199], v[72:75]
	s_waitcnt lgkmcnt(3)
	v_mfma_f32_16x16x32_bf16 v[124:127], v[132:135], v[158:161], v[124:127]
	v_mfma_f32_16x16x32_bf16 v[120:123], v[140:143], v[158:161], v[120:123]
	s_waitcnt lgkmcnt(2)
	v_mfma_f32_16x16x32_bf16 v[108:111], v[132:135], v[170:173], v[108:111]
	v_mfma_f32_16x16x32_bf16 v[104:107], v[140:143], v[170:173], v[104:107]
	s_waitcnt lgkmcnt(1)
	v_mfma_f32_16x16x32_bf16 v[92:95], v[132:135], v[192:195], v[92:95]
	v_mfma_f32_16x16x32_bf16 v[88:91], v[140:143], v[192:195], v[88:91]
	s_waitcnt lgkmcnt(0)
	v_mfma_f32_16x16x32_bf16 v[76:79], v[132:135], v[200:203], v[76:79]
	v_mfma_f32_16x16x32_bf16 v[72:75], v[140:143], v[200:203], v[72:75]
	s_setprio 0
	s_barrier
	s_add_i32 s29, 0, 0x14000
	v_add_u32_e32 v174, s29, v164
	s_add_i32 s18, s28, s68
	ds_read_b128 v[204:207], v174
	ds_read_b128 v[208:211], v174 offset:1024
	ds_read_b128 v[212:215], v174 offset:2048
	ds_read_b128 v[232:235], v174 offset:3072
	v_lshl_add_u64 v[174:175], s[62:63], 0, v[176:177]
	s_mov_b32 m0, s18
	v_lshl_add_u64 v[216:217], s[62:63], 0, v[148:149]
	global_load_lds_dwordx4 v[174:175], off
	s_add_i32 m0, s18, 0x2000
	s_nop 0
	global_load_lds_dwordx4 v[216:217], off
	s_barrier
	s_setprio 1
	s_waitcnt lgkmcnt(3)
	v_mfma_f32_16x16x32_bf16 v[116:119], v[204:207], v[154:157], v[116:119]
	s_waitcnt lgkmcnt(1)
	v_mfma_f32_16x16x32_bf16 v[112:115], v[212:215], v[154:157], v[112:115]
	v_mfma_f32_16x16x32_bf16 v[100:103], v[204:207], v[166:169], v[100:103]
	v_mfma_f32_16x16x32_bf16 v[96:99], v[212:215], v[166:169], v[96:99]
	v_mfma_f32_16x16x32_bf16 v[84:87], v[204:207], v[188:191], v[84:87]
	v_mfma_f32_16x16x32_bf16 v[80:83], v[212:215], v[188:191], v[80:83]
	v_mfma_f32_16x16x32_bf16 v[68:71], v[204:207], v[196:199], v[68:71]
	v_mfma_f32_16x16x32_bf16 v[64:67], v[212:215], v[196:199], v[64:67]
	v_mfma_f32_16x16x32_bf16 v[116:119], v[208:211], v[158:161], v[116:119]
	s_waitcnt lgkmcnt(0)
	v_mfma_f32_16x16x32_bf16 v[112:115], v[232:235], v[158:161], v[112:115]
	v_mfma_f32_16x16x32_bf16 v[100:103], v[208:211], v[170:173], v[100:103]
	v_mfma_f32_16x16x32_bf16 v[96:99], v[232:235], v[170:173], v[96:99]
	v_mfma_f32_16x16x32_bf16 v[84:87], v[208:211], v[192:195], v[84:87]
	v_mfma_f32_16x16x32_bf16 v[80:83], v[232:235], v[192:195], v[80:83]
	v_mfma_f32_16x16x32_bf16 v[68:71], v[208:211], v[200:203], v[68:71]
	v_mfma_f32_16x16x32_bf16 v[64:67], v[232:235], v[200:203], v[64:67]
	s_setprio 0
	s_mov_b32 m0, s69
	v_lshl_add_u64 v[236:237], s[64:65], 0, v[144:145]
	s_barrier
	ds_read_b128 v[154:157], v165 offset:16384
	ds_read_b128 v[166:169], v165 offset:18432
	ds_read_b128 v[188:191], v165 offset:20480
	ds_read_b128 v[196:199], v165 offset:22528
	ds_read_b128 v[158:161], v165 offset:17408
	ds_read_b128 v[170:173], v165 offset:19456
	ds_read_b128 v[192:195], v165 offset:21504
	ds_read_b128 v[200:203], v165 offset:23552
	global_load_lds_dwordx4 v[236:237], off
	v_lshl_add_u64 v[238:239], s[64:65], 0, v[146:147]
	s_mov_b32 m0, s70
	s_nop 0
	global_load_lds_dwordx4 v[238:239], off
	s_barrier
	s_setprio 1
	s_waitcnt lgkmcnt(7)
	v_mfma_f32_16x16x32_bf16 v[60:63], v[128:131], v[154:157], v[60:63]
	v_mfma_f32_16x16x32_bf16 v[56:59], v[136:139], v[154:157], v[56:59]
	s_waitcnt lgkmcnt(6)
	v_mfma_f32_16x16x32_bf16 v[44:47], v[128:131], v[166:169], v[44:47]
	v_mfma_f32_16x16x32_bf16 v[40:43], v[136:139], v[166:169], v[40:43]
	s_waitcnt lgkmcnt(5)
	v_mfma_f32_16x16x32_bf16 v[28:31], v[128:131], v[188:191], v[28:31]
	v_mfma_f32_16x16x32_bf16 v[24:27], v[136:139], v[188:191], v[24:27]
	s_waitcnt lgkmcnt(4)
	v_mfma_f32_16x16x32_bf16 v[12:15], v[128:131], v[196:199], v[12:15]
	v_mfma_f32_16x16x32_bf16 v[8:11], v[136:139], v[196:199], v[8:11]
	s_waitcnt lgkmcnt(3)
	v_mfma_f32_16x16x32_bf16 v[60:63], v[132:135], v[158:161], v[60:63]
	v_mfma_f32_16x16x32_bf16 v[56:59], v[140:143], v[158:161], v[56:59]
	s_waitcnt lgkmcnt(2)
	v_mfma_f32_16x16x32_bf16 v[44:47], v[132:135], v[170:173], v[44:47]
	v_mfma_f32_16x16x32_bf16 v[40:43], v[140:143], v[170:173], v[40:43]
	s_waitcnt lgkmcnt(1)
	v_mfma_f32_16x16x32_bf16 v[28:31], v[132:135], v[192:195], v[28:31]
	v_mfma_f32_16x16x32_bf16 v[24:27], v[140:143], v[192:195], v[24:27]
	s_waitcnt lgkmcnt(0)
	v_mfma_f32_16x16x32_bf16 v[12:15], v[132:135], v[200:203], v[12:15]
	v_mfma_f32_16x16x32_bf16 v[8:11], v[140:143], v[200:203], v[8:11]
	s_setprio 0
	s_barrier
	s_add_u32 s18, s62, 0x18000
	s_addc_u32 s19, s63, 0
	s_add_i32 s28, s29, s68
	v_lshl_add_u64 v[128:129], s[18:19], 0, v[176:177]
	s_mov_b32 m0, s28
	s_nop 0
	global_load_lds_dwordx4 v[128:129], off
	v_lshl_add_u64 v[128:129], s[18:19], 0, v[148:149]
	s_add_i32 m0, s28, 0x2000
	s_nop 0
	global_load_lds_dwordx4 v[128:129], off
	s_waitcnt vmcnt(6)
	s_barrier
	s_setprio 1
	v_mfma_f32_16x16x32_bf16 v[52:55], v[204:207], v[154:157], v[52:55]
	v_mfma_f32_16x16x32_bf16 v[48:51], v[212:215], v[154:157], v[48:51]
	v_mfma_f32_16x16x32_bf16 v[36:39], v[204:207], v[166:169], v[36:39]
	v_mfma_f32_16x16x32_bf16 v[32:35], v[212:215], v[166:169], v[32:35]
	v_mfma_f32_16x16x32_bf16 v[20:23], v[204:207], v[188:191], v[20:23]
	v_mfma_f32_16x16x32_bf16 v[16:19], v[212:215], v[188:191], v[16:19]
	v_mfma_f32_16x16x32_bf16 v[4:7], v[204:207], v[196:199], v[4:7]
	v_mfma_f32_16x16x32_bf16 v[0:3], v[212:215], v[196:199], v[0:3]
	v_mfma_f32_16x16x32_bf16 v[52:55], v[208:211], v[158:161], v[52:55]
	v_mfma_f32_16x16x32_bf16 v[48:51], v[232:235], v[158:161], v[48:51]
	v_mfma_f32_16x16x32_bf16 v[36:39], v[208:211], v[170:173], v[36:39]
	v_mfma_f32_16x16x32_bf16 v[32:35], v[232:235], v[170:173], v[32:35]
	v_mfma_f32_16x16x32_bf16 v[20:23], v[208:211], v[192:195], v[20:23]
	v_mfma_f32_16x16x32_bf16 v[16:19], v[232:235], v[192:195], v[16:19]
	v_mfma_f32_16x16x32_bf16 v[4:7], v[208:211], v[200:203], v[4:7]
	v_mfma_f32_16x16x32_bf16 v[0:3], v[232:235], v[200:203], v[0:3]
	s_setprio 0
	s_add_i32 s28, 0, 0x18000
	v_add_u32_e32 v140, s28, v164
	s_barrier
	ds_read_b128 v[128:131], v140
	ds_read_b128 v[132:135], v140 offset:1024
	ds_read_b128 v[136:139], v140 offset:2048
	ds_read_b128 v[140:143], v140 offset:3072
	s_add_u32 s18, s64, 0x18000
	s_addc_u32 s19, s65, 0
	s_mov_b32 m0, s71
	v_lshl_add_u64 v[204:205], s[18:19], 0, v[144:145]
	ds_read_b128 v[154:157], v165 offset:32768
	ds_read_b128 v[166:169], v165 offset:34816
	ds_read_b128 v[188:191], v165 offset:36864
	ds_read_b128 v[196:199], v165 offset:38912
	ds_read_b128 v[158:161], v165 offset:33792
	ds_read_b128 v[170:173], v165 offset:35840
	ds_read_b128 v[192:195], v165 offset:37888
	ds_read_b128 v[200:203], v165 offset:39936
	global_load_lds_dwordx4 v[204:205], off
	v_lshl_add_u64 v[204:205], s[18:19], 0, v[146:147]
	s_mov_b32 m0, s72
	s_nop 0
	global_load_lds_dwordx4 v[204:205], off
	s_waitcnt lgkmcnt(8)
	s_barrier
	s_setprio 1
	s_waitcnt lgkmcnt(7)
	v_mfma_f32_16x16x32_bf16 v[124:127], v[128:131], v[154:157], v[124:127]
	v_mfma_f32_16x16x32_bf16 v[120:123], v[136:139], v[154:157], v[120:123]
	s_waitcnt lgkmcnt(6)
	v_mfma_f32_16x16x32_bf16 v[108:111], v[128:131], v[166:169], v[108:111]
	v_mfma_f32_16x16x32_bf16 v[104:107], v[136:139], v[166:169], v[104:107]
	s_waitcnt lgkmcnt(5)
	v_mfma_f32_16x16x32_bf16 v[92:95], v[128:131], v[188:191], v[92:95]
	v_mfma_f32_16x16x32_bf16 v[88:91], v[136:139], v[188:191], v[88:91]
	s_waitcnt lgkmcnt(4)
	v_mfma_f32_16x16x32_bf16 v[76:79], v[128:131], v[196:199], v[76:79]
	v_mfma_f32_16x16x32_bf16 v[72:75], v[136:139], v[196:199], v[72:75]
	s_waitcnt lgkmcnt(3)
	v_mfma_f32_16x16x32_bf16 v[124:127], v[132:135], v[158:161], v[124:127]
	v_mfma_f32_16x16x32_bf16 v[120:123], v[140:143], v[158:161], v[120:123]
	s_waitcnt lgkmcnt(2)
	v_mfma_f32_16x16x32_bf16 v[108:111], v[132:135], v[170:173], v[108:111]
	v_mfma_f32_16x16x32_bf16 v[104:107], v[140:143], v[170:173], v[104:107]
	s_waitcnt lgkmcnt(1)
	v_mfma_f32_16x16x32_bf16 v[92:95], v[132:135], v[192:195], v[92:95]
	v_mfma_f32_16x16x32_bf16 v[88:91], v[140:143], v[192:195], v[88:91]
	s_waitcnt lgkmcnt(0)
	v_mfma_f32_16x16x32_bf16 v[76:79], v[132:135], v[200:203], v[76:79]
	v_mfma_f32_16x16x32_bf16 v[72:75], v[140:143], v[200:203], v[72:75]
	s_setprio 0
	s_barrier
	s_add_i32 s29, 0, 0x1c000
	s_add_i32 s18, s28, s68
	v_add_u32_e32 v232, s29, v164
	v_lshl_add_u64 v[174:175], v[174:175], 0, s[40:41]
	s_mov_b32 m0, s18
	ds_read_b128 v[204:207], v232
	ds_read_b128 v[208:211], v232 offset:1024
	ds_read_b128 v[212:215], v232 offset:2048
	ds_read_b128 v[232:235], v232 offset:3072
	global_load_lds_dwordx4 v[174:175], off
	v_lshl_add_u64 v[174:175], v[216:217], 0, s[40:41]
	s_add_i32 m0, s18, 0x2000
	s_nop 0
	global_load_lds_dwordx4 v[174:175], off
	s_barrier
	s_setprio 1
	s_waitcnt lgkmcnt(3)
	v_mfma_f32_16x16x32_bf16 v[116:119], v[204:207], v[154:157], v[116:119]
	s_waitcnt lgkmcnt(1)
	v_mfma_f32_16x16x32_bf16 v[112:115], v[212:215], v[154:157], v[112:115]
	v_mfma_f32_16x16x32_bf16 v[100:103], v[204:207], v[166:169], v[100:103]
	v_mfma_f32_16x16x32_bf16 v[96:99], v[212:215], v[166:169], v[96:99]
	v_mfma_f32_16x16x32_bf16 v[84:87], v[204:207], v[188:191], v[84:87]
	v_mfma_f32_16x16x32_bf16 v[80:83], v[212:215], v[188:191], v[80:83]
	v_mfma_f32_16x16x32_bf16 v[68:71], v[204:207], v[196:199], v[68:71]
	v_mfma_f32_16x16x32_bf16 v[64:67], v[212:215], v[196:199], v[64:67]
	v_mfma_f32_16x16x32_bf16 v[116:119], v[208:211], v[158:161], v[116:119]
	s_waitcnt lgkmcnt(0)
	v_mfma_f32_16x16x32_bf16 v[112:115], v[232:235], v[158:161], v[112:115]
	v_mfma_f32_16x16x32_bf16 v[100:103], v[208:211], v[170:173], v[100:103]
	v_mfma_f32_16x16x32_bf16 v[96:99], v[232:235], v[170:173], v[96:99]
	v_mfma_f32_16x16x32_bf16 v[84:87], v[208:211], v[192:195], v[84:87]
	v_mfma_f32_16x16x32_bf16 v[80:83], v[232:235], v[192:195], v[80:83]
	v_mfma_f32_16x16x32_bf16 v[68:71], v[208:211], v[200:203], v[68:71]
	v_mfma_f32_16x16x32_bf16 v[64:67], v[232:235], v[200:203], v[64:67]
	s_setprio 0
	s_mov_b32 m0, s75
	v_lshl_add_u64 v[174:175], v[236:237], 0, s[40:41]
	s_barrier
	ds_read_b128 v[154:157], v165 offset:49152
	ds_read_b128 v[166:169], v165 offset:51200
	ds_read_b128 v[188:191], v165 offset:53248
	ds_read_b128 v[196:199], v165 offset:55296
	ds_read_b128 v[158:161], v165 offset:50176
	ds_read_b128 v[170:173], v165 offset:52224
	ds_read_b128 v[192:195], v165 offset:54272
	ds_read_b128 v[200:203], v165 offset:56320
	global_load_lds_dwordx4 v[174:175], off
	v_lshl_add_u64 v[174:175], v[238:239], 0, s[40:41]
	s_mov_b32 m0, s76
	s_nop 0
	global_load_lds_dwordx4 v[174:175], off
	s_barrier
	s_setprio 1
	s_waitcnt lgkmcnt(7)
	v_mfma_f32_16x16x32_bf16 v[60:63], v[128:131], v[154:157], v[60:63]
	v_mfma_f32_16x16x32_bf16 v[56:59], v[136:139], v[154:157], v[56:59]
	s_waitcnt lgkmcnt(6)
	v_mfma_f32_16x16x32_bf16 v[44:47], v[128:131], v[166:169], v[44:47]
	v_mfma_f32_16x16x32_bf16 v[40:43], v[136:139], v[166:169], v[40:43]
	s_waitcnt lgkmcnt(5)
	v_mfma_f32_16x16x32_bf16 v[28:31], v[128:131], v[188:191], v[28:31]
	v_mfma_f32_16x16x32_bf16 v[24:27], v[136:139], v[188:191], v[24:27]
	s_waitcnt lgkmcnt(4)
	v_mfma_f32_16x16x32_bf16 v[12:15], v[128:131], v[196:199], v[12:15]
	v_mfma_f32_16x16x32_bf16 v[8:11], v[136:139], v[196:199], v[8:11]
	s_waitcnt lgkmcnt(3)
	v_mfma_f32_16x16x32_bf16 v[60:63], v[132:135], v[158:161], v[60:63]
	v_mfma_f32_16x16x32_bf16 v[56:59], v[140:143], v[158:161], v[56:59]
	s_waitcnt lgkmcnt(2)
	v_mfma_f32_16x16x32_bf16 v[44:47], v[132:135], v[170:173], v[44:47]
	v_mfma_f32_16x16x32_bf16 v[40:43], v[140:143], v[170:173], v[40:43]
	s_waitcnt lgkmcnt(1)
	v_mfma_f32_16x16x32_bf16 v[28:31], v[132:135], v[192:195], v[28:31]
	v_mfma_f32_16x16x32_bf16 v[24:27], v[140:143], v[192:195], v[24:27]
	s_waitcnt lgkmcnt(0)
	v_mfma_f32_16x16x32_bf16 v[12:15], v[132:135], v[200:203], v[12:15]
	v_mfma_f32_16x16x32_bf16 v[8:11], v[140:143], v[200:203], v[8:11]
	s_setprio 0
	s_barrier
	s_add_u32 s18, s62, 0x18080
	s_addc_u32 s19, s63, 0
	s_add_i32 s28, s29, s68
	v_lshl_add_u64 v[128:129], s[18:19], 0, v[176:177]
	s_mov_b32 m0, s28
	s_nop 0
	global_load_lds_dwordx4 v[128:129], off
	v_lshl_add_u64 v[128:129], s[18:19], 0, v[148:149]
	s_add_i32 m0, s28, 0x2000
	s_nop 0
	global_load_lds_dwordx4 v[128:129], off
	s_waitcnt vmcnt(6)
	s_barrier
	s_setprio 1
	v_mfma_f32_16x16x32_bf16 v[52:55], v[204:207], v[154:157], v[52:55]
	v_mfma_f32_16x16x32_bf16 v[48:51], v[212:215], v[154:157], v[48:51]
	v_mfma_f32_16x16x32_bf16 v[36:39], v[204:207], v[166:169], v[36:39]
	v_mfma_f32_16x16x32_bf16 v[32:35], v[212:215], v[166:169], v[32:35]
	v_mfma_f32_16x16x32_bf16 v[20:23], v[204:207], v[188:191], v[20:23]
	v_mfma_f32_16x16x32_bf16 v[16:19], v[212:215], v[188:191], v[16:19]
	v_mfma_f32_16x16x32_bf16 v[4:7], v[204:207], v[196:199], v[4:7]
	v_mfma_f32_16x16x32_bf16 v[0:3], v[212:215], v[196:199], v[0:3]
	v_mfma_f32_16x16x32_bf16 v[52:55], v[208:211], v[158:161], v[52:55]
	v_mfma_f32_16x16x32_bf16 v[48:51], v[232:235], v[158:161], v[48:51]
	v_mfma_f32_16x16x32_bf16 v[36:39], v[208:211], v[170:173], v[36:39]
	v_mfma_f32_16x16x32_bf16 v[32:35], v[232:235], v[170:173], v[32:35]
	v_mfma_f32_16x16x32_bf16 v[20:23], v[208:211], v[192:195], v[20:23]
	v_mfma_f32_16x16x32_bf16 v[16:19], v[232:235], v[192:195], v[16:19]
	v_mfma_f32_16x16x32_bf16 v[4:7], v[208:211], v[200:203], v[4:7]
	v_mfma_f32_16x16x32_bf16 v[0:3], v[232:235], v[200:203], v[0:3]
	s_setprio 0
	s_add_u32 s85, s85, 0x100
	s_addc_u32 s91, s91, 0
	s_cmp_lt_i32 vcc_lo, s67
	s_mov_b64 s[18:19], s[4:5]
	s_mov_b32 s62, vcc_lo
	s_barrier
	s_cbranch_scc1 .LBB0_413
	s_ashr_i32 s4, s66, 2
	v_mov_b32_e32 v128, v163
	v_mov_b32_e32 v166, v162
	s_cmp_eq_u32 s4, 2
	s_cbranch_scc1 .LBB0_416
	s_mul_i32 s13, s4, 0x2280000
	s_mul_hi_i32 s5, s4, 0x2280000
	s_add_u32 s18, s13, 0x5858000
	s_addc_u32 s19, s5, 0
	s_mov_b32 s62, 1.0
	s_branch .LBB0_417

.LBB0_505:
	s_add_u32 s6, s4, 0xfff80080
	s_addc_u32 s7, s5, -1
	s_add_i32 s28, 0, 0x10000
	v_add_u32_e32 v154, s28, v144
	ds_read_b128 v[138:141], v154
	ds_read_b128 v[146:149], v154 offset:1024
	ds_read_b128 v[150:153], v154 offset:2048
	ds_read_b128 v[154:157], v154 offset:3072
	s_cmp_eq_u32 s72, 28
	s_cselect_b32 s9, s10, s7
	s_cselect_b32 s8, s11, s6
	s_cselect_b32 s7, s63, s71
	s_cselect_b32 s6, s65, s70
	v_lshl_add_u64 v[174:175], s[4:5], 0, v[134:135]
	s_add_i32 m0, s17, 0xc000
	ds_read_b128 v[158:161], v145
	ds_read_b128 v[166:169], v145 offset:2048
	ds_read_b128 v[188:191], v145 offset:4096
	ds_read_b128 v[196:199], v145 offset:6144
	ds_read_b128 v[162:165], v145 offset:1024
	ds_read_b128 v[170:173], v145 offset:3072
	ds_read_b128 v[192:195], v145 offset:5120
	ds_read_b128 v[200:203], v145 offset:7168
	global_load_lds_dwordx4 v[174:175], off
	v_lshl_add_u64 v[174:175], s[4:5], 0, v[136:137]
	s_add_i32 m0, s17, 0xe000
	s_nop 0
	global_load_lds_dwordx4 v[174:175], off
	s_waitcnt lgkmcnt(8)
	s_barrier
	s_setprio 1
	s_waitcnt lgkmcnt(7)
	v_mfma_f32_16x16x32_bf16 v[124:127], v[138:141], v[158:161], v[124:127]
	v_mfma_f32_16x16x32_bf16 v[120:123], v[150:153], v[158:161], v[120:123]
	s_waitcnt lgkmcnt(6)
	v_mfma_f32_16x16x32_bf16 v[116:119], v[138:141], v[166:169], v[116:119]
	v_mfma_f32_16x16x32_bf16 v[108:111], v[150:153], v[166:169], v[108:111]
	s_waitcnt lgkmcnt(5)
	v_mfma_f32_16x16x32_bf16 v[100:103], v[138:141], v[188:191], v[100:103]
	v_mfma_f32_16x16x32_bf16 v[92:95], v[150:153], v[188:191], v[92:95]
	s_waitcnt lgkmcnt(4)
	v_mfma_f32_16x16x32_bf16 v[84:87], v[138:141], v[196:199], v[84:87]
	v_mfma_f32_16x16x32_bf16 v[76:79], v[150:153], v[196:199], v[76:79]
	s_waitcnt lgkmcnt(3)
	v_mfma_f32_16x16x32_bf16 v[124:127], v[146:149], v[162:165], v[124:127]
	v_mfma_f32_16x16x32_bf16 v[120:123], v[154:157], v[162:165], v[120:123]
	s_waitcnt lgkmcnt(2)
	v_mfma_f32_16x16x32_bf16 v[116:119], v[146:149], v[170:173], v[116:119]
	v_mfma_f32_16x16x32_bf16 v[108:111], v[154:157], v[170:173], v[108:111]
	s_waitcnt lgkmcnt(1)
	v_mfma_f32_16x16x32_bf16 v[100:103], v[146:149], v[192:195], v[100:103]
	v_mfma_f32_16x16x32_bf16 v[92:95], v[154:157], v[192:195], v[92:95]
	s_waitcnt lgkmcnt(0)
	v_mfma_f32_16x16x32_bf16 v[84:87], v[146:149], v[200:203], v[84:87]
	v_mfma_f32_16x16x32_bf16 v[76:79], v[154:157], v[200:203], v[76:79]
	s_setprio 0
	s_barrier
	s_add_i32 s29, 0, 0x14000
	v_add_u32_e32 v174, s29, v144
	s_add_i32 s28, s28, s77
	ds_read_b128 v[204:207], v174
	ds_read_b128 v[208:211], v174 offset:1024
	ds_read_b128 v[212:215], v174 offset:2048
	ds_read_b128 v[232:235], v174 offset:3072
	v_lshl_add_u64 v[174:175], s[6:7], 0, v[176:177]
	s_mov_b32 m0, s28
	v_lshl_add_u64 v[216:217], s[6:7], 0, v[132:133]
	global_load_lds_dwordx4 v[174:175], off
	s_add_i32 m0, s28, 0x2000
	s_nop 0
	global_load_lds_dwordx4 v[216:217], off
	s_barrier
	s_setprio 1
	s_waitcnt lgkmcnt(3)
	v_mfma_f32_16x16x32_bf16 v[112:115], v[204:207], v[158:161], v[112:115]
	s_waitcnt lgkmcnt(1)
	v_mfma_f32_16x16x32_bf16 v[104:107], v[212:215], v[158:161], v[104:107]
	v_mfma_f32_16x16x32_bf16 v[96:99], v[204:207], v[166:169], v[96:99]
	v_mfma_f32_16x16x32_bf16 v[88:91], v[212:215], v[166:169], v[88:91]
	v_mfma_f32_16x16x32_bf16 v[80:83], v[204:207], v[188:191], v[80:83]
	v_mfma_f32_16x16x32_bf16 v[72:75], v[212:215], v[188:191], v[72:75]
	v_mfma_f32_16x16x32_bf16 v[68:71], v[204:207], v[196:199], v[68:71]
	v_mfma_f32_16x16x32_bf16 v[64:67], v[212:215], v[196:199], v[64:67]
	v_mfma_f32_16x16x32_bf16 v[112:115], v[208:211], v[162:165], v[112:115]
	s_waitcnt lgkmcnt(0)
	v_mfma_f32_16x16x32_bf16 v[104:107], v[232:235], v[162:165], v[104:107]
	v_mfma_f32_16x16x32_bf16 v[96:99], v[208:211], v[170:173], v[96:99]
	v_mfma_f32_16x16x32_bf16 v[88:91], v[232:235], v[170:173], v[88:91]
	v_mfma_f32_16x16x32_bf16 v[80:83], v[208:211], v[192:195], v[80:83]
	v_mfma_f32_16x16x32_bf16 v[72:75], v[232:235], v[192:195], v[72:75]
	v_mfma_f32_16x16x32_bf16 v[68:71], v[208:211], v[200:203], v[68:71]
	v_mfma_f32_16x16x32_bf16 v[64:67], v[232:235], v[200:203], v[64:67]
	s_setprio 0
	s_mov_b32 m0, s17
	v_lshl_add_u64 v[236:237], s[8:9], 0, v[128:129]
	s_barrier
	ds_read_b128 v[158:161], v145 offset:16384
	ds_read_b128 v[166:169], v145 offset:18432
	ds_read_b128 v[188:191], v145 offset:20480
	ds_read_b128 v[196:199], v145 offset:22528
	ds_read_b128 v[162:165], v145 offset:17408
	ds_read_b128 v[170:173], v145 offset:19456
	ds_read_b128 v[192:195], v145 offset:21504
	ds_read_b128 v[200:203], v145 offset:23552
	global_load_lds_dwordx4 v[236:237], off
	v_lshl_add_u64 v[238:239], s[8:9], 0, v[130:131]
	s_mov_b32 m0, s19
	s_nop 0
	global_load_lds_dwordx4 v[238:239], off
	s_barrier
	s_setprio 1
	s_waitcnt lgkmcnt(7)
	v_mfma_f32_16x16x32_bf16 v[60:63], v[138:141], v[158:161], v[60:63]
	v_mfma_f32_16x16x32_bf16 v[56:59], v[150:153], v[158:161], v[56:59]
	s_waitcnt lgkmcnt(6)
	v_mfma_f32_16x16x32_bf16 v[52:55], v[138:141], v[166:169], v[52:55]
	v_mfma_f32_16x16x32_bf16 v[44:47], v[150:153], v[166:169], v[44:47]
	s_waitcnt lgkmcnt(5)
	v_mfma_f32_16x16x32_bf16 v[36:39], v[138:141], v[188:191], v[36:39]
	v_mfma_f32_16x16x32_bf16 v[28:31], v[150:153], v[188:191], v[28:31]
	s_waitcnt lgkmcnt(4)
	v_mfma_f32_16x16x32_bf16 v[20:23], v[138:141], v[196:199], v[20:23]
	v_mfma_f32_16x16x32_bf16 v[12:15], v[150:153], v[196:199], v[12:15]
	s_waitcnt lgkmcnt(3)
	v_mfma_f32_16x16x32_bf16 v[60:63], v[146:149], v[162:165], v[60:63]
	v_mfma_f32_16x16x32_bf16 v[56:59], v[154:157], v[162:165], v[56:59]
	s_waitcnt lgkmcnt(2)
	v_mfma_f32_16x16x32_bf16 v[52:55], v[146:149], v[170:173], v[52:55]
	v_mfma_f32_16x16x32_bf16 v[44:47], v[154:157], v[170:173], v[44:47]
	s_waitcnt lgkmcnt(1)
	v_mfma_f32_16x16x32_bf16 v[36:39], v[146:149], v[192:195], v[36:39]
	v_mfma_f32_16x16x32_bf16 v[28:31], v[154:157], v[192:195], v[28:31]
	s_waitcnt lgkmcnt(0)
	v_mfma_f32_16x16x32_bf16 v[20:23], v[146:149], v[200:203], v[20:23]
	v_mfma_f32_16x16x32_bf16 v[12:15], v[154:157], v[200:203], v[12:15]
	s_setprio 0
	s_barrier
	s_add_u32 vcc_lo, s6, 0x80000
	s_addc_u32 vcc_hi, s7, 0
	s_add_i32 s28, s29, s77
	v_lshl_add_u64 v[138:139], vcc, 0, v[176:177]
	s_mov_b32 m0, s28
	s_nop 0
	global_load_lds_dwordx4 v[138:139], off
	v_lshl_add_u64 v[138:139], vcc, 0, v[132:133]
	s_add_i32 m0, s28, 0x2000
	s_nop 0
	global_load_lds_dwordx4 v[138:139], off
	s_waitcnt vmcnt(6)
	s_barrier
	s_setprio 1
	v_mfma_f32_16x16x32_bf16 v[48:51], v[204:207], v[158:161], v[48:51]
	v_mfma_f32_16x16x32_bf16 v[40:43], v[212:215], v[158:161], v[40:43]
	v_mfma_f32_16x16x32_bf16 v[32:35], v[204:207], v[166:169], v[32:35]
	v_mfma_f32_16x16x32_bf16 v[24:27], v[212:215], v[166:169], v[24:27]
	v_mfma_f32_16x16x32_bf16 v[16:19], v[204:207], v[188:191], v[16:19]
	v_mfma_f32_16x16x32_bf16 v[8:11], v[212:215], v[188:191], v[8:11]
	v_mfma_f32_16x16x32_bf16 v[4:7], v[204:207], v[196:199], v[4:7]
	v_mfma_f32_16x16x32_bf16 v[0:3], v[212:215], v[196:199], v[0:3]
	v_mfma_f32_16x16x32_bf16 v[48:51], v[208:211], v[162:165], v[48:51]
	v_mfma_f32_16x16x32_bf16 v[40:43], v[232:235], v[162:165], v[40:43]
	v_mfma_f32_16x16x32_bf16 v[32:35], v[208:211], v[170:173], v[32:35]
	v_mfma_f32_16x16x32_bf16 v[24:27], v[232:235], v[170:173], v[24:27]
	v_mfma_f32_16x16x32_bf16 v[16:19], v[208:211], v[192:195], v[16:19]
	v_mfma_f32_16x16x32_bf16 v[8:11], v[232:235], v[192:195], v[8:11]
	v_mfma_f32_16x16x32_bf16 v[4:7], v[208:211], v[200:203], v[4:7]
	v_mfma_f32_16x16x32_bf16 v[0:3], v[232:235], v[200:203], v[0:3]
	s_setprio 0
	s_add_i32 s28, 0, 0x18000
	v_add_u32_e32 v154, s28, v144
	s_barrier
	ds_read_b128 v[138:141], v154
	ds_read_b128 v[146:149], v154 offset:1024
	ds_read_b128 v[150:153], v154 offset:2048
	ds_read_b128 v[154:157], v154 offset:3072
	s_add_u32 s8, s8, 0x80000
	s_addc_u32 s9, s9, 0
	s_mov_b32 m0, s78
	v_lshl_add_u64 v[204:205], s[8:9], 0, v[128:129]
	ds_read_b128 v[158:161], v145 offset:32768
	ds_read_b128 v[166:169], v145 offset:34816
	ds_read_b128 v[188:191], v145 offset:36864
	ds_read_b128 v[196:199], v145 offset:38912
	ds_read_b128 v[162:165], v145 offset:33792
	ds_read_b128 v[170:173], v145 offset:35840
	ds_read_b128 v[192:195], v145 offset:37888
	ds_read_b128 v[200:203], v145 offset:39936
	global_load_lds_dwordx4 v[204:205], off
	v_lshl_add_u64 v[204:205], s[8:9], 0, v[130:131]
	s_mov_b32 m0, s79
	s_nop 0
	global_load_lds_dwordx4 v[204:205], off
	s_waitcnt lgkmcnt(8)
	s_barrier
	s_setprio 1
	s_waitcnt lgkmcnt(7)
	v_mfma_f32_16x16x32_bf16 v[124:127], v[138:141], v[158:161], v[124:127]
	v_mfma_f32_16x16x32_bf16 v[120:123], v[150:153], v[158:161], v[120:123]
	s_waitcnt lgkmcnt(6)
	v_mfma_f32_16x16x32_bf16 v[116:119], v[138:141], v[166:169], v[116:119]
	v_mfma_f32_16x16x32_bf16 v[108:111], v[150:153], v[166:169], v[108:111]
	s_waitcnt lgkmcnt(5)
	v_mfma_f32_16x16x32_bf16 v[100:103], v[138:141], v[188:191], v[100:103]
	v_mfma_f32_16x16x32_bf16 v[92:95], v[150:153], v[188:191], v[92:95]
	s_waitcnt lgkmcnt(4)
	v_mfma_f32_16x16x32_bf16 v[84:87], v[138:141], v[196:199], v[84:87]
	v_mfma_f32_16x16x32_bf16 v[76:79], v[150:153], v[196:199], v[76:79]
	s_waitcnt lgkmcnt(3)
	v_mfma_f32_16x16x32_bf16 v[124:127], v[146:149], v[162:165], v[124:127]
	v_mfma_f32_16x16x32_bf16 v[120:123], v[154:157], v[162:165], v[120:123]
	s_waitcnt lgkmcnt(2)
	v_mfma_f32_16x16x32_bf16 v[116:119], v[146:149], v[170:173], v[116:119]
	v_mfma_f32_16x16x32_bf16 v[108:111], v[154:157], v[170:173], v[108:111]
	s_waitcnt lgkmcnt(1)
	v_mfma_f32_16x16x32_bf16 v[100:103], v[146:149], v[192:195], v[100:103]
	v_mfma_f32_16x16x32_bf16 v[92:95], v[154:157], v[192:195], v[92:95]
	s_waitcnt lgkmcnt(0)
	v_mfma_f32_16x16x32_bf16 v[84:87], v[146:149], v[200:203], v[84:87]
	v_mfma_f32_16x16x32_bf16 v[76:79], v[154:157], v[200:203], v[76:79]
	s_setprio 0
	s_barrier
	s_add_i32 s8, 0, 0x1c000
	s_add_i32 s9, s28, s77
	v_add_u32_e32 v232, s8, v144
	v_lshl_add_u64 v[174:175], v[174:175], 0, s[40:41]
	s_mov_b32 m0, s9
	ds_read_b128 v[204:207], v232
	ds_read_b128 v[208:211], v232 offset:1024
	ds_read_b128 v[212:215], v232 offset:2048
	ds_read_b128 v[232:235], v232 offset:3072
	global_load_lds_dwordx4 v[174:175], off
	v_lshl_add_u64 v[174:175], v[216:217], 0, s[40:41]
	s_add_i32 m0, s9, 0x2000
	s_nop 0
	global_load_lds_dwordx4 v[174:175], off
	s_barrier
	s_setprio 1
	s_waitcnt lgkmcnt(3)
	v_mfma_f32_16x16x32_bf16 v[112:115], v[204:207], v[158:161], v[112:115]
	s_waitcnt lgkmcnt(1)
	v_mfma_f32_16x16x32_bf16 v[104:107], v[212:215], v[158:161], v[104:107]
	v_mfma_f32_16x16x32_bf16 v[96:99], v[204:207], v[166:169], v[96:99]
	v_mfma_f32_16x16x32_bf16 v[88:91], v[212:215], v[166:169], v[88:91]
	v_mfma_f32_16x16x32_bf16 v[80:83], v[204:207], v[188:191], v[80:83]
	v_mfma_f32_16x16x32_bf16 v[72:75], v[212:215], v[188:191], v[72:75]
	v_mfma_f32_16x16x32_bf16 v[68:71], v[204:207], v[196:199], v[68:71]
	v_mfma_f32_16x16x32_bf16 v[64:67], v[212:215], v[196:199], v[64:67]
	v_mfma_f32_16x16x32_bf16 v[112:115], v[208:211], v[162:165], v[112:115]
	s_waitcnt lgkmcnt(0)
	v_mfma_f32_16x16x32_bf16 v[104:107], v[232:235], v[162:165], v[104:107]
	v_mfma_f32_16x16x32_bf16 v[96:99], v[208:211], v[170:173], v[96:99]
	v_mfma_f32_16x16x32_bf16 v[88:91], v[232:235], v[170:173], v[88:91]
	v_mfma_f32_16x16x32_bf16 v[80:83], v[208:211], v[192:195], v[80:83]
	v_mfma_f32_16x16x32_bf16 v[72:75], v[232:235], v[192:195], v[72:75]
	v_mfma_f32_16x16x32_bf16 v[68:71], v[208:211], v[200:203], v[68:71]
	v_mfma_f32_16x16x32_bf16 v[64:67], v[232:235], v[200:203], v[64:67]
	s_setprio 0
	s_mov_b32 m0, s82
	v_lshl_add_u64 v[174:175], v[236:237], 0, s[40:41]
	s_barrier
	ds_read_b128 v[158:161], v145 offset:49152
	ds_read_b128 v[166:169], v145 offset:51200
	ds_read_b128 v[188:191], v145 offset:53248
	ds_read_b128 v[196:199], v145 offset:55296
	ds_read_b128 v[162:165], v145 offset:50176
	ds_read_b128 v[170:173], v145 offset:52224
	ds_read_b128 v[192:195], v145 offset:54272
	ds_read_b128 v[200:203], v145 offset:56320
	global_load_lds_dwordx4 v[174:175], off
	v_lshl_add_u64 v[174:175], v[238:239], 0, s[40:41]
	s_mov_b32 m0, s83
	s_nop 0
	global_load_lds_dwordx4 v[174:175], off
	s_barrier
	s_setprio 1
	s_waitcnt lgkmcnt(7)
	v_mfma_f32_16x16x32_bf16 v[60:63], v[138:141], v[158:161], v[60:63]
	v_mfma_f32_16x16x32_bf16 v[56:59], v[150:153], v[158:161], v[56:59]
	s_waitcnt lgkmcnt(6)
	v_mfma_f32_16x16x32_bf16 v[52:55], v[138:141], v[166:169], v[52:55]
	v_mfma_f32_16x16x32_bf16 v[44:47], v[150:153], v[166:169], v[44:47]
	s_waitcnt lgkmcnt(5)
	v_mfma_f32_16x16x32_bf16 v[36:39], v[138:141], v[188:191], v[36:39]
	v_mfma_f32_16x16x32_bf16 v[28:31], v[150:153], v[188:191], v[28:31]
	s_waitcnt lgkmcnt(4)
	v_mfma_f32_16x16x32_bf16 v[20:23], v[138:141], v[196:199], v[20:23]
	v_mfma_f32_16x16x32_bf16 v[12:15], v[150:153], v[196:199], v[12:15]
	s_waitcnt lgkmcnt(3)
	v_mfma_f32_16x16x32_bf16 v[60:63], v[146:149], v[162:165], v[60:63]
	v_mfma_f32_16x16x32_bf16 v[56:59], v[154:157], v[162:165], v[56:59]
	s_waitcnt lgkmcnt(2)
	v_mfma_f32_16x16x32_bf16 v[52:55], v[146:149], v[170:173], v[52:55]
	v_mfma_f32_16x16x32_bf16 v[44:47], v[154:157], v[170:173], v[44:47]
	s_waitcnt lgkmcnt(1)
	v_mfma_f32_16x16x32_bf16 v[36:39], v[146:149], v[192:195], v[36:39]
	v_mfma_f32_16x16x32_bf16 v[28:31], v[154:157], v[192:195], v[28:31]
	s_waitcnt lgkmcnt(0)
	v_mfma_f32_16x16x32_bf16 v[20:23], v[146:149], v[200:203], v[20:23]
	v_mfma_f32_16x16x32_bf16 v[12:15], v[154:157], v[200:203], v[12:15]
	s_setprio 0
	s_barrier
	s_add_u32 s6, s6, 0x80080
	s_addc_u32 s7, s7, 0
	s_add_i32 s8, s8, s77
	v_lshl_add_u64 v[138:139], s[6:7], 0, v[176:177]
	s_mov_b32 m0, s8
	s_nop 0
	global_load_lds_dwordx4 v[138:139], off
	v_lshl_add_u64 v[138:139], s[6:7], 0, v[132:133]
	s_add_i32 m0, s8, 0x2000
	s_nop 0
	global_load_lds_dwordx4 v[138:139], off
	s_waitcnt vmcnt(6)
	s_barrier
	s_setprio 1
	v_mfma_f32_16x16x32_bf16 v[48:51], v[204:207], v[158:161], v[48:51]
	v_mfma_f32_16x16x32_bf16 v[40:43], v[212:215], v[158:161], v[40:43]
	v_mfma_f32_16x16x32_bf16 v[32:35], v[204:207], v[166:169], v[32:35]
	v_mfma_f32_16x16x32_bf16 v[24:27], v[212:215], v[166:169], v[24:27]
	v_mfma_f32_16x16x32_bf16 v[16:19], v[204:207], v[188:191], v[16:19]
	v_mfma_f32_16x16x32_bf16 v[8:11], v[212:215], v[188:191], v[8:11]
	v_mfma_f32_16x16x32_bf16 v[4:7], v[204:207], v[196:199], v[4:7]
	v_mfma_f32_16x16x32_bf16 v[0:3], v[212:215], v[196:199], v[0:3]
	v_mfma_f32_16x16x32_bf16 v[48:51], v[208:211], v[162:165], v[48:51]
	v_mfma_f32_16x16x32_bf16 v[40:43], v[232:235], v[162:165], v[40:43]
	v_mfma_f32_16x16x32_bf16 v[32:35], v[208:211], v[170:173], v[32:35]
	v_mfma_f32_16x16x32_bf16 v[24:27], v[232:235], v[170:173], v[24:27]
	v_mfma_f32_16x16x32_bf16 v[16:19], v[208:211], v[192:195], v[16:19]
	v_mfma_f32_16x16x32_bf16 v[8:11], v[232:235], v[192:195], v[8:11]
	v_mfma_f32_16x16x32_bf16 v[4:7], v[208:211], v[200:203], v[4:7]
	v_mfma_f32_16x16x32_bf16 v[0:3], v[232:235], v[200:203], v[0:3]
	s_setprio 0
	s_add_i32 s72, s72, 2
	s_add_u32 s4, s4, 0x100
	s_addc_u32 s5, s5, 0
	s_add_u32 s70, s70, 0x100
	s_addc_u32 s71, s71, 0
	s_cmp_lt_u32 s72, 30
	s_barrier
	s_cbranch_scc1 .LBB0_505
	v_mov_b32_e32 v147, v142
	v_mov_b32_e32 v146, v143
	s_cmp_lt_i32 s16, 12
	s_mov_b64 s[4:5], -1
	s_cbranch_scc1 .LBB0_1052
	s_lshl_b32 s4, s18, 8
	s_add_i32 s4, s4, s80
	v_add_u32_e32 v149, s4, v147
	s_lshl_b32 s4, s16, 8
	s_add_i32 s4, s84, s4
	v_lshl_add_u32 v138, v146, 3, s4
	v_mad_i64_i32 v[140:141], s[4:5], v149, s97, 0
	v_cmp_gt_i32_e32 vcc, s34, v138
	s_and_saveexec_b64 s[10:11], vcc
	s_cbranch_execz .LBB0_541
	v_cmp_lt_i32_e64 s[8:9], 63, v138
	v_cmp_gt_u32_e64 s[4:5], s93, v138
	v_cmp_gt_u32_e64 s[6:7], s96, v138
	s_and_saveexec_b64 s[70:71], s[8:9]
	s_xor_b64 s[70:71], exec, s[70:71]
	s_cbranch_execz .LBB0_510
	v_mul_f32_e32 v139, 0xbfb8aa3b, v124
	v_exp_f32_e32 v139, v139
	s_nop 0
	v_add_f32_e32 v139, 1.0, v139
	v_rcp_f32_e32 v139, v139
	s_nop 0
	v_cndmask_b32_e64 v139, 0, v139, s[6:7]
	v_cndmask_b32_e64 v139, v139, v124, s[4:5]
	s_andn2_saveexec_b64 s[70:71], s[70:71]
	s_cbranch_execz .LBB0_512
	s_branch .LBB0_511

.LBB0_1114:
	s_add_i32 vcc_hi, s66, 2
	s_add_u32 s28, s64, 0x80
	s_addc_u32 s29, s65, 0
	s_add_i32 s88, 0, 0x10000
	v_add_u32_e32 v140, s88, v194
	ds_read_b128 v[128:131], v140
	ds_read_b128 v[132:135], v140 offset:1024
	ds_read_b128 v[136:139], v140 offset:2048
	ds_read_b128 v[140:143], v140 offset:3072
	s_cmp_eq_u32 s85, s66
	s_cselect_b32 s66, s4, s28
	s_cselect_b32 s67, s5, s29
	s_cselect_b32 s69, s7, vcc_lo
	s_cselect_b32 s68, s6, s91
	v_lshl_add_u64 v[174:175], s[64:65], 0, v[158:159]
	s_add_i32 m0, s70, 0xc000
	ds_read_b128 v[144:147], v195
	ds_read_b128 v[162:165], v195 offset:2048
	ds_read_b128 v[170:173], v195 offset:4096
	ds_read_b128 v[196:199], v195 offset:6144
	ds_read_b128 v[148:151], v195 offset:1024
	ds_read_b128 v[166:169], v195 offset:3072
	ds_read_b128 v[188:191], v195 offset:5120
	ds_read_b128 v[200:203], v195 offset:7168
	global_load_lds_dwordx4 v[174:175], off
	v_lshl_add_u64 v[174:175], s[64:65], 0, v[160:161]
	s_add_i32 m0, s70, 0xe000
	s_nop 0
	global_load_lds_dwordx4 v[174:175], off
	s_waitcnt lgkmcnt(8)
	s_barrier
	s_setprio 1
	s_waitcnt lgkmcnt(7)
	v_mfma_f32_16x16x32_bf16 v[124:127], v[128:131], v[144:147], v[124:127]
	v_mfma_f32_16x16x32_bf16 v[120:123], v[136:139], v[144:147], v[120:123]
	s_waitcnt lgkmcnt(6)
	v_mfma_f32_16x16x32_bf16 v[108:111], v[128:131], v[162:165], v[108:111]
	v_mfma_f32_16x16x32_bf16 v[104:107], v[136:139], v[162:165], v[104:107]
	s_waitcnt lgkmcnt(5)
	v_mfma_f32_16x16x32_bf16 v[92:95], v[128:131], v[170:173], v[92:95]
	v_mfma_f32_16x16x32_bf16 v[88:91], v[136:139], v[170:173], v[88:91]
	s_waitcnt lgkmcnt(4)
	v_mfma_f32_16x16x32_bf16 v[76:79], v[128:131], v[196:199], v[76:79]
	v_mfma_f32_16x16x32_bf16 v[72:75], v[136:139], v[196:199], v[72:75]
	s_waitcnt lgkmcnt(3)
	v_mfma_f32_16x16x32_bf16 v[124:127], v[132:135], v[148:151], v[124:127]
	v_mfma_f32_16x16x32_bf16 v[120:123], v[140:143], v[148:151], v[120:123]
	s_waitcnt lgkmcnt(2)
	v_mfma_f32_16x16x32_bf16 v[108:111], v[132:135], v[166:169], v[108:111]
	v_mfma_f32_16x16x32_bf16 v[104:107], v[140:143], v[166:169], v[104:107]
	s_waitcnt lgkmcnt(1)
	v_mfma_f32_16x16x32_bf16 v[92:95], v[132:135], v[188:191], v[92:95]
	v_mfma_f32_16x16x32_bf16 v[88:91], v[140:143], v[188:191], v[88:91]
	s_waitcnt lgkmcnt(0)
	v_mfma_f32_16x16x32_bf16 v[76:79], v[132:135], v[200:203], v[76:79]
	v_mfma_f32_16x16x32_bf16 v[72:75], v[140:143], v[200:203], v[72:75]
	s_setprio 0
	s_barrier
	s_add_i32 s28, 0, 0x14000
	v_add_u32_e32 v174, s28, v194
	s_add_i32 s29, s88, s47
	ds_read_b128 v[204:207], v174
	ds_read_b128 v[208:211], v174 offset:1024
	ds_read_b128 v[212:215], v174 offset:2048
	ds_read_b128 v[232:235], v174 offset:3072
	v_lshl_add_u64 v[174:175], s[68:69], 0, v[176:177]
	s_mov_b32 m0, s29
	v_lshl_add_u64 v[216:217], s[68:69], 0, v[156:157]
	global_load_lds_dwordx4 v[174:175], off
	s_add_i32 m0, s29, 0x2000
	s_nop 0
	global_load_lds_dwordx4 v[216:217], off
	s_barrier
	s_setprio 1
	s_waitcnt lgkmcnt(3)
	v_mfma_f32_16x16x32_bf16 v[116:119], v[204:207], v[144:147], v[116:119]
	s_waitcnt lgkmcnt(1)
	v_mfma_f32_16x16x32_bf16 v[112:115], v[212:215], v[144:147], v[112:115]
	v_mfma_f32_16x16x32_bf16 v[100:103], v[204:207], v[162:165], v[100:103]
	v_mfma_f32_16x16x32_bf16 v[96:99], v[212:215], v[162:165], v[96:99]
	v_mfma_f32_16x16x32_bf16 v[84:87], v[204:207], v[170:173], v[84:87]
	v_mfma_f32_16x16x32_bf16 v[80:83], v[212:215], v[170:173], v[80:83]
	v_mfma_f32_16x16x32_bf16 v[68:71], v[204:207], v[196:199], v[68:71]
	v_mfma_f32_16x16x32_bf16 v[64:67], v[212:215], v[196:199], v[64:67]
	v_mfma_f32_16x16x32_bf16 v[116:119], v[208:211], v[148:151], v[116:119]
	s_waitcnt lgkmcnt(0)
	v_mfma_f32_16x16x32_bf16 v[112:115], v[232:235], v[148:151], v[112:115]
	v_mfma_f32_16x16x32_bf16 v[100:103], v[208:211], v[166:169], v[100:103]
	v_mfma_f32_16x16x32_bf16 v[96:99], v[232:235], v[166:169], v[96:99]
	v_mfma_f32_16x16x32_bf16 v[84:87], v[208:211], v[188:191], v[84:87]
	v_mfma_f32_16x16x32_bf16 v[80:83], v[232:235], v[188:191], v[80:83]
	v_mfma_f32_16x16x32_bf16 v[68:71], v[208:211], v[200:203], v[68:71]
	v_mfma_f32_16x16x32_bf16 v[64:67], v[232:235], v[200:203], v[64:67]
	s_setprio 0
	s_mov_b32 m0, s70
	v_lshl_add_u64 v[236:237], s[66:67], 0, v[152:153]
	s_barrier
	ds_read_b128 v[144:147], v195 offset:16384
	ds_read_b128 v[162:165], v195 offset:18432
	ds_read_b128 v[170:173], v195 offset:20480
	ds_read_b128 v[196:199], v195 offset:22528
	ds_read_b128 v[148:151], v195 offset:17408
	ds_read_b128 v[166:169], v195 offset:19456
	ds_read_b128 v[188:191], v195 offset:21504
	ds_read_b128 v[200:203], v195 offset:23552
	global_load_lds_dwordx4 v[236:237], off
	v_lshl_add_u64 v[238:239], s[66:67], 0, v[154:155]
	s_mov_b32 m0, s71
	s_nop 0
	global_load_lds_dwordx4 v[238:239], off
	s_barrier
	s_setprio 1
	s_waitcnt lgkmcnt(7)
	v_mfma_f32_16x16x32_bf16 v[60:63], v[128:131], v[144:147], v[60:63]
	v_mfma_f32_16x16x32_bf16 v[56:59], v[136:139], v[144:147], v[56:59]
	s_waitcnt lgkmcnt(6)
	v_mfma_f32_16x16x32_bf16 v[44:47], v[128:131], v[162:165], v[44:47]
	v_mfma_f32_16x16x32_bf16 v[40:43], v[136:139], v[162:165], v[40:43]
	s_waitcnt lgkmcnt(5)
	v_mfma_f32_16x16x32_bf16 v[28:31], v[128:131], v[170:173], v[28:31]
	v_mfma_f32_16x16x32_bf16 v[24:27], v[136:139], v[170:173], v[24:27]
	s_waitcnt lgkmcnt(4)
	v_mfma_f32_16x16x32_bf16 v[12:15], v[128:131], v[196:199], v[12:15]
	v_mfma_f32_16x16x32_bf16 v[8:11], v[136:139], v[196:199], v[8:11]
	s_waitcnt lgkmcnt(3)
	v_mfma_f32_16x16x32_bf16 v[60:63], v[132:135], v[148:151], v[60:63]
	v_mfma_f32_16x16x32_bf16 v[56:59], v[140:143], v[148:151], v[56:59]
	s_waitcnt lgkmcnt(2)
	v_mfma_f32_16x16x32_bf16 v[44:47], v[132:135], v[166:169], v[44:47]
	v_mfma_f32_16x16x32_bf16 v[40:43], v[140:143], v[166:169], v[40:43]
	s_waitcnt lgkmcnt(1)
	v_mfma_f32_16x16x32_bf16 v[28:31], v[132:135], v[188:191], v[28:31]
	v_mfma_f32_16x16x32_bf16 v[24:27], v[140:143], v[188:191], v[24:27]
	s_waitcnt lgkmcnt(0)
	v_mfma_f32_16x16x32_bf16 v[12:15], v[132:135], v[200:203], v[12:15]
	v_mfma_f32_16x16x32_bf16 v[8:11], v[140:143], v[200:203], v[8:11]
	s_setprio 0
	s_barrier
	s_add_u32 s68, s68, s58
	s_addc_u32 s69, s69, 0
	s_add_i32 s28, s28, s47
	v_lshl_add_u64 v[240:241], s[68:69], 0, v[176:177]
	s_mov_b32 m0, s28
	v_lshl_add_u64 v[242:243], s[68:69], 0, v[156:157]
	global_load_lds_dwordx4 v[240:241], off
	s_add_i32 m0, s28, 0x2000
	s_nop 0
	global_load_lds_dwordx4 v[242:243], off
	s_waitcnt vmcnt(6)
	s_barrier
	s_setprio 1
	v_mfma_f32_16x16x32_bf16 v[52:55], v[204:207], v[144:147], v[52:55]
	v_mfma_f32_16x16x32_bf16 v[48:51], v[212:215], v[144:147], v[48:51]
	v_mfma_f32_16x16x32_bf16 v[36:39], v[204:207], v[162:165], v[36:39]
	v_mfma_f32_16x16x32_bf16 v[32:35], v[212:215], v[162:165], v[32:35]
	v_mfma_f32_16x16x32_bf16 v[20:23], v[204:207], v[170:173], v[20:23]
	v_mfma_f32_16x16x32_bf16 v[16:19], v[212:215], v[170:173], v[16:19]
	v_mfma_f32_16x16x32_bf16 v[4:7], v[204:207], v[196:199], v[4:7]
	v_mfma_f32_16x16x32_bf16 v[0:3], v[212:215], v[196:199], v[0:3]
	v_mfma_f32_16x16x32_bf16 v[52:55], v[208:211], v[148:151], v[52:55]
	v_mfma_f32_16x16x32_bf16 v[48:51], v[232:235], v[148:151], v[48:51]
	v_mfma_f32_16x16x32_bf16 v[36:39], v[208:211], v[166:169], v[36:39]
	v_mfma_f32_16x16x32_bf16 v[32:35], v[232:235], v[166:169], v[32:35]
	v_mfma_f32_16x16x32_bf16 v[20:23], v[208:211], v[188:191], v[20:23]
	v_mfma_f32_16x16x32_bf16 v[16:19], v[232:235], v[188:191], v[16:19]
	v_mfma_f32_16x16x32_bf16 v[4:7], v[208:211], v[200:203], v[4:7]
	v_mfma_f32_16x16x32_bf16 v[0:3], v[232:235], v[200:203], v[0:3]
	s_setprio 0
	s_add_i32 s28, 0, 0x18000
	v_add_u32_e32 v140, s28, v194
	s_barrier
	ds_read_b128 v[128:131], v140
	ds_read_b128 v[132:135], v140 offset:1024
	ds_read_b128 v[136:139], v140 offset:2048
	ds_read_b128 v[140:143], v140 offset:3072
	s_add_u32 s66, s66, s58
	s_addc_u32 s67, s67, 0
	s_mov_b32 m0, s72
	v_lshl_add_u64 v[204:205], s[66:67], 0, v[152:153]
	ds_read_b128 v[144:147], v195 offset:32768
	ds_read_b128 v[162:165], v195 offset:34816
	ds_read_b128 v[170:173], v195 offset:36864
	ds_read_b128 v[196:199], v195 offset:38912
	ds_read_b128 v[148:151], v195 offset:33792
	ds_read_b128 v[166:169], v195 offset:35840
	ds_read_b128 v[188:191], v195 offset:37888
	ds_read_b128 v[200:203], v195 offset:39936
	global_load_lds_dwordx4 v[204:205], off
	v_lshl_add_u64 v[204:205], s[66:67], 0, v[154:155]
	s_mov_b32 m0, s73
	s_nop 0
	global_load_lds_dwordx4 v[204:205], off
	s_waitcnt lgkmcnt(8)
	s_barrier
	s_setprio 1
	s_waitcnt lgkmcnt(7)
	v_mfma_f32_16x16x32_bf16 v[124:127], v[128:131], v[144:147], v[124:127]
	v_mfma_f32_16x16x32_bf16 v[120:123], v[136:139], v[144:147], v[120:123]
	s_waitcnt lgkmcnt(6)
	v_mfma_f32_16x16x32_bf16 v[108:111], v[128:131], v[162:165], v[108:111]
	v_mfma_f32_16x16x32_bf16 v[104:107], v[136:139], v[162:165], v[104:107]
	s_waitcnt lgkmcnt(5)
	v_mfma_f32_16x16x32_bf16 v[92:95], v[128:131], v[170:173], v[92:95]
	v_mfma_f32_16x16x32_bf16 v[88:91], v[136:139], v[170:173], v[88:91]
	s_waitcnt lgkmcnt(4)
	v_mfma_f32_16x16x32_bf16 v[76:79], v[128:131], v[196:199], v[76:79]
	v_mfma_f32_16x16x32_bf16 v[72:75], v[136:139], v[196:199], v[72:75]
	s_waitcnt lgkmcnt(3)
	v_mfma_f32_16x16x32_bf16 v[124:127], v[132:135], v[148:151], v[124:127]
	v_mfma_f32_16x16x32_bf16 v[120:123], v[140:143], v[148:151], v[120:123]
	s_waitcnt lgkmcnt(2)
	v_mfma_f32_16x16x32_bf16 v[108:111], v[132:135], v[166:169], v[108:111]
	v_mfma_f32_16x16x32_bf16 v[104:107], v[140:143], v[166:169], v[104:107]
	s_waitcnt lgkmcnt(1)
	v_mfma_f32_16x16x32_bf16 v[92:95], v[132:135], v[188:191], v[92:95]
	v_mfma_f32_16x16x32_bf16 v[88:91], v[140:143], v[188:191], v[88:91]
	s_waitcnt lgkmcnt(0)
	v_mfma_f32_16x16x32_bf16 v[76:79], v[132:135], v[200:203], v[76:79]
	v_mfma_f32_16x16x32_bf16 v[72:75], v[140:143], v[200:203], v[72:75]
	s_setprio 0
	s_barrier
	s_add_i32 s29, 0, 0x1c000
	s_add_i32 s28, s28, s47
	v_add_u32_e32 v232, s29, v194
	v_lshl_add_u64 v[174:175], v[174:175], 0, s[40:41]
	s_mov_b32 m0, s28
	ds_read_b128 v[204:207], v232
	ds_read_b128 v[208:211], v232 offset:1024
	ds_read_b128 v[212:215], v232 offset:2048
	ds_read_b128 v[232:235], v232 offset:3072
	global_load_lds_dwordx4 v[174:175], off
	v_lshl_add_u64 v[174:175], v[216:217], 0, s[40:41]
	s_add_i32 m0, s28, 0x2000
	s_nop 0
	global_load_lds_dwordx4 v[174:175], off
	s_barrier
	s_setprio 1
	s_waitcnt lgkmcnt(3)
	v_mfma_f32_16x16x32_bf16 v[116:119], v[204:207], v[144:147], v[116:119]
	s_waitcnt lgkmcnt(1)
	v_mfma_f32_16x16x32_bf16 v[112:115], v[212:215], v[144:147], v[112:115]
	v_mfma_f32_16x16x32_bf16 v[100:103], v[204:207], v[162:165], v[100:103]
	v_mfma_f32_16x16x32_bf16 v[96:99], v[212:215], v[162:165], v[96:99]
	v_mfma_f32_16x16x32_bf16 v[84:87], v[204:207], v[170:173], v[84:87]
	v_mfma_f32_16x16x32_bf16 v[80:83], v[212:215], v[170:173], v[80:83]
	v_mfma_f32_16x16x32_bf16 v[68:71], v[204:207], v[196:199], v[68:71]
	v_mfma_f32_16x16x32_bf16 v[64:67], v[212:215], v[196:199], v[64:67]
	v_mfma_f32_16x16x32_bf16 v[116:119], v[208:211], v[148:151], v[116:119]
	s_waitcnt lgkmcnt(0)
	v_mfma_f32_16x16x32_bf16 v[112:115], v[232:235], v[148:151], v[112:115]
	v_mfma_f32_16x16x32_bf16 v[100:103], v[208:211], v[166:169], v[100:103]
	v_mfma_f32_16x16x32_bf16 v[96:99], v[232:235], v[166:169], v[96:99]
	v_mfma_f32_16x16x32_bf16 v[84:87], v[208:211], v[188:191], v[84:87]
	v_mfma_f32_16x16x32_bf16 v[80:83], v[232:235], v[188:191], v[80:83]
	v_mfma_f32_16x16x32_bf16 v[68:71], v[208:211], v[200:203], v[68:71]
	v_mfma_f32_16x16x32_bf16 v[64:67], v[232:235], v[200:203], v[64:67]
	s_setprio 0
	s_mov_b32 m0, s74
	v_lshl_add_u64 v[174:175], v[236:237], 0, s[40:41]
	s_barrier
	ds_read_b128 v[144:147], v195 offset:49152
	ds_read_b128 v[162:165], v195 offset:51200
	ds_read_b128 v[170:173], v195 offset:53248
	ds_read_b128 v[196:199], v195 offset:55296
	ds_read_b128 v[148:151], v195 offset:50176
	ds_read_b128 v[166:169], v195 offset:52224
	ds_read_b128 v[188:191], v195 offset:54272
	ds_read_b128 v[200:203], v195 offset:56320
	global_load_lds_dwordx4 v[174:175], off
	v_lshl_add_u64 v[174:175], v[238:239], 0, s[40:41]
	s_mov_b32 m0, s75
	s_nop 0
	global_load_lds_dwordx4 v[174:175], off
	s_barrier
	s_setprio 1
	s_waitcnt lgkmcnt(7)
	v_mfma_f32_16x16x32_bf16 v[60:63], v[128:131], v[144:147], v[60:63]
	v_mfma_f32_16x16x32_bf16 v[56:59], v[136:139], v[144:147], v[56:59]
	s_waitcnt lgkmcnt(6)
	v_mfma_f32_16x16x32_bf16 v[44:47], v[128:131], v[162:165], v[44:47]
	v_mfma_f32_16x16x32_bf16 v[40:43], v[136:139], v[162:165], v[40:43]
	s_waitcnt lgkmcnt(5)
	v_mfma_f32_16x16x32_bf16 v[28:31], v[128:131], v[170:173], v[28:31]
	v_mfma_f32_16x16x32_bf16 v[24:27], v[136:139], v[170:173], v[24:27]
	s_waitcnt lgkmcnt(4)
	v_mfma_f32_16x16x32_bf16 v[12:15], v[128:131], v[196:199], v[12:15]
	v_mfma_f32_16x16x32_bf16 v[8:11], v[136:139], v[196:199], v[8:11]
	s_waitcnt lgkmcnt(3)
	v_mfma_f32_16x16x32_bf16 v[60:63], v[132:135], v[148:151], v[60:63]
	v_mfma_f32_16x16x32_bf16 v[56:59], v[140:143], v[148:151], v[56:59]
	s_waitcnt lgkmcnt(2)
	v_mfma_f32_16x16x32_bf16 v[44:47], v[132:135], v[166:169], v[44:47]
	v_mfma_f32_16x16x32_bf16 v[40:43], v[140:143], v[166:169], v[40:43]
	s_waitcnt lgkmcnt(1)
	v_mfma_f32_16x16x32_bf16 v[28:31], v[132:135], v[188:191], v[28:31]
	v_mfma_f32_16x16x32_bf16 v[24:27], v[140:143], v[188:191], v[24:27]
	s_waitcnt lgkmcnt(0)
	v_mfma_f32_16x16x32_bf16 v[12:15], v[132:135], v[200:203], v[12:15]
	v_mfma_f32_16x16x32_bf16 v[8:11], v[140:143], v[200:203], v[8:11]
	s_setprio 0
	s_barrier
	s_add_i32 s28, s29, s47
	v_lshl_add_u64 v[128:129], v[240:241], 0, s[40:41]
	s_mov_b32 m0, s28
	s_nop 0
	global_load_lds_dwordx4 v[128:129], off
	v_lshl_add_u64 v[128:129], v[242:243], 0, s[40:41]
	s_add_i32 m0, s28, 0x2000
	s_nop 0
	global_load_lds_dwordx4 v[128:129], off
	s_waitcnt vmcnt(6)
	s_barrier
	s_setprio 1
	v_mfma_f32_16x16x32_bf16 v[52:55], v[204:207], v[144:147], v[52:55]
	v_mfma_f32_16x16x32_bf16 v[48:51], v[212:215], v[144:147], v[48:51]
	v_mfma_f32_16x16x32_bf16 v[36:39], v[204:207], v[162:165], v[36:39]
	v_mfma_f32_16x16x32_bf16 v[32:35], v[212:215], v[162:165], v[32:35]
	v_mfma_f32_16x16x32_bf16 v[20:23], v[204:207], v[170:173], v[20:23]
	v_mfma_f32_16x16x32_bf16 v[16:19], v[212:215], v[170:173], v[16:19]
	v_mfma_f32_16x16x32_bf16 v[4:7], v[204:207], v[196:199], v[4:7]
	v_mfma_f32_16x16x32_bf16 v[0:3], v[212:215], v[196:199], v[0:3]
	v_mfma_f32_16x16x32_bf16 v[52:55], v[208:211], v[148:151], v[52:55]
	v_mfma_f32_16x16x32_bf16 v[48:51], v[232:235], v[148:151], v[48:51]
	v_mfma_f32_16x16x32_bf16 v[36:39], v[208:211], v[166:169], v[36:39]
	v_mfma_f32_16x16x32_bf16 v[32:35], v[232:235], v[166:169], v[32:35]
	v_mfma_f32_16x16x32_bf16 v[20:23], v[208:211], v[188:191], v[20:23]
	v_mfma_f32_16x16x32_bf16 v[16:19], v[232:235], v[188:191], v[16:19]
	v_mfma_f32_16x16x32_bf16 v[4:7], v[208:211], v[200:203], v[4:7]
	v_mfma_f32_16x16x32_bf16 v[0:3], v[232:235], v[200:203], v[0:3]
	s_setprio 0
	s_add_u32 s64, s64, 0x100
	s_addc_u32 s65, s65, 0
	s_add_u32 s91, s91, 0x100
	s_addc_u32 vcc_lo, vcc_lo, 0
	s_cmp_lt_i32 vcc_hi, s76
	s_mov_b32 s66, vcc_hi
	s_barrier
	s_cbranch_scc1 .LBB0_1114
	s_lshl_b32 s28, s84, 8
	v_mov_b32_e32 v128, v193
	v_mov_b32_e32 v129, v192
	s_add_i32 s28, s28, s78
	s_lshl_b32 s64, s24, 2
	v_add_u32_e32 v166, s28, v129
	s_lshl_b32 s28, s24, 8
	s_or_b32 s28, s28, s79
	v_lshl_add_u32 v162, v128, 3, s28
	v_ashrrev_i32_e32 v163, 31, v162
	v_lshlrev_b64 v[204:205], 1, v[162:163]
	v_ashrrev_i32_e32 v167, 31, v166
	v_lshl_add_u64 v[164:165], s[12:13], 0, v[204:205]
	v_lshlrev_b64 v[206:207], 11, v[166:167]
	v_cmp_eq_u32_e32 vcc, 0, v128
	v_lshl_add_u64 v[128:129], v[164:165], 0, v[206:207]
	global_load_dwordx4 v[196:199], v[128:129], off
	global_load_dwordx4 v[200:203], v[128:129], off offset:256
	v_add_u32_e32 v188, 16, v166
	v_ashrrev_i32_e32 v189, 31, v188
	v_add_u32_e32 v172, 32, v166
	v_lshlrev_b64 v[190:191], 11, v[188:189]
	v_ashrrev_i32_e32 v173, 31, v172
	v_add_u32_e32 v168, 48, v166
	v_lshl_add_u64 v[128:129], v[164:165], 0, v[190:191]
	v_lshlrev_b64 v[174:175], 11, v[172:173]
	v_ashrrev_i32_e32 v169, 31, v168
	global_load_dwordx4 v[148:151], v[128:129], off
	global_load_dwordx4 v[144:147], v[128:129], off offset:256
	v_lshl_add_u64 v[128:129], v[164:165], 0, v[174:175]
	v_lshlrev_b64 v[170:171], 11, v[168:169]
	global_load_dwordx4 v[140:143], v[128:129], off
	global_load_dwordx4 v[136:139], v[128:129], off offset:256
	v_lshl_add_u64 v[128:129], v[164:165], 0, v[170:171]
	global_load_dwordx4 v[132:135], v[128:129], off
	s_nop 0
	global_load_dwordx4 v[128:131], v[128:129], off offset:256
	v_lshl_add_u64 v[206:207], s[12:13], 0, v[206:207]
	v_lshl_add_u64 v[204:205], v[206:207], 0, v[204:205]
	s_ashr_i32 s65, s64, 31
	s_waitcnt vmcnt(0)
	v_lshlrev_b32_e32 v208, 16, v196
	v_and_b32_e32 v209, 0xffff0000, v196
	v_lshlrev_b32_e32 v196, 16, v197
	v_and_b32_e32 v197, 0xffff0000, v197
	v_lshlrev_b32_e32 v210, 16, v198
	v_and_b32_e32 v211, 0xffff0000, v198
	v_lshlrev_b32_e32 v198, 16, v199
	v_and_b32_e32 v199, 0xffff0000, v199
	v_pk_fma_f32 v[126:127], s[62:63], v[126:127], v[196:197]
	v_pk_fma_f32 v[124:125], s[10:11], v[124:125], v[208:209]
	v_pk_fma_f32 v[196:197], s[62:63], v[122:123], v[198:199]
	v_pk_fma_f32 v[198:199], s[10:11], v[120:121], v[210:211]
	v_cvt_pk_bf16_f32 v120, v124, v125
	v_cvt_pk_bf16_f32 v121, v126, v127
	s_nop 0
	v_cvt_pk_bf16_f32 v122, v198, v199
	v_cvt_pk_bf16_f32 v123, v196, v197
	global_store_dwordx4 v[204:205], v[120:123], off
	s_nop 1
	v_pk_mul_f32 v[120:121], v[198:199], v[198:199]
	v_pk_mul_f32 v[122:123], v[196:197], v[196:197]
	v_pk_fma_f32 v[120:121], v[124:125], v[124:125], v[120:121]
	v_pk_fma_f32 v[122:123], v[126:127], v[126:127], v[122:123]
	v_add_f32_e32 v120, v120, v121
	v_add_f32_e32 v121, v122, v123
	v_add_f32_e32 v196, v120, v121
	v_lshlrev_b32_e32 v120, 16, v200
	v_and_b32_e32 v121, 0xffff0000, v200
	v_lshlrev_b32_e32 v122, 16, v201
	v_and_b32_e32 v123, 0xffff0000, v201
	v_lshlrev_b32_e32 v124, 16, v202
	v_and_b32_e32 v125, 0xffff0000, v202
	v_lshlrev_b32_e32 v126, 16, v203
	v_and_b32_e32 v127, 0xffff0000, v203
	v_pk_fma_f32 v[118:119], s[62:63], v[118:119], v[122:123]
	v_pk_fma_f32 v[116:117], s[10:11], v[116:117], v[120:121]
	v_pk_fma_f32 v[120:121], s[62:63], v[114:115], v[126:127]
	v_pk_fma_f32 v[122:123], s[10:11], v[112:113], v[124:125]
	v_cvt_pk_bf16_f32 v112, v116, v117
	v_cvt_pk_bf16_f32 v113, v118, v119
	s_nop 0
	v_cvt_pk_bf16_f32 v114, v122, v123
	v_cvt_pk_bf16_f32 v115, v120, v121
	global_store_dwordx4 v[204:205], v[112:115], off offset:256
	s_nop 1
	v_pk_mul_f32 v[112:113], v[122:123], v[122:123]
	v_pk_mul_f32 v[114:115], v[120:121], v[120:121]
	v_pk_fma_f32 v[112:113], v[116:117], v[116:117], v[112:113]
	v_pk_fma_f32 v[114:115], v[118:119], v[118:119], v[114:115]
	v_add_f32_e32 v112, v112, v113
	v_add_f32_e32 v113, v114, v115
	v_add_f32_e32 v112, v112, v113
	v_add_f32_e32 v112, v196, v112
	ds_bpermute_b32 v113, v219, v112
	s_waitcnt lgkmcnt(0)
	v_add_f32_e32 v112, v112, v113
	ds_bpermute_b32 v113, v218, v112
	s_and_saveexec_b64 s[66:67], vcc
	s_cbranch_execz .LBB0_1117
	v_lshlrev_b64 v[114:115], 6, v[166:167]
	v_lshl_add_u64 v[114:115], s[8:9], 0, v[114:115]
	v_lshl_add_u64 v[114:115], s[64:65], 2, v[114:115]
	s_lshl_b32 s24, s77, 2
	v_lshl_add_u64 v[114:115], v[114:115], 0, s[24:25]
	s_waitcnt lgkmcnt(0)
	v_add_f32_e32 v112, v112, v113
	global_store_dword v[114:115], v112, off

.LBB0_1282:
	s_add_i32 s81, s60, 2
	s_add_u32 s28, s58, 0x80
	s_addc_u32 s29, s59, 0
	s_add_i32 s82, 0, 0x10000
	v_add_u32_e32 v140, s82, v195
	ds_read_b128 v[128:131], v140
	ds_read_b128 v[132:135], v140 offset:1024
	ds_read_b128 v[136:139], v140 offset:2048
	ds_read_b128 v[140:143], v140 offset:3072
	s_cmp_eq_u32 s5, s60
	s_cselect_b32 s60, s56, s28
	s_cselect_b32 s61, s57, s29
	s_cselect_b32 s63, s3, s80
	s_cselect_b32 s62, s2, s21
	v_lshl_add_u64 v[174:175], s[58:59], 0, v[158:159]
	s_add_i32 m0, s66, 0xc000
	ds_read_b128 v[144:147], v196
	ds_read_b128 v[162:165], v196 offset:2048
	ds_read_b128 v[170:173], v196 offset:4096
	ds_read_b128 v[198:201], v196 offset:6144
	ds_read_b128 v[148:151], v196 offset:1024
	ds_read_b128 v[166:169], v196 offset:3072
	ds_read_b128 v[188:191], v196 offset:5120
	ds_read_b128 v[202:205], v196 offset:7168
	global_load_lds_dwordx4 v[174:175], off
	v_lshl_add_u64 v[174:175], s[58:59], 0, v[160:161]
	s_add_i32 m0, s66, 0xe000
	s_nop 0
	global_load_lds_dwordx4 v[174:175], off
	s_waitcnt lgkmcnt(8)
	s_barrier
	s_setprio 1
	s_waitcnt lgkmcnt(7)
	v_mfma_f32_16x16x32_bf16 v[124:127], v[128:131], v[144:147], v[124:127]
	v_mfma_f32_16x16x32_bf16 v[120:123], v[136:139], v[144:147], v[120:123]
	s_waitcnt lgkmcnt(6)
	v_mfma_f32_16x16x32_bf16 v[108:111], v[128:131], v[162:165], v[108:111]
	v_mfma_f32_16x16x32_bf16 v[104:107], v[136:139], v[162:165], v[104:107]
	s_waitcnt lgkmcnt(5)
	v_mfma_f32_16x16x32_bf16 v[92:95], v[128:131], v[170:173], v[92:95]
	v_mfma_f32_16x16x32_bf16 v[88:91], v[136:139], v[170:173], v[88:91]
	s_waitcnt lgkmcnt(4)
	v_mfma_f32_16x16x32_bf16 v[76:79], v[128:131], v[198:201], v[76:79]
	v_mfma_f32_16x16x32_bf16 v[72:75], v[136:139], v[198:201], v[72:75]
	s_waitcnt lgkmcnt(3)
	v_mfma_f32_16x16x32_bf16 v[124:127], v[132:135], v[148:151], v[124:127]
	v_mfma_f32_16x16x32_bf16 v[120:123], v[140:143], v[148:151], v[120:123]
	s_waitcnt lgkmcnt(2)
	v_mfma_f32_16x16x32_bf16 v[108:111], v[132:135], v[166:169], v[108:111]
	v_mfma_f32_16x16x32_bf16 v[104:107], v[140:143], v[166:169], v[104:107]
	s_waitcnt lgkmcnt(1)
	v_mfma_f32_16x16x32_bf16 v[92:95], v[132:135], v[188:191], v[92:95]
	v_mfma_f32_16x16x32_bf16 v[88:91], v[140:143], v[188:191], v[88:91]
	s_waitcnt lgkmcnt(0)
	v_mfma_f32_16x16x32_bf16 v[76:79], v[132:135], v[202:205], v[76:79]
	v_mfma_f32_16x16x32_bf16 v[72:75], v[140:143], v[202:205], v[72:75]
	s_setprio 0
	s_barrier
	s_add_i32 s28, 0, 0x14000
	v_add_u32_e32 v174, s28, v195
	s_add_i32 s29, s82, s65
	ds_read_b128 v[206:209], v174
	ds_read_b128 v[210:213], v174 offset:1024
	ds_read_b128 v[214:217], v174 offset:2048
	ds_read_b128 v[232:235], v174 offset:3072
	v_lshl_add_u64 v[174:175], s[62:63], 0, v[176:177]
	s_mov_b32 m0, s29
	v_lshl_add_u64 v[236:237], s[62:63], 0, v[156:157]
	global_load_lds_dwordx4 v[174:175], off
	s_add_i32 m0, s29, 0x2000
	s_nop 0
	global_load_lds_dwordx4 v[236:237], off
	s_barrier
	s_setprio 1
	s_waitcnt lgkmcnt(3)
	v_mfma_f32_16x16x32_bf16 v[116:119], v[206:209], v[144:147], v[116:119]
	s_waitcnt lgkmcnt(1)
	v_mfma_f32_16x16x32_bf16 v[112:115], v[214:217], v[144:147], v[112:115]
	v_mfma_f32_16x16x32_bf16 v[100:103], v[206:209], v[162:165], v[100:103]
	v_mfma_f32_16x16x32_bf16 v[96:99], v[214:217], v[162:165], v[96:99]
	v_mfma_f32_16x16x32_bf16 v[84:87], v[206:209], v[170:173], v[84:87]
	v_mfma_f32_16x16x32_bf16 v[80:83], v[214:217], v[170:173], v[80:83]
	v_mfma_f32_16x16x32_bf16 v[68:71], v[206:209], v[198:201], v[68:71]
	v_mfma_f32_16x16x32_bf16 v[64:67], v[214:217], v[198:201], v[64:67]
	v_mfma_f32_16x16x32_bf16 v[116:119], v[210:213], v[148:151], v[116:119]
	s_waitcnt lgkmcnt(0)
	v_mfma_f32_16x16x32_bf16 v[112:115], v[232:235], v[148:151], v[112:115]
	v_mfma_f32_16x16x32_bf16 v[100:103], v[210:213], v[166:169], v[100:103]
	v_mfma_f32_16x16x32_bf16 v[96:99], v[232:235], v[166:169], v[96:99]
	v_mfma_f32_16x16x32_bf16 v[84:87], v[210:213], v[188:191], v[84:87]
	v_mfma_f32_16x16x32_bf16 v[80:83], v[232:235], v[188:191], v[80:83]
	v_mfma_f32_16x16x32_bf16 v[68:71], v[210:213], v[202:205], v[68:71]
	v_mfma_f32_16x16x32_bf16 v[64:67], v[232:235], v[202:205], v[64:67]
	s_setprio 0
	s_mov_b32 m0, s66
	v_lshl_add_u64 v[238:239], s[60:61], 0, v[152:153]
	s_barrier
	ds_read_b128 v[144:147], v196 offset:16384
	ds_read_b128 v[162:165], v196 offset:18432
	ds_read_b128 v[170:173], v196 offset:20480
	ds_read_b128 v[198:201], v196 offset:22528
	ds_read_b128 v[148:151], v196 offset:17408
	ds_read_b128 v[166:169], v196 offset:19456
	ds_read_b128 v[188:191], v196 offset:21504
	ds_read_b128 v[202:205], v196 offset:23552
	global_load_lds_dwordx4 v[238:239], off
	v_lshl_add_u64 v[240:241], s[60:61], 0, v[154:155]
	s_mov_b32 m0, s67
	s_nop 0
	global_load_lds_dwordx4 v[240:241], off
	s_barrier
	s_setprio 1
	s_waitcnt lgkmcnt(7)
	v_mfma_f32_16x16x32_bf16 v[60:63], v[128:131], v[144:147], v[60:63]
	v_mfma_f32_16x16x32_bf16 v[56:59], v[136:139], v[144:147], v[56:59]
	s_waitcnt lgkmcnt(6)
	v_mfma_f32_16x16x32_bf16 v[44:47], v[128:131], v[162:165], v[44:47]
	v_mfma_f32_16x16x32_bf16 v[40:43], v[136:139], v[162:165], v[40:43]
	s_waitcnt lgkmcnt(5)
	v_mfma_f32_16x16x32_bf16 v[28:31], v[128:131], v[170:173], v[28:31]
	v_mfma_f32_16x16x32_bf16 v[24:27], v[136:139], v[170:173], v[24:27]
	s_waitcnt lgkmcnt(4)
	v_mfma_f32_16x16x32_bf16 v[12:15], v[128:131], v[198:201], v[12:15]
	v_mfma_f32_16x16x32_bf16 v[8:11], v[136:139], v[198:201], v[8:11]
	s_waitcnt lgkmcnt(3)
	v_mfma_f32_16x16x32_bf16 v[60:63], v[132:135], v[148:151], v[60:63]
	v_mfma_f32_16x16x32_bf16 v[56:59], v[140:143], v[148:151], v[56:59]
	s_waitcnt lgkmcnt(2)
	v_mfma_f32_16x16x32_bf16 v[44:47], v[132:135], v[166:169], v[44:47]
	v_mfma_f32_16x16x32_bf16 v[40:43], v[140:143], v[166:169], v[40:43]
	s_waitcnt lgkmcnt(1)
	v_mfma_f32_16x16x32_bf16 v[28:31], v[132:135], v[188:191], v[28:31]
	v_mfma_f32_16x16x32_bf16 v[24:27], v[140:143], v[188:191], v[24:27]
	s_waitcnt lgkmcnt(0)
	v_mfma_f32_16x16x32_bf16 v[12:15], v[132:135], v[202:205], v[12:15]
	v_mfma_f32_16x16x32_bf16 v[8:11], v[140:143], v[202:205], v[8:11]
	s_setprio 0
	s_barrier
	s_add_u32 s62, s62, s4
	s_addc_u32 s63, s63, 0
	s_add_i32 s28, s28, s65
	v_lshl_add_u64 v[242:243], s[62:63], 0, v[176:177]
	s_mov_b32 m0, s28
	v_lshl_add_u64 v[244:245], s[62:63], 0, v[156:157]
	global_load_lds_dwordx4 v[242:243], off
	s_add_i32 m0, s28, 0x2000
	s_nop 0
	global_load_lds_dwordx4 v[244:245], off
	s_waitcnt vmcnt(6)
	s_barrier
	s_setprio 1
	v_mfma_f32_16x16x32_bf16 v[52:55], v[206:209], v[144:147], v[52:55]
	v_mfma_f32_16x16x32_bf16 v[48:51], v[214:217], v[144:147], v[48:51]
	v_mfma_f32_16x16x32_bf16 v[36:39], v[206:209], v[162:165], v[36:39]
	v_mfma_f32_16x16x32_bf16 v[32:35], v[214:217], v[162:165], v[32:35]
	v_mfma_f32_16x16x32_bf16 v[20:23], v[206:209], v[170:173], v[20:23]
	v_mfma_f32_16x16x32_bf16 v[16:19], v[214:217], v[170:173], v[16:19]
	v_mfma_f32_16x16x32_bf16 v[4:7], v[206:209], v[198:201], v[4:7]
	v_mfma_f32_16x16x32_bf16 v[0:3], v[214:217], v[198:201], v[0:3]
	v_mfma_f32_16x16x32_bf16 v[52:55], v[210:213], v[148:151], v[52:55]
	v_mfma_f32_16x16x32_bf16 v[48:51], v[232:235], v[148:151], v[48:51]
	v_mfma_f32_16x16x32_bf16 v[36:39], v[210:213], v[166:169], v[36:39]
	v_mfma_f32_16x16x32_bf16 v[32:35], v[232:235], v[166:169], v[32:35]
	v_mfma_f32_16x16x32_bf16 v[20:23], v[210:213], v[188:191], v[20:23]
	v_mfma_f32_16x16x32_bf16 v[16:19], v[232:235], v[188:191], v[16:19]
	v_mfma_f32_16x16x32_bf16 v[4:7], v[210:213], v[202:205], v[4:7]
	v_mfma_f32_16x16x32_bf16 v[0:3], v[232:235], v[202:205], v[0:3]
	s_setprio 0
	s_add_i32 s28, 0, 0x18000
	v_add_u32_e32 v140, s28, v195
	s_barrier
	ds_read_b128 v[128:131], v140
	ds_read_b128 v[132:135], v140 offset:1024
	ds_read_b128 v[136:139], v140 offset:2048
	ds_read_b128 v[140:143], v140 offset:3072
	s_add_u32 s60, s60, s4
	s_addc_u32 s61, s61, 0
	s_mov_b32 m0, s68
	v_lshl_add_u64 v[206:207], s[60:61], 0, v[152:153]
	ds_read_b128 v[144:147], v196 offset:32768
	ds_read_b128 v[162:165], v196 offset:34816
	ds_read_b128 v[170:173], v196 offset:36864
	ds_read_b128 v[198:201], v196 offset:38912
	ds_read_b128 v[148:151], v196 offset:33792
	ds_read_b128 v[166:169], v196 offset:35840
	ds_read_b128 v[188:191], v196 offset:37888
	ds_read_b128 v[202:205], v196 offset:39936
	global_load_lds_dwordx4 v[206:207], off
	v_lshl_add_u64 v[206:207], s[60:61], 0, v[154:155]
	s_mov_b32 m0, s69
	s_nop 0
	global_load_lds_dwordx4 v[206:207], off
	s_waitcnt lgkmcnt(8)
	s_barrier
	s_setprio 1
	s_waitcnt lgkmcnt(7)
	v_mfma_f32_16x16x32_bf16 v[124:127], v[128:131], v[144:147], v[124:127]
	v_mfma_f32_16x16x32_bf16 v[120:123], v[136:139], v[144:147], v[120:123]
	s_waitcnt lgkmcnt(6)
	v_mfma_f32_16x16x32_bf16 v[108:111], v[128:131], v[162:165], v[108:111]
	v_mfma_f32_16x16x32_bf16 v[104:107], v[136:139], v[162:165], v[104:107]
	s_waitcnt lgkmcnt(5)
	v_mfma_f32_16x16x32_bf16 v[92:95], v[128:131], v[170:173], v[92:95]
	v_mfma_f32_16x16x32_bf16 v[88:91], v[136:139], v[170:173], v[88:91]
	s_waitcnt lgkmcnt(4)
	v_mfma_f32_16x16x32_bf16 v[76:79], v[128:131], v[198:201], v[76:79]
	v_mfma_f32_16x16x32_bf16 v[72:75], v[136:139], v[198:201], v[72:75]
	s_waitcnt lgkmcnt(3)
	v_mfma_f32_16x16x32_bf16 v[124:127], v[132:135], v[148:151], v[124:127]
	v_mfma_f32_16x16x32_bf16 v[120:123], v[140:143], v[148:151], v[120:123]
	s_waitcnt lgkmcnt(2)
	v_mfma_f32_16x16x32_bf16 v[108:111], v[132:135], v[166:169], v[108:111]
	v_mfma_f32_16x16x32_bf16 v[104:107], v[140:143], v[166:169], v[104:107]
	s_waitcnt lgkmcnt(1)
	v_mfma_f32_16x16x32_bf16 v[92:95], v[132:135], v[188:191], v[92:95]
	v_mfma_f32_16x16x32_bf16 v[88:91], v[140:143], v[188:191], v[88:91]
	s_waitcnt lgkmcnt(0)
	v_mfma_f32_16x16x32_bf16 v[76:79], v[132:135], v[202:205], v[76:79]
	v_mfma_f32_16x16x32_bf16 v[72:75], v[140:143], v[202:205], v[72:75]
	s_setprio 0
	s_barrier
	s_add_i32 s29, 0, 0x1c000
	s_add_i32 s28, s28, s65
	v_add_u32_e32 v197, s29, v195
	v_lshl_add_u64 v[174:175], v[174:175], 0, s[40:41]
	s_mov_b32 m0, s28
	ds_read_b128 v[206:209], v197
	ds_read_b128 v[210:213], v197 offset:1024
	ds_read_b128 v[214:217], v197 offset:2048
	ds_read_b128 v[232:235], v197 offset:3072
	global_load_lds_dwordx4 v[174:175], off
	v_lshl_add_u64 v[174:175], v[236:237], 0, s[40:41]
	s_add_i32 m0, s28, 0x2000
	s_nop 0
	global_load_lds_dwordx4 v[174:175], off
	s_barrier
	s_setprio 1
	s_waitcnt lgkmcnt(3)
	v_mfma_f32_16x16x32_bf16 v[116:119], v[206:209], v[144:147], v[116:119]
	s_waitcnt lgkmcnt(1)
	v_mfma_f32_16x16x32_bf16 v[112:115], v[214:217], v[144:147], v[112:115]
	v_mfma_f32_16x16x32_bf16 v[100:103], v[206:209], v[162:165], v[100:103]
	v_mfma_f32_16x16x32_bf16 v[96:99], v[214:217], v[162:165], v[96:99]
	v_mfma_f32_16x16x32_bf16 v[84:87], v[206:209], v[170:173], v[84:87]
	v_mfma_f32_16x16x32_bf16 v[80:83], v[214:217], v[170:173], v[80:83]
	v_mfma_f32_16x16x32_bf16 v[68:71], v[206:209], v[198:201], v[68:71]
	v_mfma_f32_16x16x32_bf16 v[64:67], v[214:217], v[198:201], v[64:67]
	v_mfma_f32_16x16x32_bf16 v[116:119], v[210:213], v[148:151], v[116:119]
	s_waitcnt lgkmcnt(0)
	v_mfma_f32_16x16x32_bf16 v[112:115], v[232:235], v[148:151], v[112:115]
	v_mfma_f32_16x16x32_bf16 v[100:103], v[210:213], v[166:169], v[100:103]
	v_mfma_f32_16x16x32_bf16 v[96:99], v[232:235], v[166:169], v[96:99]
	v_mfma_f32_16x16x32_bf16 v[84:87], v[210:213], v[188:191], v[84:87]
	v_mfma_f32_16x16x32_bf16 v[80:83], v[232:235], v[188:191], v[80:83]
	v_mfma_f32_16x16x32_bf16 v[68:71], v[210:213], v[202:205], v[68:71]
	v_mfma_f32_16x16x32_bf16 v[64:67], v[232:235], v[202:205], v[64:67]
	s_setprio 0
	s_mov_b32 m0, s71
	v_lshl_add_u64 v[174:175], v[238:239], 0, s[40:41]
	s_barrier
	ds_read_b128 v[144:147], v196 offset:49152
	ds_read_b128 v[162:165], v196 offset:51200
	ds_read_b128 v[170:173], v196 offset:53248
	ds_read_b128 v[198:201], v196 offset:55296
	ds_read_b128 v[148:151], v196 offset:50176
	ds_read_b128 v[166:169], v196 offset:52224
	ds_read_b128 v[188:191], v196 offset:54272
	ds_read_b128 v[202:205], v196 offset:56320
	global_load_lds_dwordx4 v[174:175], off
	v_lshl_add_u64 v[174:175], v[240:241], 0, s[40:41]
	s_mov_b32 m0, s72
	s_nop 0
	global_load_lds_dwordx4 v[174:175], off
	s_barrier
	s_setprio 1
	s_waitcnt lgkmcnt(7)
	v_mfma_f32_16x16x32_bf16 v[60:63], v[128:131], v[144:147], v[60:63]
	v_mfma_f32_16x16x32_bf16 v[56:59], v[136:139], v[144:147], v[56:59]
	s_waitcnt lgkmcnt(6)
	v_mfma_f32_16x16x32_bf16 v[44:47], v[128:131], v[162:165], v[44:47]
	v_mfma_f32_16x16x32_bf16 v[40:43], v[136:139], v[162:165], v[40:43]
	s_waitcnt lgkmcnt(5)
	v_mfma_f32_16x16x32_bf16 v[28:31], v[128:131], v[170:173], v[28:31]
	v_mfma_f32_16x16x32_bf16 v[24:27], v[136:139], v[170:173], v[24:27]
	s_waitcnt lgkmcnt(4)
	v_mfma_f32_16x16x32_bf16 v[12:15], v[128:131], v[198:201], v[12:15]
	v_mfma_f32_16x16x32_bf16 v[8:11], v[136:139], v[198:201], v[8:11]
	s_waitcnt lgkmcnt(3)
	v_mfma_f32_16x16x32_bf16 v[60:63], v[132:135], v[148:151], v[60:63]
	v_mfma_f32_16x16x32_bf16 v[56:59], v[140:143], v[148:151], v[56:59]
	s_waitcnt lgkmcnt(2)
	v_mfma_f32_16x16x32_bf16 v[44:47], v[132:135], v[166:169], v[44:47]
	v_mfma_f32_16x16x32_bf16 v[40:43], v[140:143], v[166:169], v[40:43]
	s_waitcnt lgkmcnt(1)
	v_mfma_f32_16x16x32_bf16 v[28:31], v[132:135], v[188:191], v[28:31]
	v_mfma_f32_16x16x32_bf16 v[24:27], v[140:143], v[188:191], v[24:27]
	s_waitcnt lgkmcnt(0)
	v_mfma_f32_16x16x32_bf16 v[12:15], v[132:135], v[202:205], v[12:15]
	v_mfma_f32_16x16x32_bf16 v[8:11], v[140:143], v[202:205], v[8:11]
	s_setprio 0
	s_barrier
	s_add_i32 s28, s29, s65
	v_lshl_add_u64 v[128:129], v[242:243], 0, s[40:41]
	s_mov_b32 m0, s28
	s_nop 0
	global_load_lds_dwordx4 v[128:129], off
	v_lshl_add_u64 v[128:129], v[244:245], 0, s[40:41]
	s_add_i32 m0, s28, 0x2000
	s_nop 0
	global_load_lds_dwordx4 v[128:129], off
	s_waitcnt vmcnt(6)
	s_barrier
	s_setprio 1
	v_mfma_f32_16x16x32_bf16 v[52:55], v[206:209], v[144:147], v[52:55]
	v_mfma_f32_16x16x32_bf16 v[48:51], v[214:217], v[144:147], v[48:51]
	v_mfma_f32_16x16x32_bf16 v[36:39], v[206:209], v[162:165], v[36:39]
	v_mfma_f32_16x16x32_bf16 v[32:35], v[214:217], v[162:165], v[32:35]
	v_mfma_f32_16x16x32_bf16 v[20:23], v[206:209], v[170:173], v[20:23]
	v_mfma_f32_16x16x32_bf16 v[16:19], v[214:217], v[170:173], v[16:19]
	v_mfma_f32_16x16x32_bf16 v[4:7], v[206:209], v[198:201], v[4:7]
	v_mfma_f32_16x16x32_bf16 v[0:3], v[214:217], v[198:201], v[0:3]
	v_mfma_f32_16x16x32_bf16 v[52:55], v[210:213], v[148:151], v[52:55]
	v_mfma_f32_16x16x32_bf16 v[48:51], v[232:235], v[148:151], v[48:51]
	v_mfma_f32_16x16x32_bf16 v[36:39], v[210:213], v[166:169], v[36:39]
	v_mfma_f32_16x16x32_bf16 v[32:35], v[232:235], v[166:169], v[32:35]
	v_mfma_f32_16x16x32_bf16 v[20:23], v[210:213], v[188:191], v[20:23]
	v_mfma_f32_16x16x32_bf16 v[16:19], v[232:235], v[188:191], v[16:19]
	v_mfma_f32_16x16x32_bf16 v[4:7], v[210:213], v[202:205], v[4:7]
	v_mfma_f32_16x16x32_bf16 v[0:3], v[232:235], v[202:205], v[0:3]
	s_setprio 0
	s_add_u32 s58, s58, 0x100
	s_addc_u32 s59, s59, 0
	s_add_u32 s21, s21, 0x100
	s_addc_u32 s80, s80, 0
	s_cmp_ge_i32 s81, s79
	s_mov_b32 s60, s81
	s_barrier
	s_cbranch_scc0 .LBB0_1282
	s_cmp_gt_i32 s24, -1
	s_mov_b64 s[58:59], -1
	s_cbranch_scc0 .LBB0_1285
	s_lshl_b64 s[58:59], s[24:25], 17
	v_mov_b32_e32 v128, v231
	s_add_u32 s58, s37, s58
	s_addc_u32 s59, s46, s59
	v_ashrrev_i32_e32 v129, 31, v128
	v_lshl_add_u64 v[128:129], v[128:129], 4, s[58:59]
	v_add_co_u32_e32 v134, vcc, s36, v128
	v_cvt_pk_bf16_f32 v130, v124, v125
	v_cvt_pk_bf16_f32 v131, v126, v127
	v_cvt_pk_bf16_f32 v132, v120, v121
	v_cvt_pk_bf16_f32 v133, v122, v123
	s_nop 1
	v_addc_co_u32_e32 v135, vcc, 0, v129, vcc
	s_movk_i32 s5, 0x4000
	global_store_dwordx4 v[128:129], v[130:133], off
	s_mov_b64 s[58:59], 0
	s_nop 0
	v_cvt_pk_bf16_f32 v130, v108, v109
	v_cvt_pk_bf16_f32 v131, v110, v111
	v_cvt_pk_bf16_f32 v132, v104, v105
	v_cvt_pk_bf16_f32 v133, v106, v107
	global_store_dwordx4 v[134:135], v[130:133], off
	v_add_co_u32_e32 v134, vcc, s5, v128
	s_movk_i32 s5, 0x6000
	s_nop 0
	v_addc_co_u32_e32 v135, vcc, 0, v129, vcc
	v_cvt_pk_bf16_f32 v130, v92, v93
	v_cvt_pk_bf16_f32 v131, v94, v95
	v_cvt_pk_bf16_f32 v132, v88, v89
	v_cvt_pk_bf16_f32 v133, v90, v91
	global_store_dwordx4 v[134:135], v[130:133], off
	v_add_co_u32_e32 v134, vcc, s5, v128
	s_nop 0
	v_cvt_pk_bf16_f32 v130, v76, v77
	v_cvt_pk_bf16_f32 v131, v78, v79
	v_cvt_pk_bf16_f32 v132, v72, v73
	v_cvt_pk_bf16_f32 v133, v74, v75
	s_nop 0
	v_addc_co_u32_e32 v135, vcc, 0, v129, vcc
	global_store_dwordx4 v[134:135], v[130:133], off
	v_add_co_u32_e32 v134, vcc, s92, v128
	s_mov_b32 s5, 0xa000
	s_nop 0
	v_addc_co_u32_e32 v135, vcc, 0, v129, vcc
	v_cvt_pk_bf16_f32 v130, v116, v117
	v_cvt_pk_bf16_f32 v131, v118, v119
	v_cvt_pk_bf16_f32 v132, v112, v113
	v_cvt_pk_bf16_f32 v133, v114, v115
	global_store_dwordx4 v[134:135], v[130:133], off
	v_add_co_u32_e32 v134, vcc, s5, v128
	s_mov_b32 s5, 0xc000
	s_nop 0
	v_addc_co_u32_e32 v135, vcc, 0, v129, vcc
	v_cvt_pk_bf16_f32 v130, v100, v101
	v_cvt_pk_bf16_f32 v131, v102, v103
	v_cvt_pk_bf16_f32 v132, v96, v97
	v_cvt_pk_bf16_f32 v133, v98, v99
	global_store_dwordx4 v[134:135], v[130:133], off
	v_add_co_u32_e32 v134, vcc, s5, v128
	s_mov_b32 s5, 0xe000
	s_nop 0
	v_addc_co_u32_e32 v135, vcc, 0, v129, vcc
	v_cvt_pk_bf16_f32 v130, v84, v85
	v_cvt_pk_bf16_f32 v131, v86, v87
	v_cvt_pk_bf16_f32 v132, v80, v81
	v_cvt_pk_bf16_f32 v133, v82, v83
	global_store_dwordx4 v[134:135], v[130:133], off
	v_add_co_u32_e32 v134, vcc, s5, v128
	s_mov_b32 s5, 0x10000
	s_nop 0
	v_addc_co_u32_e32 v135, vcc, 0, v129, vcc
	v_cvt_pk_bf16_f32 v130, v68, v69
	v_cvt_pk_bf16_f32 v131, v70, v71
	v_cvt_pk_bf16_f32 v132, v64, v65
	v_cvt_pk_bf16_f32 v133, v66, v67
	global_store_dwordx4 v[134:135], v[130:133], off
	v_add_co_u32_e32 v134, vcc, s5, v128
	s_mov_b32 s5, 0x12000
	s_nop 0
	v_addc_co_u32_e32 v135, vcc, 0, v129, vcc
	v_cvt_pk_bf16_f32 v130, v60, v61
	v_cvt_pk_bf16_f32 v131, v62, v63
	v_cvt_pk_bf16_f32 v132, v56, v57
	v_cvt_pk_bf16_f32 v133, v58, v59
	global_store_dwordx4 v[134:135], v[130:133], off
	v_add_co_u32_e32 v134, vcc, s5, v128
	s_mov_b32 s5, 0x14000
	s_nop 0
	v_addc_co_u32_e32 v135, vcc, 0, v129, vcc
	v_cvt_pk_bf16_f32 v130, v44, v45
	v_cvt_pk_bf16_f32 v131, v46, v47
	v_cvt_pk_bf16_f32 v132, v40, v41
	v_cvt_pk_bf16_f32 v133, v42, v43
	global_store_dwordx4 v[134:135], v[130:133], off
	v_add_co_u32_e32 v134, vcc, s5, v128
	s_mov_b32 s5, 0x16000
	s_nop 0
	v_addc_co_u32_e32 v135, vcc, 0, v129, vcc
	v_cvt_pk_bf16_f32 v130, v28, v29
	v_cvt_pk_bf16_f32 v131, v30, v31
	v_cvt_pk_bf16_f32 v132, v24, v25
	v_cvt_pk_bf16_f32 v133, v26, v27
	global_store_dwordx4 v[134:135], v[130:133], off
	v_add_co_u32_e32 v134, vcc, s5, v128
	s_mov_b32 s5, 0x18000
	s_nop 0
	v_addc_co_u32_e32 v135, vcc, 0, v129, vcc
	v_cvt_pk_bf16_f32 v130, v12, v13
	v_cvt_pk_bf16_f32 v131, v14, v15
	v_cvt_pk_bf16_f32 v132, v8, v9
	v_cvt_pk_bf16_f32 v133, v10, v11
	global_store_dwordx4 v[134:135], v[130:133], off
	v_add_co_u32_e32 v134, vcc, s5, v128
	s_mov_b32 s5, 0x1a000
	s_nop 0
	v_addc_co_u32_e32 v135, vcc, 0, v129, vcc
	v_cvt_pk_bf16_f32 v130, v52, v53
	v_cvt_pk_bf16_f32 v131, v54, v55
	v_cvt_pk_bf16_f32 v132, v48, v49
	v_cvt_pk_bf16_f32 v133, v50, v51
	global_store_dwordx4 v[134:135], v[130:133], off
	v_add_co_u32_e32 v134, vcc, s5, v128
	s_mov_b32 s5, 0x1c000
	s_nop 0
	v_addc_co_u32_e32 v135, vcc, 0, v129, vcc
	v_cvt_pk_bf16_f32 v130, v36, v37
	v_cvt_pk_bf16_f32 v131, v38, v39
	v_cvt_pk_bf16_f32 v132, v32, v33
	v_cvt_pk_bf16_f32 v133, v34, v35
	global_store_dwordx4 v[134:135], v[130:133], off
	v_add_co_u32_e32 v134, vcc, s5, v128
	s_nop 0
	v_cvt_pk_bf16_f32 v130, v20, v21
	v_cvt_pk_bf16_f32 v131, v22, v23
	v_cvt_pk_bf16_f32 v132, v16, v17
	v_cvt_pk_bf16_f32 v133, v18, v19
	s_nop 0
	v_addc_co_u32_e32 v135, vcc, 0, v129, vcc
	v_add_co_u32_e32 v128, vcc, 0x1e000, v128
	global_store_dwordx4 v[134:135], v[130:133], off
	s_nop 0
	v_addc_co_u32_e32 v129, vcc, 0, v129, vcc
	v_cvt_pk_bf16_f32 v130, v4, v5
	v_cvt_pk_bf16_f32 v131, v6, v7
	v_cvt_pk_bf16_f32 v132, v0, v1
	v_cvt_pk_bf16_f32 v133, v2, v3
	global_store_dwordx4 v[128:129], v[130:133], off

.LBB0_1436:
	s_add_u32 s28, s6, 0xfffc0080
	s_addc_u32 s29, s7, -1
	s_add_i32 s71, 0, 0x10000
	v_add_u32_e32 v140, s71, v200
	ds_read_b128 v[128:131], v140
	ds_read_b128 v[132:135], v140 offset:1024
	ds_read_b128 v[136:139], v140 offset:2048
	ds_read_b128 v[140:143], v140 offset:3072
	s_cmp_eq_u32 s70, 12
	s_cselect_b32 s53, s17, s29
	s_cselect_b32 s52, s66, s28
	s_cselect_b32 s51, s13, s69
	s_cselect_b32 s50, s67, s68
	v_lshl_add_u64 v[174:175], s[6:7], 0, v[162:163]
	s_add_i32 m0, s56, 0xc000
	ds_read_b128 v[144:147], v201
	ds_read_b128 v[152:155], v201 offset:2048
	ds_read_b128 v[170:173], v201 offset:4096
	ds_read_b128 v[192:195], v201 offset:6144
	ds_read_b128 v[148:151], v201 offset:1024
	ds_read_b128 v[166:169], v201 offset:3072
	ds_read_b128 v[188:191], v201 offset:5120
	ds_read_b128 v[202:205], v201 offset:7168
	global_load_lds_dwordx4 v[174:175], off
	v_lshl_add_u64 v[174:175], s[6:7], 0, v[164:165]
	s_add_i32 m0, s56, 0xe000
	s_nop 0
	global_load_lds_dwordx4 v[174:175], off
	s_waitcnt lgkmcnt(8)
	s_barrier
	s_setprio 1
	s_waitcnt lgkmcnt(7)
	v_mfma_f32_16x16x32_bf16 v[124:127], v[128:131], v[144:147], v[124:127]
	v_mfma_f32_16x16x32_bf16 v[116:119], v[136:139], v[144:147], v[116:119]
	s_waitcnt lgkmcnt(6)
	v_mfma_f32_16x16x32_bf16 v[108:111], v[128:131], v[152:155], v[108:111]
	v_mfma_f32_16x16x32_bf16 v[100:103], v[136:139], v[152:155], v[100:103]
	s_waitcnt lgkmcnt(5)
	v_mfma_f32_16x16x32_bf16 v[92:95], v[128:131], v[170:173], v[92:95]
	v_mfma_f32_16x16x32_bf16 v[84:87], v[136:139], v[170:173], v[84:87]
	s_waitcnt lgkmcnt(4)
	v_mfma_f32_16x16x32_bf16 v[76:79], v[128:131], v[192:195], v[76:79]
	v_mfma_f32_16x16x32_bf16 v[68:71], v[136:139], v[192:195], v[68:71]
	s_waitcnt lgkmcnt(3)
	v_mfma_f32_16x16x32_bf16 v[124:127], v[132:135], v[148:151], v[124:127]
	v_mfma_f32_16x16x32_bf16 v[116:119], v[140:143], v[148:151], v[116:119]
	s_waitcnt lgkmcnt(2)
	v_mfma_f32_16x16x32_bf16 v[108:111], v[132:135], v[166:169], v[108:111]
	v_mfma_f32_16x16x32_bf16 v[100:103], v[140:143], v[166:169], v[100:103]
	s_waitcnt lgkmcnt(1)
	v_mfma_f32_16x16x32_bf16 v[92:95], v[132:135], v[188:191], v[92:95]
	v_mfma_f32_16x16x32_bf16 v[84:87], v[140:143], v[188:191], v[84:87]
	s_waitcnt lgkmcnt(0)
	v_mfma_f32_16x16x32_bf16 v[76:79], v[132:135], v[202:205], v[76:79]
	v_mfma_f32_16x16x32_bf16 v[68:71], v[140:143], v[202:205], v[68:71]
	s_setprio 0
	s_barrier
	s_add_i32 s28, 0, 0x14000
	v_add_u32_e32 v174, s28, v200
	s_add_i32 s29, s71, s55
	ds_read_b128 v[206:209], v174
	ds_read_b128 v[210:213], v174 offset:1024
	ds_read_b128 v[214:217], v174 offset:2048
	ds_read_b128 v[232:235], v174 offset:3072
	v_lshl_add_u64 v[174:175], s[50:51], 0, v[176:177]
	s_mov_b32 m0, s29
	v_lshl_add_u64 v[196:197], s[50:51], 0, v[160:161]
	global_load_lds_dwordx4 v[174:175], off
	s_add_i32 m0, s29, 0x2000
	s_nop 0
	global_load_lds_dwordx4 v[196:197], off
	s_barrier
	s_setprio 1
	s_waitcnt lgkmcnt(3)
	v_mfma_f32_16x16x32_bf16 v[120:123], v[206:209], v[144:147], v[120:123]
	s_waitcnt lgkmcnt(1)
	v_mfma_f32_16x16x32_bf16 v[112:115], v[214:217], v[144:147], v[112:115]
	v_mfma_f32_16x16x32_bf16 v[104:107], v[206:209], v[152:155], v[104:107]
	v_mfma_f32_16x16x32_bf16 v[96:99], v[214:217], v[152:155], v[96:99]
	v_mfma_f32_16x16x32_bf16 v[88:91], v[206:209], v[170:173], v[88:91]
	v_mfma_f32_16x16x32_bf16 v[80:83], v[214:217], v[170:173], v[80:83]
	v_mfma_f32_16x16x32_bf16 v[72:75], v[206:209], v[192:195], v[72:75]
	v_mfma_f32_16x16x32_bf16 v[64:67], v[214:217], v[192:195], v[64:67]
	v_mfma_f32_16x16x32_bf16 v[120:123], v[210:213], v[148:151], v[120:123]
	s_waitcnt lgkmcnt(0)
	v_mfma_f32_16x16x32_bf16 v[112:115], v[232:235], v[148:151], v[112:115]
	v_mfma_f32_16x16x32_bf16 v[104:107], v[210:213], v[166:169], v[104:107]
	v_mfma_f32_16x16x32_bf16 v[96:99], v[232:235], v[166:169], v[96:99]
	v_mfma_f32_16x16x32_bf16 v[88:91], v[210:213], v[188:191], v[88:91]
	v_mfma_f32_16x16x32_bf16 v[80:83], v[232:235], v[188:191], v[80:83]
	v_mfma_f32_16x16x32_bf16 v[72:75], v[210:213], v[202:205], v[72:75]
	v_mfma_f32_16x16x32_bf16 v[64:67], v[232:235], v[202:205], v[64:67]
	s_setprio 0
	s_mov_b32 m0, s56
	v_lshl_add_u64 v[236:237], s[52:53], 0, v[156:157]
	s_barrier
	ds_read_b128 v[144:147], v201 offset:16384
	ds_read_b128 v[152:155], v201 offset:18432
	ds_read_b128 v[170:173], v201 offset:20480
	ds_read_b128 v[192:195], v201 offset:22528
	ds_read_b128 v[148:151], v201 offset:17408
	ds_read_b128 v[166:169], v201 offset:19456
	ds_read_b128 v[188:191], v201 offset:21504
	ds_read_b128 v[202:205], v201 offset:23552
	global_load_lds_dwordx4 v[236:237], off
	v_lshl_add_u64 v[238:239], s[52:53], 0, v[158:159]
	s_mov_b32 m0, s57
	s_nop 0
	global_load_lds_dwordx4 v[238:239], off
	s_barrier
	s_setprio 1
	s_waitcnt lgkmcnt(7)
	v_mfma_f32_16x16x32_bf16 v[60:63], v[128:131], v[144:147], v[60:63]
	v_mfma_f32_16x16x32_bf16 v[52:55], v[136:139], v[144:147], v[52:55]
	s_waitcnt lgkmcnt(6)
	v_mfma_f32_16x16x32_bf16 v[44:47], v[128:131], v[152:155], v[44:47]
	v_mfma_f32_16x16x32_bf16 v[36:39], v[136:139], v[152:155], v[36:39]
	s_waitcnt lgkmcnt(5)
	v_mfma_f32_16x16x32_bf16 v[28:31], v[128:131], v[170:173], v[28:31]
	v_mfma_f32_16x16x32_bf16 v[20:23], v[136:139], v[170:173], v[20:23]
	s_waitcnt lgkmcnt(4)
	v_mfma_f32_16x16x32_bf16 v[12:15], v[128:131], v[192:195], v[12:15]
	v_mfma_f32_16x16x32_bf16 v[4:7], v[136:139], v[192:195], v[4:7]
	s_waitcnt lgkmcnt(3)
	v_mfma_f32_16x16x32_bf16 v[60:63], v[132:135], v[148:151], v[60:63]
	v_mfma_f32_16x16x32_bf16 v[52:55], v[140:143], v[148:151], v[52:55]
	s_waitcnt lgkmcnt(2)
	v_mfma_f32_16x16x32_bf16 v[44:47], v[132:135], v[166:169], v[44:47]
	v_mfma_f32_16x16x32_bf16 v[36:39], v[140:143], v[166:169], v[36:39]
	s_waitcnt lgkmcnt(1)
	v_mfma_f32_16x16x32_bf16 v[28:31], v[132:135], v[188:191], v[28:31]
	v_mfma_f32_16x16x32_bf16 v[20:23], v[140:143], v[188:191], v[20:23]
	s_waitcnt lgkmcnt(0)
	v_mfma_f32_16x16x32_bf16 v[12:15], v[132:135], v[202:205], v[12:15]
	v_mfma_f32_16x16x32_bf16 v[4:7], v[140:143], v[202:205], v[4:7]
	s_setprio 0
	s_barrier
	s_add_u32 s72, s50, 0x40000
	s_addc_u32 s73, s51, 0
	s_add_i32 s28, s28, s55
	v_lshl_add_u64 v[128:129], s[72:73], 0, v[176:177]
	s_mov_b32 m0, s28
	s_nop 0
	global_load_lds_dwordx4 v[128:129], off
	v_lshl_add_u64 v[128:129], s[72:73], 0, v[160:161]
	s_add_i32 m0, s28, 0x2000
	s_nop 0
	global_load_lds_dwordx4 v[128:129], off
	s_waitcnt vmcnt(6)
	s_barrier
	s_setprio 1
	v_mfma_f32_16x16x32_bf16 v[56:59], v[206:209], v[144:147], v[56:59]
	v_mfma_f32_16x16x32_bf16 v[48:51], v[214:217], v[144:147], v[48:51]
	v_mfma_f32_16x16x32_bf16 v[40:43], v[206:209], v[152:155], v[40:43]
	v_mfma_f32_16x16x32_bf16 v[32:35], v[214:217], v[152:155], v[32:35]
	v_mfma_f32_16x16x32_bf16 v[24:27], v[206:209], v[170:173], v[24:27]
	v_mfma_f32_16x16x32_bf16 v[16:19], v[214:217], v[170:173], v[16:19]
	v_mfma_f32_16x16x32_bf16 v[8:11], v[206:209], v[192:195], v[8:11]
	v_mfma_f32_16x16x32_bf16 v[0:3], v[214:217], v[192:195], v[0:3]
	v_mfma_f32_16x16x32_bf16 v[56:59], v[210:213], v[148:151], v[56:59]
	v_mfma_f32_16x16x32_bf16 v[48:51], v[232:235], v[148:151], v[48:51]
	v_mfma_f32_16x16x32_bf16 v[40:43], v[210:213], v[166:169], v[40:43]
	v_mfma_f32_16x16x32_bf16 v[32:35], v[232:235], v[166:169], v[32:35]
	v_mfma_f32_16x16x32_bf16 v[24:27], v[210:213], v[188:191], v[24:27]
	v_mfma_f32_16x16x32_bf16 v[16:19], v[232:235], v[188:191], v[16:19]
	v_mfma_f32_16x16x32_bf16 v[8:11], v[210:213], v[202:205], v[8:11]
	v_mfma_f32_16x16x32_bf16 v[0:3], v[232:235], v[202:205], v[0:3]
	s_setprio 0
	s_add_i32 s28, 0, 0x18000
	v_add_u32_e32 v140, s28, v200
	s_barrier
	ds_read_b128 v[128:131], v140
	ds_read_b128 v[132:135], v140 offset:1024
	ds_read_b128 v[136:139], v140 offset:2048
	ds_read_b128 v[140:143], v140 offset:3072
	s_add_u32 s52, s52, 0x40000
	s_addc_u32 s53, s53, 0
	s_mov_b32 m0, s58
	v_lshl_add_u64 v[206:207], s[52:53], 0, v[156:157]
	ds_read_b128 v[144:147], v201 offset:32768
	ds_read_b128 v[152:155], v201 offset:34816
	ds_read_b128 v[170:173], v201 offset:36864
	ds_read_b128 v[192:195], v201 offset:38912
	ds_read_b128 v[148:151], v201 offset:33792
	ds_read_b128 v[166:169], v201 offset:35840
	ds_read_b128 v[188:191], v201 offset:37888
	ds_read_b128 v[202:205], v201 offset:39936
	global_load_lds_dwordx4 v[206:207], off
	v_lshl_add_u64 v[206:207], s[52:53], 0, v[158:159]
	s_mov_b32 m0, s59
	s_nop 0
	global_load_lds_dwordx4 v[206:207], off
	s_waitcnt lgkmcnt(8)
	s_barrier
	s_setprio 1
	s_waitcnt lgkmcnt(7)
	v_mfma_f32_16x16x32_bf16 v[124:127], v[128:131], v[144:147], v[124:127]
	v_mfma_f32_16x16x32_bf16 v[116:119], v[136:139], v[144:147], v[116:119]
	s_waitcnt lgkmcnt(6)
	v_mfma_f32_16x16x32_bf16 v[108:111], v[128:131], v[152:155], v[108:111]
	v_mfma_f32_16x16x32_bf16 v[100:103], v[136:139], v[152:155], v[100:103]
	s_waitcnt lgkmcnt(5)
	v_mfma_f32_16x16x32_bf16 v[92:95], v[128:131], v[170:173], v[92:95]
	v_mfma_f32_16x16x32_bf16 v[84:87], v[136:139], v[170:173], v[84:87]
	s_waitcnt lgkmcnt(4)
	v_mfma_f32_16x16x32_bf16 v[76:79], v[128:131], v[192:195], v[76:79]
	v_mfma_f32_16x16x32_bf16 v[68:71], v[136:139], v[192:195], v[68:71]
	s_waitcnt lgkmcnt(3)
	v_mfma_f32_16x16x32_bf16 v[124:127], v[132:135], v[148:151], v[124:127]
	v_mfma_f32_16x16x32_bf16 v[116:119], v[140:143], v[148:151], v[116:119]
	s_waitcnt lgkmcnt(2)
	v_mfma_f32_16x16x32_bf16 v[108:111], v[132:135], v[166:169], v[108:111]
	v_mfma_f32_16x16x32_bf16 v[100:103], v[140:143], v[166:169], v[100:103]
	s_waitcnt lgkmcnt(1)
	v_mfma_f32_16x16x32_bf16 v[92:95], v[132:135], v[188:191], v[92:95]
	v_mfma_f32_16x16x32_bf16 v[84:87], v[140:143], v[188:191], v[84:87]
	s_waitcnt lgkmcnt(0)
	v_mfma_f32_16x16x32_bf16 v[76:79], v[132:135], v[202:205], v[76:79]
	v_mfma_f32_16x16x32_bf16 v[68:71], v[140:143], v[202:205], v[68:71]
	s_setprio 0
	s_barrier
	s_add_i32 s29, 0, 0x1c000
	s_add_i32 s28, s28, s55
	v_add_u32_e32 v232, s29, v200
	v_lshl_add_u64 v[174:175], v[174:175], 0, s[40:41]
	s_mov_b32 m0, s28
	ds_read_b128 v[206:209], v232
	ds_read_b128 v[210:213], v232 offset:1024
	ds_read_b128 v[214:217], v232 offset:2048
	ds_read_b128 v[232:235], v232 offset:3072
	global_load_lds_dwordx4 v[174:175], off
	v_lshl_add_u64 v[174:175], v[196:197], 0, s[40:41]
	s_add_i32 m0, s28, 0x2000
	s_nop 0
	global_load_lds_dwordx4 v[174:175], off
	s_barrier
	s_setprio 1
	s_waitcnt lgkmcnt(3)
	v_mfma_f32_16x16x32_bf16 v[120:123], v[206:209], v[144:147], v[120:123]
	s_waitcnt lgkmcnt(1)
	v_mfma_f32_16x16x32_bf16 v[112:115], v[214:217], v[144:147], v[112:115]
	v_mfma_f32_16x16x32_bf16 v[104:107], v[206:209], v[152:155], v[104:107]
	v_mfma_f32_16x16x32_bf16 v[96:99], v[214:217], v[152:155], v[96:99]
	v_mfma_f32_16x16x32_bf16 v[88:91], v[206:209], v[170:173], v[88:91]
	v_mfma_f32_16x16x32_bf16 v[80:83], v[214:217], v[170:173], v[80:83]
	v_mfma_f32_16x16x32_bf16 v[72:75], v[206:209], v[192:195], v[72:75]
	v_mfma_f32_16x16x32_bf16 v[64:67], v[214:217], v[192:195], v[64:67]
	v_mfma_f32_16x16x32_bf16 v[120:123], v[210:213], v[148:151], v[120:123]
	s_waitcnt lgkmcnt(0)
	v_mfma_f32_16x16x32_bf16 v[112:115], v[232:235], v[148:151], v[112:115]
	v_mfma_f32_16x16x32_bf16 v[104:107], v[210:213], v[166:169], v[104:107]
	v_mfma_f32_16x16x32_bf16 v[96:99], v[232:235], v[166:169], v[96:99]
	v_mfma_f32_16x16x32_bf16 v[88:91], v[210:213], v[188:191], v[88:91]
	v_mfma_f32_16x16x32_bf16 v[80:83], v[232:235], v[188:191], v[80:83]
	v_mfma_f32_16x16x32_bf16 v[72:75], v[210:213], v[202:205], v[72:75]
	v_mfma_f32_16x16x32_bf16 v[64:67], v[232:235], v[202:205], v[64:67]
	s_setprio 0
	s_mov_b32 m0, s62
	v_lshl_add_u64 v[174:175], v[236:237], 0, s[40:41]
	s_barrier
	ds_read_b128 v[144:147], v201 offset:49152
	ds_read_b128 v[152:155], v201 offset:51200
	ds_read_b128 v[170:173], v201 offset:53248
	ds_read_b128 v[192:195], v201 offset:55296
	ds_read_b128 v[148:151], v201 offset:50176
	ds_read_b128 v[166:169], v201 offset:52224
	ds_read_b128 v[188:191], v201 offset:54272
	ds_read_b128 v[202:205], v201 offset:56320
	global_load_lds_dwordx4 v[174:175], off
	v_lshl_add_u64 v[174:175], v[238:239], 0, s[40:41]
	s_mov_b32 m0, s63
	s_nop 0
	global_load_lds_dwordx4 v[174:175], off
	s_barrier
	s_setprio 1
	s_waitcnt lgkmcnt(7)
	v_mfma_f32_16x16x32_bf16 v[60:63], v[128:131], v[144:147], v[60:63]
	v_mfma_f32_16x16x32_bf16 v[52:55], v[136:139], v[144:147], v[52:55]
	s_waitcnt lgkmcnt(6)
	v_mfma_f32_16x16x32_bf16 v[44:47], v[128:131], v[152:155], v[44:47]
	v_mfma_f32_16x16x32_bf16 v[36:39], v[136:139], v[152:155], v[36:39]
	s_waitcnt lgkmcnt(5)
	v_mfma_f32_16x16x32_bf16 v[28:31], v[128:131], v[170:173], v[28:31]
	v_mfma_f32_16x16x32_bf16 v[20:23], v[136:139], v[170:173], v[20:23]
	s_waitcnt lgkmcnt(4)
	v_mfma_f32_16x16x32_bf16 v[12:15], v[128:131], v[192:195], v[12:15]
	v_mfma_f32_16x16x32_bf16 v[4:7], v[136:139], v[192:195], v[4:7]
	s_waitcnt lgkmcnt(3)
	v_mfma_f32_16x16x32_bf16 v[60:63], v[132:135], v[148:151], v[60:63]
	v_mfma_f32_16x16x32_bf16 v[52:55], v[140:143], v[148:151], v[52:55]
	s_waitcnt lgkmcnt(2)
	v_mfma_f32_16x16x32_bf16 v[44:47], v[132:135], v[166:169], v[44:47]
	v_mfma_f32_16x16x32_bf16 v[36:39], v[140:143], v[166:169], v[36:39]
	s_waitcnt lgkmcnt(1)
	v_mfma_f32_16x16x32_bf16 v[28:31], v[132:135], v[188:191], v[28:31]
	v_mfma_f32_16x16x32_bf16 v[20:23], v[140:143], v[188:191], v[20:23]
	s_waitcnt lgkmcnt(0)
	v_mfma_f32_16x16x32_bf16 v[12:15], v[132:135], v[202:205], v[12:15]
	v_mfma_f32_16x16x32_bf16 v[4:7], v[140:143], v[202:205], v[4:7]
	s_setprio 0
	s_barrier
	s_add_u32 s50, s50, 0x40080
	s_addc_u32 s51, s51, 0
	s_add_i32 s28, s29, s55
	v_lshl_add_u64 v[128:129], s[50:51], 0, v[176:177]
	s_mov_b32 m0, s28
	s_nop 0
	global_load_lds_dwordx4 v[128:129], off
	v_lshl_add_u64 v[128:129], s[50:51], 0, v[160:161]
	s_add_i32 m0, s28, 0x2000
	s_nop 0
	global_load_lds_dwordx4 v[128:129], off
	s_waitcnt vmcnt(6)
	s_barrier
	s_setprio 1
	v_mfma_f32_16x16x32_bf16 v[56:59], v[206:209], v[144:147], v[56:59]
	v_mfma_f32_16x16x32_bf16 v[48:51], v[214:217], v[144:147], v[48:51]
	v_mfma_f32_16x16x32_bf16 v[40:43], v[206:209], v[152:155], v[40:43]
	v_mfma_f32_16x16x32_bf16 v[32:35], v[214:217], v[152:155], v[32:35]
	v_mfma_f32_16x16x32_bf16 v[24:27], v[206:209], v[170:173], v[24:27]
	v_mfma_f32_16x16x32_bf16 v[16:19], v[214:217], v[170:173], v[16:19]
	v_mfma_f32_16x16x32_bf16 v[8:11], v[206:209], v[192:195], v[8:11]
	v_mfma_f32_16x16x32_bf16 v[0:3], v[214:217], v[192:195], v[0:3]
	v_mfma_f32_16x16x32_bf16 v[56:59], v[210:213], v[148:151], v[56:59]
	v_mfma_f32_16x16x32_bf16 v[48:51], v[232:235], v[148:151], v[48:51]
	v_mfma_f32_16x16x32_bf16 v[40:43], v[210:213], v[166:169], v[40:43]
	v_mfma_f32_16x16x32_bf16 v[32:35], v[232:235], v[166:169], v[32:35]
	v_mfma_f32_16x16x32_bf16 v[24:27], v[210:213], v[188:191], v[24:27]
	v_mfma_f32_16x16x32_bf16 v[16:19], v[232:235], v[188:191], v[16:19]
	v_mfma_f32_16x16x32_bf16 v[8:11], v[210:213], v[202:205], v[8:11]
	v_mfma_f32_16x16x32_bf16 v[0:3], v[232:235], v[202:205], v[0:3]
	s_setprio 0
	s_add_i32 s70, s70, 2
	s_add_u32 s6, s6, 0x100
	s_addc_u32 s7, s7, 0
	s_add_u32 s68, s68, 0x100
	s_addc_u32 s69, s69, 0
	s_cmp_lt_u32 s70, 14
	s_barrier
	s_cbranch_scc1 .LBB0_1436
	v_mov_b32_e32 v134, v199
	v_mov_b32_e32 v128, v198
	s_lshl_b32 s4, s4, 8
	s_add_i32 s4, s4, s60
	v_add_u32_e32 v192, s4, v128
	v_lshlrev_b32_e32 v128, 2, v134
	v_ashrrev_i32_e32 v129, 31, v128
	v_ashrrev_i32_e32 v193, 31, v192
	v_add_u32_e32 v190, 16, v192
	v_lshl_add_u64 v[132:133], v[128:129], 2, s[8:9]
	v_lshlrev_b64 v[128:129], 6, v[192:193]
	v_ashrrev_i32_e32 v191, 31, v190
	v_add_u32_e32 v188, 32, v192
	v_lshl_add_u64 v[128:129], v[132:133], 0, v[128:129]
	v_lshlrev_b64 v[130:131], 6, v[190:191]
	v_ashrrev_i32_e32 v189, 31, v188
	v_lshl_add_u64 v[130:131], v[132:133], 0, v[130:131]
	global_load_dwordx4 v[202:205], v[128:129], off
	global_load_dwordx4 v[144:147], v[130:131], off
	v_lshlrev_b64 v[128:129], 6, v[188:189]
	v_add_u32_e32 v174, 48, v192
	v_lshl_add_u64 v[128:129], v[132:133], 0, v[128:129]
	v_ashrrev_i32_e32 v175, 31, v174
	global_load_dwordx4 v[148:151], v[128:129], off
	v_lshlrev_b64 v[128:129], 6, v[174:175]
	v_lshl_add_u64 v[128:129], v[132:133], 0, v[128:129]
	global_load_dwordx4 v[152:155], v[128:129], off
	v_add_u32_e32 v172, 0x80, v192
	v_ashrrev_i32_e32 v173, 31, v172
	v_lshlrev_b64 v[128:129], 6, v[172:173]
	v_lshl_add_u64 v[128:129], v[132:133], 0, v[128:129]
	global_load_dwordx4 v[140:143], v[128:129], off
	v_add_u32_e32 v170, 0x90, v192
	v_ashrrev_i32_e32 v171, 31, v170
	v_lshlrev_b64 v[128:129], 6, v[170:171]
	v_lshl_add_u64 v[128:129], v[132:133], 0, v[128:129]
	global_load_dwordx4 v[128:131], v[128:129], off
	s_lshl_b32 s5, s5, 7
	v_add_u32_e32 v168, 0xa0, v192
	v_add_u32_e32 v166, 0xb0, v192
	s_or_b32 s5, s5, s61
	v_ashrrev_i32_e32 v169, 31, v168
	v_ashrrev_i32_e32 v167, 31, v166
	v_lshl_add_u32 v194, v134, 3, s5
	v_lshlrev_b64 v[134:135], 6, v[168:169]
	v_lshlrev_b64 v[136:137], 6, v[166:167]
	v_lshl_add_u64 v[134:135], v[132:133], 0, v[134:135]
	v_lshl_add_u64 v[132:133], v[132:133], 0, v[136:137]
	global_load_dwordx4 v[136:139], v[134:135], off
	s_nop 0
	global_load_dwordx4 v[132:135], v[132:133], off
	s_mov_b32 s4, 0x358637bd
	v_mov_b64_e32 v[196:197], s[4:5]
	v_ashrrev_i32_e32 v195, 31, v194
	s_mov_b64 s[50:51], s[20:21]
	s_waitcnt vmcnt(0)
	v_mov_b32_e32 v206, v203
	v_mov_b32_e32 v207, v204
	v_mov_b32_e32 v203, v205
	v_mov_b32_e32 v204, v145
	v_mov_b32_e32 v205, v146
	v_mov_b32_e32 v145, v147
	v_pk_add_f32 v[202:203], v[206:207], v[202:203]
	v_mov_b32_e32 v146, v149
	v_mov_b32_e32 v147, v150
	v_mov_b32_e32 v149, v151
	v_mov_b32_e32 v150, v153
	v_mov_b32_e32 v151, v154
	v_mov_b32_e32 v153, v155
	v_pk_add_f32 v[144:145], v[204:205], v[144:145]
	v_mov_b32_e32 v155, v202
	v_pk_add_f32 v[146:147], v[146:147], v[148:149]
	v_pk_add_f32 v[148:149], v[150:151], v[152:153]
	v_mov_b32_e32 v154, v144
	v_mov_b32_e32 v202, v145
	v_mov_b32_e32 v144, v148
	v_mov_b32_e32 v145, v146
	v_mov_b32_e32 v146, v149
	v_pk_add_f32 v[148:149], v[154:155], v[202:203]
	v_pk_add_f32 v[144:145], v[144:145], v[146:147]
	ds_bpermute_b32 v147, v219, v149
	ds_bpermute_b32 v146, v219, v148
	ds_bpermute_b32 v151, v219, v145
	ds_bpermute_b32 v150, v219, v144
	v_mov_b32_e32 v152, v141
	v_mov_b32_e32 v153, v142
	v_mov_b32_e32 v141, v143
	s_waitcnt lgkmcnt(0)
	v_pk_add_f32 v[142:143], v[148:149], v[146:147]
	ds_bpermute_b32 v147, v218, v143
	ds_bpermute_b32 v146, v218, v142
	v_pk_add_f32 v[144:145], v[144:145], v[150:151]
	ds_bpermute_b32 v149, v218, v145
	ds_bpermute_b32 v148, v218, v144
	v_mov_b32_e32 v150, v129
	s_waitcnt lgkmcnt(2)
	v_pk_add_f32 v[142:143], v[142:143], v[146:147]
	v_mov_b32_e32 v151, v130
	v_pk_fma_f32 v[142:143], v[142:143], s[30:31], v[196:197] op_sel_hi:[1,0,0]
	s_waitcnt lgkmcnt(0)
	v_pk_add_f32 v[144:145], v[144:145], v[148:149]
	v_mul_f32_e32 v129, 0x4b800000, v143
	v_cmp_gt_f32_e32 vcc, s86, v143
	v_pk_fma_f32 v[146:147], v[144:145], s[30:31], v[196:197] op_sel_hi:[1,0,0]
	v_mul_f32_e32 v130, 0x4b800000, v142
	v_cndmask_b32_e32 v129, v143, v129, vcc
	v_rsq_f32_e32 v129, v129
	v_cmp_gt_f32_e64 s[4:5], s86, v142
	v_mul_f32_e32 v144, 0x4b800000, v147
	v_cmp_gt_f32_e64 s[6:7], s86, v147
	v_cndmask_b32_e64 v130, v142, v130, s[4:5]
	v_rsq_f32_e32 v142, v130
	v_cndmask_b32_e64 v130, v147, v144, s[6:7]
	v_rsq_f32_e32 v143, v130
	v_mul_f32_e32 v130, 0x45800000, v129
	v_cndmask_b32_e32 v144, v129, v130, vcc
	v_mov_b32_e32 v129, v131
	v_pk_add_f32 v[140:141], v[152:153], v[140:141]
	v_pk_add_f32 v[128:129], v[150:151], v[128:129]
	v_mov_b32_e32 v131, v140
	v_mov_b32_e32 v130, v128
	v_mov_b32_e32 v140, v129
	v_pk_add_f32 v[128:129], v[130:131], v[140:141]
	ds_bpermute_b32 v131, v219, v129
	ds_bpermute_b32 v130, v219, v128
	v_mul_f32_e32 v145, 0x45800000, v142
	v_cndmask_b32_e64 v142, v142, v145, s[4:5]
	v_mul_f32_e32 v140, 0x4b800000, v146
	v_cmp_gt_f32_e32 vcc, s86, v146
	s_waitcnt lgkmcnt(0)
	v_pk_add_f32 v[128:129], v[128:129], v[130:131]
	ds_bpermute_b32 v131, v218, v129
	ds_bpermute_b32 v130, v218, v128
	v_cndmask_b32_e32 v140, v146, v140, vcc
	v_rsq_f32_e32 v141, v140
	v_mul_f32_e32 v140, 0x45800000, v143
	v_cndmask_b32_e64 v140, v143, v140, s[6:7]
	s_waitcnt lgkmcnt(0)
	v_pk_add_f32 v[128:129], v[128:129], v[130:131]
	v_mov_b32_e32 v131, v138
	v_pk_fma_f32 v[128:129], v[128:129], s[30:31], v[196:197] op_sel_hi:[1,0,0]
	v_mul_f32_e32 v143, 0x45800000, v141
	v_mul_f32_e32 v130, 0x4b800000, v129
	v_cmp_gt_f32_e64 s[4:5], s86, v129
	v_cmp_gt_f32_e64 s[6:7], s86, v128
	v_pk_mul_f32 v[110:111], v[110:111], v[142:143] op_sel_hi:[1,0]
	v_cndmask_b32_e64 v129, v129, v130, s[4:5]
	v_mov_b32_e32 v130, v137
	v_mov_b32_e32 v137, v139
	v_pk_add_f32 v[130:131], v[130:131], v[136:137]
	v_mov_b32_e32 v136, v133
	v_mov_b32_e32 v137, v134
	v_mov_b32_e32 v133, v135
	v_pk_add_f32 v[132:133], v[136:137], v[132:133]
	v_mov_b32_e32 v135, v130
	v_mov_b32_e32 v134, v132
	v_mov_b32_e32 v130, v133
	v_pk_add_f32 v[130:131], v[134:135], v[130:131]
	ds_bpermute_b32 v133, v219, v131
	ds_bpermute_b32 v132, v219, v130
	v_rsq_f32_e32 v145, v129
	v_mul_f32_e32 v129, 0x4b800000, v128
	v_cndmask_b32_e64 v128, v128, v129, s[6:7]
	v_rsq_f32_e32 v135, v128
	s_waitcnt lgkmcnt(0)
	v_pk_add_f32 v[128:129], v[130:131], v[132:133]
	ds_bpermute_b32 v131, v218, v129
	ds_bpermute_b32 v130, v218, v128
	v_pk_mul_f32 v[126:127], v[126:127], v[144:145] op_sel_hi:[1,0]
	v_pk_mul_f32 v[122:123], v[122:123], v[144:145] op_sel_hi:[1,0]
	v_pk_mul_f32 v[116:117], v[116:117], v[144:145] op_sel_hi:[1,0]
	v_pk_mul_f32 v[124:125], v[124:125], v[144:145] op_sel_hi:[1,0]
	v_pk_mul_f32 v[138:139], v[126:127], s[44:45] op_sel_hi:[1,0]
	v_pk_mul_f32 v[120:121], v[120:121], v[144:145] op_sel_hi:[1,0]
	v_pk_mul_f32 v[122:123], v[126:127], v[122:123]
	v_pk_mul_f32 v[118:119], v[118:119], v[144:145] op_sel_hi:[1,0]
	v_pk_mul_f32 v[126:127], v[116:117], s[44:45] op_sel_hi:[1,0]
	v_pk_mul_f32 v[146:147], v[124:125], s[44:45] op_sel_hi:[1,0]
	v_pk_mul_f32 v[120:121], v[124:125], v[120:121]
	v_pk_mul_f32 v[124:125], v[118:119], s[44:45] op_sel_hi:[1,0]
	v_exp_f32_e32 v126, v126
	v_exp_f32_e32 v127, v127
	s_waitcnt lgkmcnt(0)
	v_pk_add_f32 v[128:129], v[128:129], v[130:131]
	v_exp_f32_e32 v146, v146
	v_exp_f32_e32 v138, v138
	v_exp_f32_e32 v139, v139
	v_exp_f32_e32 v147, v147
	v_exp_f32_e32 v124, v124
	v_exp_f32_e32 v125, v125
	v_pk_fma_f32 v[128:129], v[128:129], s[30:31], v[196:197] op_sel_hi:[1,0,0]
	v_cndmask_b32_e32 v136, v141, v143, vcc
	v_mul_f32_e32 v132, 0x45800000, v145
	v_mul_f32_e32 v130, 0x4b800000, v129
	v_cmp_gt_f32_e32 vcc, s86, v129
	v_cndmask_b32_e64 v134, v145, v132, s[4:5]
	v_cmp_gt_f32_e64 s[4:5], s86, v128
	v_cndmask_b32_e32 v129, v129, v130, vcc
	v_mul_f32_e32 v130, 0x4b800000, v128
	v_pk_add_f32 v[126:127], v[126:127], 1.0 op_sel_hi:[1,0]
	v_rsq_f32_e32 v129, v129
	v_cndmask_b32_e64 v128, v128, v130, s[4:5]
	v_pk_add_f32 v[138:139], v[138:139], 1.0 op_sel_hi:[1,0]
	v_pk_add_f32 v[146:147], v[146:147], 1.0 op_sel_hi:[1,0]
	v_pk_add_f32 v[124:125], v[124:125], 1.0 op_sel_hi:[1,0]
	v_rcp_f32_e32 v126, v126
	v_rcp_f32_e32 v127, v127
	v_rsq_f32_e32 v128, v128
	v_rcp_f32_e32 v146, v146
	v_rcp_f32_e32 v138, v138
	v_rcp_f32_e32 v139, v139
	v_rcp_f32_e32 v147, v147
	v_rcp_f32_e32 v124, v124
	v_rcp_f32_e32 v125, v125
	v_pk_mul_f32 v[112:113], v[112:113], v[144:145] op_sel_hi:[1,0]
	v_pk_mul_f32 v[114:115], v[114:115], v[144:145] op_sel_hi:[1,0]
	v_pk_mul_f32 v[112:113], v[116:117], v[112:113]
	v_mul_f32_e32 v130, 0x45800000, v129
	v_pk_mul_f32 v[114:115], v[118:119], v[114:115]
	v_pk_mul_f32 v[112:113], v[112:113], v[126:127]
	v_cndmask_b32_e32 v130, v129, v130, vcc
	v_mul_f32_e32 v129, 0x45800000, v128
	v_pk_mul_f32 v[122:123], v[122:123], v[138:139]
	v_pk_mul_f32 v[120:121], v[120:121], v[146:147]
	v_pk_mul_f32 v[114:115], v[114:115], v[124:125]
	v_cvt_pk_bf16_f32 v116, v120, v121
	v_cvt_pk_bf16_f32 v117, v122, v123
	v_cvt_pk_bf16_f32 v118, v112, v113
	v_mov_b64_e32 v[112:113], s[10:11]
	v_cndmask_b32_e64 v128, v128, v129, s[4:5]
	v_cvt_pk_bf16_f32 v119, v114, v115
	v_mad_i64_i32 v[120:121], s[4:5], v192, s35, v[112:113]
	v_lshlrev_b64 v[114:115], 1, v[194:195]
	v_lshl_add_u64 v[120:121], v[120:121], 0, v[114:115]
	v_pk_mul_f32 v[108:109], v[108:109], v[142:143] op_sel_hi:[1,0]
	v_pk_mul_f32 v[106:107], v[106:107], v[142:143] op_sel_hi:[1,0]
	v_pk_mul_f32 v[104:105], v[104:105], v[142:143] op_sel_hi:[1,0]
	v_pk_mul_f32 v[102:103], v[102:103], v[142:143] op_sel_hi:[1,0]
	v_pk_mul_f32 v[100:101], v[100:101], v[142:143] op_sel_hi:[1,0]
	global_store_dwordx4 v[120:121], v[116:119], off
	v_pk_mul_f32 v[104:105], v[108:109], v[104:105]
	v_pk_mul_f32 v[106:107], v[110:111], v[106:107]
	v_pk_mul_f32 v[116:117], v[110:111], s[44:45] op_sel_hi:[1,0]
	v_pk_mul_f32 v[118:119], v[108:109], s[44:45] op_sel_hi:[1,0]
	v_pk_mul_f32 v[108:109], v[102:103], s[44:45] op_sel_hi:[1,0]
	v_pk_mul_f32 v[110:111], v[100:101], s[44:45] op_sel_hi:[1,0]
	v_exp_f32_e32 v108, v108
	v_exp_f32_e32 v110, v110
	v_exp_f32_e32 v109, v109
	v_exp_f32_e32 v111, v111
	v_exp_f32_e32 v118, v118
	v_exp_f32_e32 v116, v116
	v_exp_f32_e32 v117, v117
	v_exp_f32_e32 v119, v119
	v_pk_add_f32 v[108:109], v[108:109], 1.0 op_sel_hi:[1,0]
	v_pk_add_f32 v[110:111], v[110:111], 1.0 op_sel_hi:[1,0]
	v_pk_add_f32 v[116:117], v[116:117], 1.0 op_sel_hi:[1,0]
	v_pk_add_f32 v[118:119], v[118:119], 1.0 op_sel_hi:[1,0]
	v_rcp_f32_e32 v110, v110
	v_rcp_f32_e32 v108, v108
	v_rcp_f32_e32 v109, v109
	v_rcp_f32_e32 v111, v111
	v_rcp_f32_e32 v118, v118
	v_rcp_f32_e32 v116, v116
	v_rcp_f32_e32 v117, v117
	v_rcp_f32_e32 v119, v119
	v_pk_mul_f32 v[98:99], v[98:99], v[142:143] op_sel_hi:[1,0]
	v_pk_mul_f32 v[96:97], v[96:97], v[142:143] op_sel_hi:[1,0]
	v_pk_mul_f32 v[98:99], v[102:103], v[98:99]
	v_pk_mul_f32 v[96:97], v[100:101], v[96:97]
	v_pk_mul_f32 v[100:101], v[98:99], v[108:109]
	v_pk_mul_f32 v[98:99], v[96:97], v[110:111]
	v_pk_mul_f32 v[106:107], v[106:107], v[116:117]
	v_pk_mul_f32 v[104:105], v[104:105], v[118:119]
	v_pk_mul_f32 v[94:95], v[94:95], v[140:141] op_sel_hi:[1,0]
	v_cvt_pk_bf16_f32 v96, v104, v105
	v_cvt_pk_bf16_f32 v97, v106, v107
	v_cvt_pk_bf16_f32 v98, v98, v99
	v_cvt_pk_bf16_f32 v99, v100, v101
	v_mad_i64_i32 v[100:101], s[4:5], v190, s35, v[112:113]
	v_lshl_add_u64 v[100:101], v[100:101], 0, v[114:115]
	v_pk_mul_f32 v[92:93], v[92:93], v[140:141] op_sel_hi:[1,0]
	v_pk_mul_f32 v[90:91], v[90:91], v[140:141] op_sel_hi:[1,0]
	v_pk_mul_f32 v[88:89], v[88:89], v[140:141] op_sel_hi:[1,0]
	v_pk_mul_f32 v[86:87], v[86:87], v[140:141] op_sel_hi:[1,0]
	v_pk_mul_f32 v[84:85], v[84:85], v[140:141] op_sel_hi:[1,0]
	global_store_dwordx4 v[100:101], v[96:99], off
	v_pk_mul_f32 v[88:89], v[92:93], v[88:89]
	v_pk_mul_f32 v[90:91], v[94:95], v[90:91]
	v_pk_mul_f32 v[96:97], v[94:95], s[44:45] op_sel_hi:[1,0]
	v_pk_mul_f32 v[98:99], v[92:93], s[44:45] op_sel_hi:[1,0]
	v_pk_mul_f32 v[92:93], v[86:87], s[44:45] op_sel_hi:[1,0]
	v_pk_mul_f32 v[94:95], v[84:85], s[44:45] op_sel_hi:[1,0]
	v_exp_f32_e32 v92, v92
	v_exp_f32_e32 v94, v94
	v_exp_f32_e32 v93, v93
	v_exp_f32_e32 v95, v95
	v_exp_f32_e32 v98, v98
	v_exp_f32_e32 v96, v96
	v_exp_f32_e32 v97, v97
	v_exp_f32_e32 v99, v99
	v_pk_add_f32 v[92:93], v[92:93], 1.0 op_sel_hi:[1,0]
	v_pk_add_f32 v[94:95], v[94:95], 1.0 op_sel_hi:[1,0]
	v_pk_add_f32 v[96:97], v[96:97], 1.0 op_sel_hi:[1,0]
	v_pk_add_f32 v[98:99], v[98:99], 1.0 op_sel_hi:[1,0]
	v_rcp_f32_e32 v94, v94
	v_rcp_f32_e32 v92, v92
	v_rcp_f32_e32 v93, v93
	v_rcp_f32_e32 v95, v95
	v_rcp_f32_e32 v98, v98
	v_rcp_f32_e32 v96, v96
	v_rcp_f32_e32 v97, v97
	v_rcp_f32_e32 v99, v99
	v_pk_mul_f32 v[82:83], v[82:83], v[140:141] op_sel_hi:[1,0]
	v_pk_mul_f32 v[80:81], v[80:81], v[140:141] op_sel_hi:[1,0]
	v_pk_mul_f32 v[82:83], v[86:87], v[82:83]
	v_pk_mul_f32 v[80:81], v[84:85], v[80:81]
	v_pk_mul_f32 v[84:85], v[82:83], v[92:93]
	v_pk_mul_f32 v[82:83], v[80:81], v[94:95]
	v_pk_mul_f32 v[90:91], v[90:91], v[96:97]
	v_pk_mul_f32 v[88:89], v[88:89], v[98:99]
	v_pk_mul_f32 v[78:79], v[78:79], v[136:137] op_sel_hi:[1,0]
	v_cvt_pk_bf16_f32 v80, v88, v89
	v_cvt_pk_bf16_f32 v81, v90, v91
	v_cvt_pk_bf16_f32 v82, v82, v83
	v_cvt_pk_bf16_f32 v83, v84, v85
	v_mad_i64_i32 v[84:85], s[4:5], v188, s35, v[112:113]
	v_lshl_add_u64 v[84:85], v[84:85], 0, v[114:115]
	v_pk_mul_f32 v[76:77], v[76:77], v[136:137] op_sel_hi:[1,0]
	v_pk_mul_f32 v[74:75], v[74:75], v[136:137] op_sel_hi:[1,0]
	v_pk_mul_f32 v[72:73], v[72:73], v[136:137] op_sel_hi:[1,0]
	v_pk_mul_f32 v[70:71], v[70:71], v[136:137] op_sel_hi:[1,0]
	v_pk_mul_f32 v[68:69], v[68:69], v[136:137] op_sel_hi:[1,0]
	global_store_dwordx4 v[84:85], v[80:83], off
	v_pk_mul_f32 v[72:73], v[76:77], v[72:73]
	v_pk_mul_f32 v[74:75], v[78:79], v[74:75]
	v_pk_mul_f32 v[80:81], v[78:79], s[44:45] op_sel_hi:[1,0]
	v_pk_mul_f32 v[82:83], v[76:77], s[44:45] op_sel_hi:[1,0]
	v_pk_mul_f32 v[76:77], v[70:71], s[44:45] op_sel_hi:[1,0]
	v_pk_mul_f32 v[78:79], v[68:69], s[44:45] op_sel_hi:[1,0]
	v_exp_f32_e32 v76, v76
	v_exp_f32_e32 v78, v78
	v_exp_f32_e32 v77, v77
	v_exp_f32_e32 v79, v79
	v_exp_f32_e32 v82, v82
	v_exp_f32_e32 v80, v80
	v_exp_f32_e32 v81, v81
	v_exp_f32_e32 v83, v83
	v_pk_add_f32 v[76:77], v[76:77], 1.0 op_sel_hi:[1,0]
	v_pk_add_f32 v[78:79], v[78:79], 1.0 op_sel_hi:[1,0]
	v_pk_add_f32 v[80:81], v[80:81], 1.0 op_sel_hi:[1,0]
	v_pk_add_f32 v[82:83], v[82:83], 1.0 op_sel_hi:[1,0]
	v_rcp_f32_e32 v78, v78
	v_rcp_f32_e32 v76, v76
	v_rcp_f32_e32 v77, v77
	v_rcp_f32_e32 v79, v79
	v_rcp_f32_e32 v82, v82
	v_rcp_f32_e32 v80, v80
	v_rcp_f32_e32 v81, v81
	v_rcp_f32_e32 v83, v83
	v_pk_mul_f32 v[66:67], v[66:67], v[136:137] op_sel_hi:[1,0]
	v_pk_mul_f32 v[64:65], v[64:65], v[136:137] op_sel_hi:[1,0]
	v_pk_mul_f32 v[66:67], v[70:71], v[66:67]
	v_pk_mul_f32 v[64:65], v[68:69], v[64:65]
	v_pk_mul_f32 v[68:69], v[66:67], v[76:77]
	v_pk_mul_f32 v[66:67], v[64:65], v[78:79]
	v_pk_mul_f32 v[74:75], v[74:75], v[80:81]
	v_pk_mul_f32 v[72:73], v[72:73], v[82:83]
	v_pk_mul_f32 v[62:63], v[62:63], v[134:135] op_sel_hi:[1,0]
	v_cvt_pk_bf16_f32 v64, v72, v73
	v_cvt_pk_bf16_f32 v65, v74, v75
	v_cvt_pk_bf16_f32 v66, v66, v67
	v_cvt_pk_bf16_f32 v67, v68, v69
	v_mad_i64_i32 v[68:69], s[4:5], v174, s35, v[112:113]
	v_lshl_add_u64 v[68:69], v[68:69], 0, v[114:115]
	v_pk_mul_f32 v[60:61], v[60:61], v[134:135] op_sel_hi:[1,0]
	v_pk_mul_f32 v[58:59], v[58:59], v[134:135] op_sel_hi:[1,0]
	v_pk_mul_f32 v[56:57], v[56:57], v[134:135] op_sel_hi:[1,0]
	v_pk_mul_f32 v[54:55], v[54:55], v[134:135] op_sel_hi:[1,0]
	v_pk_mul_f32 v[52:53], v[52:53], v[134:135] op_sel_hi:[1,0]
	global_store_dwordx4 v[68:69], v[64:67], off
	v_pk_mul_f32 v[56:57], v[60:61], v[56:57]
	v_pk_mul_f32 v[58:59], v[62:63], v[58:59]
	v_pk_mul_f32 v[64:65], v[62:63], s[44:45] op_sel_hi:[1,0]
	v_pk_mul_f32 v[66:67], v[60:61], s[44:45] op_sel_hi:[1,0]
	v_pk_mul_f32 v[60:61], v[54:55], s[44:45] op_sel_hi:[1,0]
	v_pk_mul_f32 v[62:63], v[52:53], s[44:45] op_sel_hi:[1,0]
	v_exp_f32_e32 v60, v60
	v_exp_f32_e32 v62, v62
	v_exp_f32_e32 v61, v61
	v_exp_f32_e32 v63, v63
	v_exp_f32_e32 v66, v66
	v_exp_f32_e32 v64, v64
	v_exp_f32_e32 v65, v65
	v_exp_f32_e32 v67, v67
	v_pk_add_f32 v[60:61], v[60:61], 1.0 op_sel_hi:[1,0]
	v_pk_add_f32 v[62:63], v[62:63], 1.0 op_sel_hi:[1,0]
	v_pk_add_f32 v[64:65], v[64:65], 1.0 op_sel_hi:[1,0]
	v_pk_add_f32 v[66:67], v[66:67], 1.0 op_sel_hi:[1,0]
	v_rcp_f32_e32 v62, v62
	v_rcp_f32_e32 v60, v60
	v_rcp_f32_e32 v61, v61
	v_rcp_f32_e32 v63, v63
	v_rcp_f32_e32 v66, v66
	v_rcp_f32_e32 v64, v64
	v_rcp_f32_e32 v65, v65
	v_rcp_f32_e32 v67, v67
	v_pk_mul_f32 v[50:51], v[50:51], v[134:135] op_sel_hi:[1,0]
	v_pk_mul_f32 v[48:49], v[48:49], v[134:135] op_sel_hi:[1,0]
	v_pk_mul_f32 v[50:51], v[54:55], v[50:51]
	v_pk_mul_f32 v[48:49], v[52:53], v[48:49]
	v_mul_f32_e32 v132, 0x45800000, v135
	v_pk_mul_f32 v[52:53], v[50:51], v[60:61]
	v_pk_mul_f32 v[50:51], v[48:49], v[62:63]
	v_cndmask_b32_e64 v132, v135, v132, s[6:7]
	v_pk_mul_f32 v[58:59], v[58:59], v[64:65]
	v_pk_mul_f32 v[56:57], v[56:57], v[66:67]
	v_pk_mul_f32 v[46:47], v[46:47], v[132:133] op_sel_hi:[1,0]
	v_cvt_pk_bf16_f32 v48, v56, v57
	v_cvt_pk_bf16_f32 v49, v58, v59
	v_cvt_pk_bf16_f32 v50, v50, v51
	v_cvt_pk_bf16_f32 v51, v52, v53
	v_mad_i64_i32 v[52:53], s[4:5], v172, s35, v[112:113]
	v_lshl_add_u64 v[52:53], v[52:53], 0, v[114:115]
	v_pk_mul_f32 v[44:45], v[44:45], v[132:133] op_sel_hi:[1,0]
	v_pk_mul_f32 v[42:43], v[42:43], v[132:133] op_sel_hi:[1,0]
	v_pk_mul_f32 v[40:41], v[40:41], v[132:133] op_sel_hi:[1,0]
	v_pk_mul_f32 v[38:39], v[38:39], v[132:133] op_sel_hi:[1,0]
	v_pk_mul_f32 v[36:37], v[36:37], v[132:133] op_sel_hi:[1,0]
	global_store_dwordx4 v[52:53], v[48:51], off
	v_pk_mul_f32 v[40:41], v[44:45], v[40:41]
	v_pk_mul_f32 v[42:43], v[46:47], v[42:43]
	v_pk_mul_f32 v[48:49], v[46:47], s[44:45] op_sel_hi:[1,0]
	v_pk_mul_f32 v[50:51], v[44:45], s[44:45] op_sel_hi:[1,0]
	v_pk_mul_f32 v[44:45], v[38:39], s[44:45] op_sel_hi:[1,0]
	v_pk_mul_f32 v[46:47], v[36:37], s[44:45] op_sel_hi:[1,0]
	v_exp_f32_e32 v44, v44
	v_exp_f32_e32 v46, v46
	v_exp_f32_e32 v45, v45
	v_exp_f32_e32 v47, v47
	v_exp_f32_e32 v50, v50
	v_exp_f32_e32 v48, v48
	v_exp_f32_e32 v49, v49
	v_exp_f32_e32 v51, v51
	v_pk_add_f32 v[44:45], v[44:45], 1.0 op_sel_hi:[1,0]
	v_pk_add_f32 v[46:47], v[46:47], 1.0 op_sel_hi:[1,0]
	v_pk_add_f32 v[48:49], v[48:49], 1.0 op_sel_hi:[1,0]
	v_pk_add_f32 v[50:51], v[50:51], 1.0 op_sel_hi:[1,0]
	v_rcp_f32_e32 v46, v46
	v_rcp_f32_e32 v44, v44
	v_rcp_f32_e32 v45, v45
	v_rcp_f32_e32 v47, v47
	v_rcp_f32_e32 v50, v50
	v_rcp_f32_e32 v48, v48
	v_rcp_f32_e32 v49, v49
	v_rcp_f32_e32 v51, v51
	v_pk_mul_f32 v[34:35], v[34:35], v[132:133] op_sel_hi:[1,0]
	v_pk_mul_f32 v[32:33], v[32:33], v[132:133] op_sel_hi:[1,0]
	v_pk_mul_f32 v[34:35], v[38:39], v[34:35]
	v_pk_mul_f32 v[32:33], v[36:37], v[32:33]
	v_pk_mul_f32 v[36:37], v[34:35], v[44:45]
	v_pk_mul_f32 v[34:35], v[32:33], v[46:47]
	v_pk_mul_f32 v[42:43], v[42:43], v[48:49]
	v_pk_mul_f32 v[40:41], v[40:41], v[50:51]
	v_pk_mul_f32 v[30:31], v[30:31], v[130:131] op_sel_hi:[1,0]
	v_cvt_pk_bf16_f32 v32, v40, v41
	v_cvt_pk_bf16_f32 v33, v42, v43
	v_cvt_pk_bf16_f32 v34, v34, v35
	v_cvt_pk_bf16_f32 v35, v36, v37
	v_mad_i64_i32 v[36:37], s[4:5], v170, s35, v[112:113]
	v_lshl_add_u64 v[36:37], v[36:37], 0, v[114:115]
	v_pk_mul_f32 v[28:29], v[28:29], v[130:131] op_sel_hi:[1,0]
	v_pk_mul_f32 v[26:27], v[26:27], v[130:131] op_sel_hi:[1,0]
	v_pk_mul_f32 v[24:25], v[24:25], v[130:131] op_sel_hi:[1,0]
	v_pk_mul_f32 v[22:23], v[22:23], v[130:131] op_sel_hi:[1,0]
	v_pk_mul_f32 v[20:21], v[20:21], v[130:131] op_sel_hi:[1,0]
	global_store_dwordx4 v[36:37], v[32:35], off
	v_pk_mul_f32 v[24:25], v[28:29], v[24:25]
	v_pk_mul_f32 v[26:27], v[30:31], v[26:27]
	v_pk_mul_f32 v[32:33], v[30:31], s[44:45] op_sel_hi:[1,0]
	v_pk_mul_f32 v[34:35], v[28:29], s[44:45] op_sel_hi:[1,0]
	v_pk_mul_f32 v[28:29], v[22:23], s[44:45] op_sel_hi:[1,0]
	v_pk_mul_f32 v[30:31], v[20:21], s[44:45] op_sel_hi:[1,0]
	v_exp_f32_e32 v28, v28
	v_exp_f32_e32 v30, v30
	v_exp_f32_e32 v29, v29
	v_exp_f32_e32 v31, v31
	v_exp_f32_e32 v34, v34
	v_exp_f32_e32 v32, v32
	v_exp_f32_e32 v33, v33
	v_exp_f32_e32 v35, v35
	v_pk_add_f32 v[28:29], v[28:29], 1.0 op_sel_hi:[1,0]
	v_pk_add_f32 v[30:31], v[30:31], 1.0 op_sel_hi:[1,0]
	v_pk_add_f32 v[32:33], v[32:33], 1.0 op_sel_hi:[1,0]
	v_pk_add_f32 v[34:35], v[34:35], 1.0 op_sel_hi:[1,0]
	v_rcp_f32_e32 v30, v30
	v_rcp_f32_e32 v28, v28
	v_rcp_f32_e32 v29, v29
	v_rcp_f32_e32 v31, v31
	v_rcp_f32_e32 v34, v34
	v_rcp_f32_e32 v32, v32
	v_rcp_f32_e32 v33, v33
	v_rcp_f32_e32 v35, v35
	v_pk_mul_f32 v[18:19], v[18:19], v[130:131] op_sel_hi:[1,0]
	v_pk_mul_f32 v[16:17], v[16:17], v[130:131] op_sel_hi:[1,0]
	v_pk_mul_f32 v[18:19], v[22:23], v[18:19]
	v_pk_mul_f32 v[16:17], v[20:21], v[16:17]
	v_pk_mul_f32 v[20:21], v[18:19], v[28:29]
	v_pk_mul_f32 v[18:19], v[16:17], v[30:31]
	v_pk_mul_f32 v[26:27], v[26:27], v[32:33]
	v_pk_mul_f32 v[24:25], v[24:25], v[34:35]
	v_pk_mul_f32 v[14:15], v[14:15], v[128:129] op_sel_hi:[1,0]
	v_cvt_pk_bf16_f32 v16, v24, v25
	v_cvt_pk_bf16_f32 v17, v26, v27
	v_cvt_pk_bf16_f32 v18, v18, v19
	v_cvt_pk_bf16_f32 v19, v20, v21
	v_mad_i64_i32 v[20:21], s[4:5], v168, s35, v[112:113]
	v_lshl_add_u64 v[20:21], v[20:21], 0, v[114:115]
	v_pk_mul_f32 v[12:13], v[12:13], v[128:129] op_sel_hi:[1,0]
	v_pk_mul_f32 v[10:11], v[10:11], v[128:129] op_sel_hi:[1,0]
	v_pk_mul_f32 v[8:9], v[8:9], v[128:129] op_sel_hi:[1,0]
	v_pk_mul_f32 v[6:7], v[6:7], v[128:129] op_sel_hi:[1,0]
	v_pk_mul_f32 v[4:5], v[4:5], v[128:129] op_sel_hi:[1,0]
	global_store_dwordx4 v[20:21], v[16:19], off
	v_pk_mul_f32 v[8:9], v[12:13], v[8:9]
	v_pk_mul_f32 v[10:11], v[14:15], v[10:11]
	v_pk_mul_f32 v[16:17], v[14:15], s[44:45] op_sel_hi:[1,0]
	v_pk_mul_f32 v[18:19], v[12:13], s[44:45] op_sel_hi:[1,0]
	v_pk_mul_f32 v[12:13], v[6:7], s[44:45] op_sel_hi:[1,0]
	v_pk_mul_f32 v[14:15], v[4:5], s[44:45] op_sel_hi:[1,0]
	v_exp_f32_e32 v12, v12
	v_exp_f32_e32 v14, v14
	v_exp_f32_e32 v13, v13
	v_exp_f32_e32 v15, v15
	v_exp_f32_e32 v18, v18
	v_exp_f32_e32 v16, v16
	v_exp_f32_e32 v17, v17
	v_exp_f32_e32 v19, v19
	v_pk_add_f32 v[12:13], v[12:13], 1.0 op_sel_hi:[1,0]
	v_pk_add_f32 v[14:15], v[14:15], 1.0 op_sel_hi:[1,0]
	v_pk_add_f32 v[16:17], v[16:17], 1.0 op_sel_hi:[1,0]
	v_pk_add_f32 v[18:19], v[18:19], 1.0 op_sel_hi:[1,0]
	v_rcp_f32_e32 v14, v14
	v_rcp_f32_e32 v12, v12
	v_rcp_f32_e32 v13, v13
	v_rcp_f32_e32 v15, v15
	v_rcp_f32_e32 v18, v18
	v_rcp_f32_e32 v16, v16
	v_rcp_f32_e32 v17, v17
	v_rcp_f32_e32 v19, v19
	v_pk_mul_f32 v[2:3], v[2:3], v[128:129] op_sel_hi:[1,0]
	v_pk_mul_f32 v[0:1], v[0:1], v[128:129] op_sel_hi:[1,0]
	v_pk_mul_f32 v[2:3], v[6:7], v[2:3]
	v_pk_mul_f32 v[0:1], v[4:5], v[0:1]
	v_pk_mul_f32 v[4:5], v[2:3], v[12:13]
	v_pk_mul_f32 v[2:3], v[0:1], v[14:15]
	v_pk_mul_f32 v[10:11], v[10:11], v[16:17]
	v_pk_mul_f32 v[8:9], v[8:9], v[18:19]
	s_andn2_b64 vcc, exec, s[2:3]
	v_cvt_pk_bf16_f32 v0, v8, v9
	v_cvt_pk_bf16_f32 v1, v10, v11
	v_cvt_pk_bf16_f32 v2, v2, v3
	v_cvt_pk_bf16_f32 v3, v4, v5
	v_mad_i64_i32 v[4:5], s[4:5], v166, s35, v[112:113]
	v_lshl_add_u64 v[4:5], v[4:5], 0, v[114:115]
	s_mov_b32 s4, s16
	s_mov_b32 s5, s12
	s_mov_b64 s[6:7], s[18:19]
	global_store_dwordx4 v[4:5], v[0:3], off
	s_cbranch_vccnz .LBB0_1429
	s_waitcnt vmcnt(0)
	s_cmpk_gt_u32 s24, 0xff
	s_cbranch_scc1 .LBB0_1440
	s_barrier
